# v40 + every K-loop DMA address in SGPR-base form (no VALU address adds left in the loader segments)
# speedup vs baseline: 1.0161x; 1.0161x over previous
.LBB0_261:
	s_ashr_i32 s35, s34, 31
	s_lshl_b64 vcc, s[34:35], 21
	s_add_u32 s13, s30, vcc_lo
	s_addc_u32 s15, s31, vcc_hi
	s_add_u32 s54, s13, s54
	s_addc_u32 s55, s15, s55
	s_and_b64 s[86:87], s[86:87], exec
	s_cselect_b32 s13, s55, s11
	s_cselect_b32 s15, s54, s10
	s_add_i32 s35, s19, -2
	s_add_u32 s40, s10, 0x100
	s_addc_u32 s49, s11, 0
	s_add_u32 s10, s38, 0x100080
	s_addc_u32 s11, s39, 0
	s_mov_b32 s38, 0
	s_add_i32 vcc_lo, s38, 2
	s_add_u32 s39, s10, 0xfff00080
	s_addc_u32 s66, s11, -1
	s_add_i32 s67, 0, 0x10000
	s_cmp_eq_u32 s35, s38
	s_cselect_b32 s87, s53, s66
	s_cselect_b32 s86, s52, s39
	s_cselect_b32 s39, s13, s49
	s_cselect_b32 s38, s15, s40
	s_add_i32 vcc_hi, 0, 0x14000
	v_add_u32_e32 v142, s67, v1
	v_add_u32_e32 v180, vcc_hi, v1
	ds_read_b128 v[130:133], v142
	ds_read_b128 v[134:137], v142 offset:1024
	ds_read_b128 v[138:141], v142 offset:2048
	ds_read_b128 v[142:145], v142 offset:3072
	ds_read_b128 v[168:171], v180
	ds_read_b128 v[172:175], v180 offset:1024
	ds_read_b128 v[176:179], v180 offset:2048
	ds_read_b128 v[180:183], v180 offset:3072
	s_add_i32 m0, s85, 0xc000
	ds_read_b128 v[198:201], v197
	ds_read_b128 v[202:205], v197 offset:1024
	ds_read_b128 v[206:209], v197 offset:2048
	ds_read_b128 v[210:213], v197 offset:3072
	ds_read_b128 v[214:217], v197 offset:4096
	ds_read_b128 v[218:221], v197 offset:5120
	ds_read_b128 v[222:225], v197 offset:6144
	ds_read_b128 v[226:229], v197 offset:7168
	global_load_lds_dwordx4 v164, s[10:11]
	s_add_i32 m0, s85, 0xe000
	s_nop 0
	global_load_lds_dwordx4 v166, s[10:11]
	s_waitcnt vmcnt(8)
	s_waitcnt lgkmcnt(0)
	s_setprio 1
	s_barrier
	v_mfma_f32_16x16x32_bf16 v[114:117], v[130:133], v[198:201], 0
	v_mfma_f32_16x16x32_bf16 v[118:121], v[138:141], v[198:201], 0
	v_mfma_f32_16x16x32_bf16 v[102:105], v[130:133], v[206:209], 0
	v_mfma_f32_16x16x32_bf16 v[98:101], v[138:141], v[206:209], 0
	v_mfma_f32_16x16x32_bf16 v[86:89], v[130:133], v[214:217], 0
	v_mfma_f32_16x16x32_bf16 v[82:85], v[138:141], v[214:217], 0
	v_mfma_f32_16x16x32_bf16 v[54:57], v[130:133], v[222:225], 0
	v_mfma_f32_16x16x32_bf16 v[50:53], v[138:141], v[222:225], 0
	v_mfma_f32_16x16x32_bf16 v[114:117], v[134:137], v[202:205], v[114:117]
	v_mfma_f32_16x16x32_bf16 v[118:121], v[142:145], v[202:205], v[118:121]
	v_mfma_f32_16x16x32_bf16 v[102:105], v[134:137], v[210:213], v[102:105]
	v_mfma_f32_16x16x32_bf16 v[98:101], v[142:145], v[210:213], v[98:101]
	v_mfma_f32_16x16x32_bf16 v[86:89], v[134:137], v[218:221], v[86:89]
	v_mfma_f32_16x16x32_bf16 v[82:85], v[142:145], v[218:221], v[82:85]
	v_mfma_f32_16x16x32_bf16 v[54:57], v[134:137], v[226:229], v[54:57]
	v_mfma_f32_16x16x32_bf16 v[50:53], v[142:145], v[226:229], v[50:53]
	s_setprio 0
	s_setprio 1
	v_mfma_f32_16x16x32_bf16 v[126:129], v[168:171], v[198:201], 0
	v_mfma_f32_16x16x32_bf16 v[122:125], v[176:179], v[198:201], 0
	v_mfma_f32_16x16x32_bf16 v[110:113], v[168:171], v[206:209], 0
	v_mfma_f32_16x16x32_bf16 v[106:109], v[176:179], v[206:209], 0
	v_mfma_f32_16x16x32_bf16 v[94:97], v[168:171], v[214:217], 0
	v_mfma_f32_16x16x32_bf16 v[90:93], v[176:179], v[214:217], 0
	v_mfma_f32_16x16x32_bf16 v[70:73], v[168:171], v[222:225], 0
	v_mfma_f32_16x16x32_bf16 v[66:69], v[176:179], v[222:225], 0
	v_mfma_f32_16x16x32_bf16 v[126:129], v[172:175], v[202:205], v[126:129]
	v_mfma_f32_16x16x32_bf16 v[122:125], v[180:183], v[202:205], v[122:125]
	v_mfma_f32_16x16x32_bf16 v[110:113], v[172:175], v[210:213], v[110:113]
	v_mfma_f32_16x16x32_bf16 v[106:109], v[180:183], v[210:213], v[106:109]
	v_mfma_f32_16x16x32_bf16 v[94:97], v[172:175], v[218:221], v[94:97]
	v_mfma_f32_16x16x32_bf16 v[90:93], v[180:183], v[218:221], v[90:93]
	v_mfma_f32_16x16x32_bf16 v[70:73], v[172:175], v[226:229], v[70:73]
	v_mfma_f32_16x16x32_bf16 v[66:69], v[180:183], v[226:229], v[66:69]
	s_barrier
	s_setprio 0
	s_add_i32 s66, s67, s97
	s_add_u32 s98, s38, 0x80
	s_addc_u32 s99, s39, 0
	s_mov_b32 m0, s66
	ds_read_b128 v[198:201], v197 offset:16384
	ds_read_b128 v[202:205], v197 offset:17408
	ds_read_b128 v[206:209], v197 offset:18432
	ds_read_b128 v[210:213], v197 offset:19456
	ds_read_b128 v[214:217], v197 offset:20480
	ds_read_b128 v[218:221], v197 offset:21504
	ds_read_b128 v[222:225], v197 offset:22528
	ds_read_b128 v[226:229], v197 offset:23552
	global_load_lds_dwordx4 v156, s[38:39]
	s_add_i32 m0, s66, 0x2000
	s_add_u32 s66, s38, 0x100000
	s_addc_u32 s67, s39, 0
	s_add_i32 vcc_hi, vcc_hi, s97
	global_load_lds_dwordx4 v160, s[38:39]
	s_mov_b32 m0, vcc_hi
	s_add_u32 s100, s86, 0x80
	s_addc_u32 s101, s87, 0
	global_load_lds_dwordx4 v156, s[66:67]
	s_add_i32 m0, vcc_hi, 0x2000
	s_nop 0
	global_load_lds_dwordx4 v160, s[66:67]
	s_mov_b32 m0, s85
	s_nop 0
	global_load_lds_dwordx4 v154, s[86:87]
	s_mov_b32 m0, s92
	s_nop 0
	global_load_lds_dwordx4 v158, s[86:87]
	s_waitcnt vmcnt(8)
	s_waitcnt lgkmcnt(0)
	s_setprio 1
	s_barrier
	v_mfma_f32_16x16x32_bf16 v[62:65], v[130:133], v[198:201], 0
	v_mfma_f32_16x16x32_bf16 v[58:61], v[138:141], v[198:201], 0
	v_mfma_f32_16x16x32_bf16 v[38:41], v[130:133], v[206:209], 0
	v_mfma_f32_16x16x32_bf16 v[34:37], v[138:141], v[206:209], 0
	v_mfma_f32_16x16x32_bf16 v[22:25], v[130:133], v[214:217], 0
	v_mfma_f32_16x16x32_bf16 v[18:21], v[138:141], v[214:217], 0
	v_mfma_f32_16x16x32_bf16 v[6:9], v[130:133], v[222:225], 0
	v_mfma_f32_16x16x32_bf16 v[2:5], v[138:141], v[222:225], 0
	v_mfma_f32_16x16x32_bf16 v[62:65], v[134:137], v[202:205], v[62:65]
	v_mfma_f32_16x16x32_bf16 v[58:61], v[142:145], v[202:205], v[58:61]
	v_mfma_f32_16x16x32_bf16 v[38:41], v[134:137], v[210:213], v[38:41]
	v_mfma_f32_16x16x32_bf16 v[34:37], v[142:145], v[210:213], v[34:37]
	v_mfma_f32_16x16x32_bf16 v[22:25], v[134:137], v[218:221], v[22:25]
	v_mfma_f32_16x16x32_bf16 v[18:21], v[142:145], v[218:221], v[18:21]
	v_mfma_f32_16x16x32_bf16 v[6:9], v[134:137], v[226:229], v[6:9]
	v_mfma_f32_16x16x32_bf16 v[2:5], v[142:145], v[226:229], v[2:5]
	s_setprio 0
	s_setprio 1
	v_mfma_f32_16x16x32_bf16 v[78:81], v[168:171], v[198:201], 0
	v_mfma_f32_16x16x32_bf16 v[74:77], v[176:179], v[198:201], 0
	v_mfma_f32_16x16x32_bf16 v[46:49], v[168:171], v[206:209], 0
	v_mfma_f32_16x16x32_bf16 v[42:45], v[176:179], v[206:209], 0
	v_mfma_f32_16x16x32_bf16 v[30:33], v[168:171], v[214:217], 0
	v_mfma_f32_16x16x32_bf16 v[26:29], v[176:179], v[214:217], 0
	v_mfma_f32_16x16x32_bf16 v[14:17], v[168:171], v[222:225], 0
	v_mfma_f32_16x16x32_bf16 v[10:13], v[176:179], v[222:225], 0
	v_mfma_f32_16x16x32_bf16 v[78:81], v[172:175], v[202:205], v[78:81]
	v_mfma_f32_16x16x32_bf16 v[74:77], v[180:183], v[202:205], v[74:77]
	v_mfma_f32_16x16x32_bf16 v[46:49], v[172:175], v[210:213], v[46:49]
	v_mfma_f32_16x16x32_bf16 v[42:45], v[180:183], v[210:213], v[42:45]
	v_mfma_f32_16x16x32_bf16 v[30:33], v[172:175], v[218:221], v[30:33]
	v_mfma_f32_16x16x32_bf16 v[26:29], v[180:183], v[218:221], v[26:29]
	v_mfma_f32_16x16x32_bf16 v[14:17], v[172:175], v[226:229], v[14:17]
	v_mfma_f32_16x16x32_bf16 v[10:13], v[180:183], v[226:229], v[10:13]
	s_barrier
	s_setprio 0
	s_add_i32 vcc_hi, 0, 0x18000
	s_add_i32 s56, 0, 0x1c000
	v_add_u32_e32 v142, vcc_hi, v1
	v_add_u32_e32 v180, s56, v1
	ds_read_b128 v[130:133], v142
	ds_read_b128 v[134:137], v142 offset:1024
	ds_read_b128 v[138:141], v142 offset:2048
	ds_read_b128 v[142:145], v142 offset:3072
	ds_read_b128 v[168:171], v180
	ds_read_b128 v[172:175], v180 offset:1024
	ds_read_b128 v[176:179], v180 offset:2048
	ds_read_b128 v[180:183], v180 offset:3072
	s_add_u32 s66, s86, 0x100000
	s_addc_u32 s67, s87, 0
	s_mov_b32 m0, s93
	ds_read_b128 v[198:201], v197 offset:32768
	ds_read_b128 v[202:205], v197 offset:33792
	ds_read_b128 v[206:209], v197 offset:34816
	ds_read_b128 v[210:213], v197 offset:35840
	ds_read_b128 v[214:217], v197 offset:36864
	ds_read_b128 v[218:221], v197 offset:37888
	ds_read_b128 v[222:225], v197 offset:38912
	ds_read_b128 v[226:229], v197 offset:39936
	global_load_lds_dwordx4 v154, s[66:67]
	s_mov_b32 m0, s42
	s_nop 0
	global_load_lds_dwordx4 v158, s[66:67]
	s_waitcnt vmcnt(8)
	s_waitcnt lgkmcnt(0)
	s_setprio 1
	s_barrier
	v_mfma_f32_16x16x32_bf16 v[114:117], v[130:133], v[198:201], v[114:117]
	v_mfma_f32_16x16x32_bf16 v[118:121], v[138:141], v[198:201], v[118:121]
	v_mfma_f32_16x16x32_bf16 v[102:105], v[130:133], v[206:209], v[102:105]
	v_mfma_f32_16x16x32_bf16 v[98:101], v[138:141], v[206:209], v[98:101]
	v_mfma_f32_16x16x32_bf16 v[86:89], v[130:133], v[214:217], v[86:89]
	v_mfma_f32_16x16x32_bf16 v[82:85], v[138:141], v[214:217], v[82:85]
	v_mfma_f32_16x16x32_bf16 v[54:57], v[130:133], v[222:225], v[54:57]
	v_mfma_f32_16x16x32_bf16 v[50:53], v[138:141], v[222:225], v[50:53]
	v_mfma_f32_16x16x32_bf16 v[114:117], v[134:137], v[202:205], v[114:117]
	v_mfma_f32_16x16x32_bf16 v[118:121], v[142:145], v[202:205], v[118:121]
	v_mfma_f32_16x16x32_bf16 v[102:105], v[134:137], v[210:213], v[102:105]
	v_mfma_f32_16x16x32_bf16 v[98:101], v[142:145], v[210:213], v[98:101]
	v_mfma_f32_16x16x32_bf16 v[86:89], v[134:137], v[218:221], v[86:89]
	v_mfma_f32_16x16x32_bf16 v[82:85], v[142:145], v[218:221], v[82:85]
	v_mfma_f32_16x16x32_bf16 v[54:57], v[134:137], v[226:229], v[54:57]
	v_mfma_f32_16x16x32_bf16 v[50:53], v[142:145], v[226:229], v[50:53]
	s_setprio 0
	s_setprio 1
	v_mfma_f32_16x16x32_bf16 v[126:129], v[168:171], v[198:201], v[126:129]
	v_mfma_f32_16x16x32_bf16 v[122:125], v[176:179], v[198:201], v[122:125]
	v_mfma_f32_16x16x32_bf16 v[110:113], v[168:171], v[206:209], v[110:113]
	v_mfma_f32_16x16x32_bf16 v[106:109], v[176:179], v[206:209], v[106:109]
	v_mfma_f32_16x16x32_bf16 v[94:97], v[168:171], v[214:217], v[94:97]
	v_mfma_f32_16x16x32_bf16 v[90:93], v[176:179], v[214:217], v[90:93]
	v_mfma_f32_16x16x32_bf16 v[70:73], v[168:171], v[222:225], v[70:73]
	v_mfma_f32_16x16x32_bf16 v[66:69], v[176:179], v[222:225], v[66:69]
	v_mfma_f32_16x16x32_bf16 v[126:129], v[172:175], v[202:205], v[126:129]
	v_mfma_f32_16x16x32_bf16 v[122:125], v[180:183], v[202:205], v[122:125]
	v_mfma_f32_16x16x32_bf16 v[110:113], v[172:175], v[210:213], v[110:113]
	v_mfma_f32_16x16x32_bf16 v[106:109], v[180:183], v[210:213], v[106:109]
	v_mfma_f32_16x16x32_bf16 v[94:97], v[172:175], v[218:221], v[94:97]
	v_mfma_f32_16x16x32_bf16 v[90:93], v[180:183], v[218:221], v[90:93]
	v_mfma_f32_16x16x32_bf16 v[70:73], v[172:175], v[226:229], v[70:73]
	v_mfma_f32_16x16x32_bf16 v[66:69], v[180:183], v[226:229], v[66:69]
	s_barrier
	s_setprio 0
	s_add_i32 s57, vcc_hi, s97
	s_mov_b32 m0, s57
	ds_read_b128 v[198:201], v197 offset:49152
	ds_read_b128 v[202:205], v197 offset:50176
	ds_read_b128 v[206:209], v197 offset:51200
	ds_read_b128 v[210:213], v197 offset:52224
	ds_read_b128 v[214:217], v197 offset:53248
	ds_read_b128 v[218:221], v197 offset:54272
	ds_read_b128 v[222:225], v197 offset:55296
	ds_read_b128 v[226:229], v197 offset:56320
	global_load_lds_dwordx4 v156, s[98:99]
	s_add_i32 m0, s57, 0x2000
	s_add_u32 s38, s38, 0x100080
	s_addc_u32 s39, s39, 0
	s_add_i32 s56, s56, s97
	global_load_lds_dwordx4 v160, s[98:99]
	s_mov_b32 m0, s56
	s_nop 0
	global_load_lds_dwordx4 v156, s[38:39]
	s_add_i32 m0, s56, 0x2000
	s_nop 0
	global_load_lds_dwordx4 v160, s[38:39]
	s_mov_b32 m0, s43
	s_nop 0
	global_load_lds_dwordx4 v154, s[100:101]
	s_mov_b32 m0, s90
	s_nop 0
	global_load_lds_dwordx4 v158, s[100:101]
	s_waitcnt vmcnt(8)
	s_waitcnt lgkmcnt(0)
	s_setprio 1
	s_barrier
	v_mfma_f32_16x16x32_bf16 v[62:65], v[130:133], v[198:201], v[62:65]
	v_mfma_f32_16x16x32_bf16 v[58:61], v[138:141], v[198:201], v[58:61]
	v_mfma_f32_16x16x32_bf16 v[38:41], v[130:133], v[206:209], v[38:41]
	v_mfma_f32_16x16x32_bf16 v[34:37], v[138:141], v[206:209], v[34:37]
	v_mfma_f32_16x16x32_bf16 v[22:25], v[130:133], v[214:217], v[22:25]
	v_mfma_f32_16x16x32_bf16 v[18:21], v[138:141], v[214:217], v[18:21]
	v_mfma_f32_16x16x32_bf16 v[6:9], v[130:133], v[222:225], v[6:9]
	v_mfma_f32_16x16x32_bf16 v[2:5], v[138:141], v[222:225], v[2:5]
	v_mfma_f32_16x16x32_bf16 v[62:65], v[134:137], v[202:205], v[62:65]
	v_mfma_f32_16x16x32_bf16 v[58:61], v[142:145], v[202:205], v[58:61]
	v_mfma_f32_16x16x32_bf16 v[38:41], v[134:137], v[210:213], v[38:41]
	v_mfma_f32_16x16x32_bf16 v[34:37], v[142:145], v[210:213], v[34:37]
	v_mfma_f32_16x16x32_bf16 v[22:25], v[134:137], v[218:221], v[22:25]
	v_mfma_f32_16x16x32_bf16 v[18:21], v[142:145], v[218:221], v[18:21]
	v_mfma_f32_16x16x32_bf16 v[6:9], v[134:137], v[226:229], v[6:9]
	v_mfma_f32_16x16x32_bf16 v[2:5], v[142:145], v[226:229], v[2:5]
	s_setprio 0
	s_setprio 1
	v_mfma_f32_16x16x32_bf16 v[78:81], v[168:171], v[198:201], v[78:81]
	v_mfma_f32_16x16x32_bf16 v[74:77], v[176:179], v[198:201], v[74:77]
	v_mfma_f32_16x16x32_bf16 v[46:49], v[168:171], v[206:209], v[46:49]
	v_mfma_f32_16x16x32_bf16 v[42:45], v[176:179], v[206:209], v[42:45]
	v_mfma_f32_16x16x32_bf16 v[30:33], v[168:171], v[214:217], v[30:33]
	v_mfma_f32_16x16x32_bf16 v[26:29], v[176:179], v[214:217], v[26:29]
	v_mfma_f32_16x16x32_bf16 v[14:17], v[168:171], v[222:225], v[14:17]
	v_mfma_f32_16x16x32_bf16 v[10:13], v[176:179], v[222:225], v[10:13]
	v_mfma_f32_16x16x32_bf16 v[78:81], v[172:175], v[202:205], v[78:81]
	v_mfma_f32_16x16x32_bf16 v[74:77], v[180:183], v[202:205], v[74:77]
	v_mfma_f32_16x16x32_bf16 v[46:49], v[172:175], v[210:213], v[46:49]
	v_mfma_f32_16x16x32_bf16 v[42:45], v[180:183], v[210:213], v[42:45]
	v_mfma_f32_16x16x32_bf16 v[30:33], v[172:175], v[218:221], v[30:33]
	v_mfma_f32_16x16x32_bf16 v[26:29], v[180:183], v[218:221], v[26:29]
	v_mfma_f32_16x16x32_bf16 v[14:17], v[172:175], v[226:229], v[14:17]
	v_mfma_f32_16x16x32_bf16 v[10:13], v[180:183], v[226:229], v[10:13]
	s_barrier
	s_setprio 0
	s_add_u32 s40, s40, 0x100
	s_addc_u32 s49, s49, 0
	s_add_u32 s10, s10, 0x100
	s_addc_u32 s11, s11, 0
	s_cmp_ge_u32 vcc_lo, s19
	s_mov_b32 s38, vcc_lo
	s_cbranch_scc1 .Lpeel_done_0
.LBB0_262:
	s_add_i32 vcc_lo, s38, 2
	s_add_u32 s39, s10, 0xfff00080
	s_addc_u32 s66, s11, -1
	s_add_i32 s67, 0, 0x10000
	s_cmp_eq_u32 s35, s38
	s_cselect_b32 s87, s53, s66
	s_cselect_b32 s86, s52, s39
	s_cselect_b32 s39, s13, s49
	s_cselect_b32 s38, s15, s40
	s_add_i32 vcc_hi, 0, 0x14000
	v_add_u32_e32 v142, s67, v1
	v_add_u32_e32 v180, vcc_hi, v1
	ds_read_b128 v[130:133], v142
	ds_read_b128 v[134:137], v142 offset:1024
	ds_read_b128 v[138:141], v142 offset:2048
	ds_read_b128 v[142:145], v142 offset:3072
	ds_read_b128 v[168:171], v180
	ds_read_b128 v[172:175], v180 offset:1024
	ds_read_b128 v[176:179], v180 offset:2048
	ds_read_b128 v[180:183], v180 offset:3072
	s_add_i32 m0, s85, 0xc000
	ds_read_b128 v[198:201], v197
	ds_read_b128 v[202:205], v197 offset:1024
	ds_read_b128 v[206:209], v197 offset:2048
	ds_read_b128 v[210:213], v197 offset:3072
	ds_read_b128 v[214:217], v197 offset:4096
	ds_read_b128 v[218:221], v197 offset:5120
	ds_read_b128 v[222:225], v197 offset:6144
	ds_read_b128 v[226:229], v197 offset:7168
	global_load_lds_dwordx4 v164, s[10:11]
	s_add_i32 m0, s85, 0xe000
	s_nop 0
	global_load_lds_dwordx4 v166, s[10:11]
	s_waitcnt vmcnt(8)
	s_waitcnt lgkmcnt(0)
	s_setprio 1
	s_barrier
	v_mfma_f32_16x16x32_bf16 v[114:117], v[130:133], v[198:201], v[114:117]
	v_mfma_f32_16x16x32_bf16 v[118:121], v[138:141], v[198:201], v[118:121]
	v_mfma_f32_16x16x32_bf16 v[102:105], v[130:133], v[206:209], v[102:105]
	v_mfma_f32_16x16x32_bf16 v[98:101], v[138:141], v[206:209], v[98:101]
	v_mfma_f32_16x16x32_bf16 v[86:89], v[130:133], v[214:217], v[86:89]
	v_mfma_f32_16x16x32_bf16 v[82:85], v[138:141], v[214:217], v[82:85]
	v_mfma_f32_16x16x32_bf16 v[54:57], v[130:133], v[222:225], v[54:57]
	v_mfma_f32_16x16x32_bf16 v[50:53], v[138:141], v[222:225], v[50:53]
	v_mfma_f32_16x16x32_bf16 v[114:117], v[134:137], v[202:205], v[114:117]
	v_mfma_f32_16x16x32_bf16 v[118:121], v[142:145], v[202:205], v[118:121]
	v_mfma_f32_16x16x32_bf16 v[102:105], v[134:137], v[210:213], v[102:105]
	v_mfma_f32_16x16x32_bf16 v[98:101], v[142:145], v[210:213], v[98:101]
	v_mfma_f32_16x16x32_bf16 v[86:89], v[134:137], v[218:221], v[86:89]
	v_mfma_f32_16x16x32_bf16 v[82:85], v[142:145], v[218:221], v[82:85]
	v_mfma_f32_16x16x32_bf16 v[54:57], v[134:137], v[226:229], v[54:57]
	v_mfma_f32_16x16x32_bf16 v[50:53], v[142:145], v[226:229], v[50:53]
	s_setprio 0
	s_setprio 1
	v_mfma_f32_16x16x32_bf16 v[126:129], v[168:171], v[198:201], v[126:129]
	v_mfma_f32_16x16x32_bf16 v[122:125], v[176:179], v[198:201], v[122:125]
	v_mfma_f32_16x16x32_bf16 v[110:113], v[168:171], v[206:209], v[110:113]
	v_mfma_f32_16x16x32_bf16 v[106:109], v[176:179], v[206:209], v[106:109]
	v_mfma_f32_16x16x32_bf16 v[94:97], v[168:171], v[214:217], v[94:97]
	v_mfma_f32_16x16x32_bf16 v[90:93], v[176:179], v[214:217], v[90:93]
	v_mfma_f32_16x16x32_bf16 v[70:73], v[168:171], v[222:225], v[70:73]
	v_mfma_f32_16x16x32_bf16 v[66:69], v[176:179], v[222:225], v[66:69]
	v_mfma_f32_16x16x32_bf16 v[126:129], v[172:175], v[202:205], v[126:129]
	v_mfma_f32_16x16x32_bf16 v[122:125], v[180:183], v[202:205], v[122:125]
	v_mfma_f32_16x16x32_bf16 v[110:113], v[172:175], v[210:213], v[110:113]
	v_mfma_f32_16x16x32_bf16 v[106:109], v[180:183], v[210:213], v[106:109]
	v_mfma_f32_16x16x32_bf16 v[94:97], v[172:175], v[218:221], v[94:97]
	v_mfma_f32_16x16x32_bf16 v[90:93], v[180:183], v[218:221], v[90:93]
	v_mfma_f32_16x16x32_bf16 v[70:73], v[172:175], v[226:229], v[70:73]
	v_mfma_f32_16x16x32_bf16 v[66:69], v[180:183], v[226:229], v[66:69]
	s_barrier
	s_setprio 0
	s_add_i32 s66, s67, s97
	s_add_u32 s98, s38, 0x80
	s_addc_u32 s99, s39, 0
	s_mov_b32 m0, s66
	ds_read_b128 v[198:201], v197 offset:16384
	ds_read_b128 v[202:205], v197 offset:17408
	ds_read_b128 v[206:209], v197 offset:18432
	ds_read_b128 v[210:213], v197 offset:19456
	ds_read_b128 v[214:217], v197 offset:20480
	ds_read_b128 v[218:221], v197 offset:21504
	ds_read_b128 v[222:225], v197 offset:22528
	ds_read_b128 v[226:229], v197 offset:23552
	global_load_lds_dwordx4 v156, s[38:39]
	s_add_i32 m0, s66, 0x2000
	s_add_u32 s66, s38, 0x100000
	s_addc_u32 s67, s39, 0
	s_add_i32 vcc_hi, vcc_hi, s97
	global_load_lds_dwordx4 v160, s[38:39]
	s_mov_b32 m0, vcc_hi
	s_add_u32 s100, s86, 0x80
	s_addc_u32 s101, s87, 0
	global_load_lds_dwordx4 v156, s[66:67]
	s_add_i32 m0, vcc_hi, 0x2000
	s_nop 0
	global_load_lds_dwordx4 v160, s[66:67]
	s_mov_b32 m0, s85
	s_nop 0
	global_load_lds_dwordx4 v154, s[86:87]
	s_mov_b32 m0, s92
	s_nop 0
	global_load_lds_dwordx4 v158, s[86:87]
	s_waitcnt vmcnt(8)
	s_waitcnt lgkmcnt(0)
	s_setprio 1
	s_barrier
	v_mfma_f32_16x16x32_bf16 v[62:65], v[130:133], v[198:201], v[62:65]
	v_mfma_f32_16x16x32_bf16 v[58:61], v[138:141], v[198:201], v[58:61]
	v_mfma_f32_16x16x32_bf16 v[38:41], v[130:133], v[206:209], v[38:41]
	v_mfma_f32_16x16x32_bf16 v[34:37], v[138:141], v[206:209], v[34:37]
	v_mfma_f32_16x16x32_bf16 v[22:25], v[130:133], v[214:217], v[22:25]
	v_mfma_f32_16x16x32_bf16 v[18:21], v[138:141], v[214:217], v[18:21]
	v_mfma_f32_16x16x32_bf16 v[6:9], v[130:133], v[222:225], v[6:9]
	v_mfma_f32_16x16x32_bf16 v[2:5], v[138:141], v[222:225], v[2:5]
	v_mfma_f32_16x16x32_bf16 v[62:65], v[134:137], v[202:205], v[62:65]
	v_mfma_f32_16x16x32_bf16 v[58:61], v[142:145], v[202:205], v[58:61]
	v_mfma_f32_16x16x32_bf16 v[38:41], v[134:137], v[210:213], v[38:41]
	v_mfma_f32_16x16x32_bf16 v[34:37], v[142:145], v[210:213], v[34:37]
	v_mfma_f32_16x16x32_bf16 v[22:25], v[134:137], v[218:221], v[22:25]
	v_mfma_f32_16x16x32_bf16 v[18:21], v[142:145], v[218:221], v[18:21]
	v_mfma_f32_16x16x32_bf16 v[6:9], v[134:137], v[226:229], v[6:9]
	v_mfma_f32_16x16x32_bf16 v[2:5], v[142:145], v[226:229], v[2:5]
	s_setprio 0
	s_setprio 1
	v_mfma_f32_16x16x32_bf16 v[78:81], v[168:171], v[198:201], v[78:81]
	v_mfma_f32_16x16x32_bf16 v[74:77], v[176:179], v[198:201], v[74:77]
	v_mfma_f32_16x16x32_bf16 v[46:49], v[168:171], v[206:209], v[46:49]
	v_mfma_f32_16x16x32_bf16 v[42:45], v[176:179], v[206:209], v[42:45]
	v_mfma_f32_16x16x32_bf16 v[30:33], v[168:171], v[214:217], v[30:33]
	v_mfma_f32_16x16x32_bf16 v[26:29], v[176:179], v[214:217], v[26:29]
	v_mfma_f32_16x16x32_bf16 v[14:17], v[168:171], v[222:225], v[14:17]
	v_mfma_f32_16x16x32_bf16 v[10:13], v[176:179], v[222:225], v[10:13]
	v_mfma_f32_16x16x32_bf16 v[78:81], v[172:175], v[202:205], v[78:81]
	v_mfma_f32_16x16x32_bf16 v[74:77], v[180:183], v[202:205], v[74:77]
	v_mfma_f32_16x16x32_bf16 v[46:49], v[172:175], v[210:213], v[46:49]
	v_mfma_f32_16x16x32_bf16 v[42:45], v[180:183], v[210:213], v[42:45]
	v_mfma_f32_16x16x32_bf16 v[30:33], v[172:175], v[218:221], v[30:33]
	v_mfma_f32_16x16x32_bf16 v[26:29], v[180:183], v[218:221], v[26:29]
	v_mfma_f32_16x16x32_bf16 v[14:17], v[172:175], v[226:229], v[14:17]
	v_mfma_f32_16x16x32_bf16 v[10:13], v[180:183], v[226:229], v[10:13]
	s_barrier
	s_setprio 0
	s_add_i32 vcc_hi, 0, 0x18000
	s_add_i32 s56, 0, 0x1c000
	v_add_u32_e32 v142, vcc_hi, v1
	v_add_u32_e32 v180, s56, v1
	ds_read_b128 v[130:133], v142
	ds_read_b128 v[134:137], v142 offset:1024
	ds_read_b128 v[138:141], v142 offset:2048
	ds_read_b128 v[142:145], v142 offset:3072
	ds_read_b128 v[168:171], v180
	ds_read_b128 v[172:175], v180 offset:1024
	ds_read_b128 v[176:179], v180 offset:2048
	ds_read_b128 v[180:183], v180 offset:3072
	s_add_u32 s66, s86, 0x100000
	s_addc_u32 s67, s87, 0
	s_mov_b32 m0, s93
	ds_read_b128 v[198:201], v197 offset:32768
	ds_read_b128 v[202:205], v197 offset:33792
	ds_read_b128 v[206:209], v197 offset:34816
	ds_read_b128 v[210:213], v197 offset:35840
	ds_read_b128 v[214:217], v197 offset:36864
	ds_read_b128 v[218:221], v197 offset:37888
	ds_read_b128 v[222:225], v197 offset:38912
	ds_read_b128 v[226:229], v197 offset:39936
	global_load_lds_dwordx4 v154, s[66:67]
	s_mov_b32 m0, s42
	s_nop 0
	global_load_lds_dwordx4 v158, s[66:67]
	s_waitcnt vmcnt(8)
	s_waitcnt lgkmcnt(0)
	s_setprio 1
	s_barrier
	v_mfma_f32_16x16x32_bf16 v[114:117], v[130:133], v[198:201], v[114:117]
	v_mfma_f32_16x16x32_bf16 v[118:121], v[138:141], v[198:201], v[118:121]
	v_mfma_f32_16x16x32_bf16 v[102:105], v[130:133], v[206:209], v[102:105]
	v_mfma_f32_16x16x32_bf16 v[98:101], v[138:141], v[206:209], v[98:101]
	v_mfma_f32_16x16x32_bf16 v[86:89], v[130:133], v[214:217], v[86:89]
	v_mfma_f32_16x16x32_bf16 v[82:85], v[138:141], v[214:217], v[82:85]
	v_mfma_f32_16x16x32_bf16 v[54:57], v[130:133], v[222:225], v[54:57]
	v_mfma_f32_16x16x32_bf16 v[50:53], v[138:141], v[222:225], v[50:53]
	v_mfma_f32_16x16x32_bf16 v[114:117], v[134:137], v[202:205], v[114:117]
	v_mfma_f32_16x16x32_bf16 v[118:121], v[142:145], v[202:205], v[118:121]
	v_mfma_f32_16x16x32_bf16 v[102:105], v[134:137], v[210:213], v[102:105]
	v_mfma_f32_16x16x32_bf16 v[98:101], v[142:145], v[210:213], v[98:101]
	v_mfma_f32_16x16x32_bf16 v[86:89], v[134:137], v[218:221], v[86:89]
	v_mfma_f32_16x16x32_bf16 v[82:85], v[142:145], v[218:221], v[82:85]
	v_mfma_f32_16x16x32_bf16 v[54:57], v[134:137], v[226:229], v[54:57]
	v_mfma_f32_16x16x32_bf16 v[50:53], v[142:145], v[226:229], v[50:53]
	s_setprio 0
	s_setprio 1
	v_mfma_f32_16x16x32_bf16 v[126:129], v[168:171], v[198:201], v[126:129]
	v_mfma_f32_16x16x32_bf16 v[122:125], v[176:179], v[198:201], v[122:125]
	v_mfma_f32_16x16x32_bf16 v[110:113], v[168:171], v[206:209], v[110:113]
	v_mfma_f32_16x16x32_bf16 v[106:109], v[176:179], v[206:209], v[106:109]
	v_mfma_f32_16x16x32_bf16 v[94:97], v[168:171], v[214:217], v[94:97]
	v_mfma_f32_16x16x32_bf16 v[90:93], v[176:179], v[214:217], v[90:93]
	v_mfma_f32_16x16x32_bf16 v[70:73], v[168:171], v[222:225], v[70:73]
	v_mfma_f32_16x16x32_bf16 v[66:69], v[176:179], v[222:225], v[66:69]
	v_mfma_f32_16x16x32_bf16 v[126:129], v[172:175], v[202:205], v[126:129]
	v_mfma_f32_16x16x32_bf16 v[122:125], v[180:183], v[202:205], v[122:125]
	v_mfma_f32_16x16x32_bf16 v[110:113], v[172:175], v[210:213], v[110:113]
	v_mfma_f32_16x16x32_bf16 v[106:109], v[180:183], v[210:213], v[106:109]
	v_mfma_f32_16x16x32_bf16 v[94:97], v[172:175], v[218:221], v[94:97]
	v_mfma_f32_16x16x32_bf16 v[90:93], v[180:183], v[218:221], v[90:93]
	v_mfma_f32_16x16x32_bf16 v[70:73], v[172:175], v[226:229], v[70:73]
	v_mfma_f32_16x16x32_bf16 v[66:69], v[180:183], v[226:229], v[66:69]
	s_barrier
	s_setprio 0
	s_add_i32 s57, vcc_hi, s97
	s_mov_b32 m0, s57
	ds_read_b128 v[198:201], v197 offset:49152
	ds_read_b128 v[202:205], v197 offset:50176
	ds_read_b128 v[206:209], v197 offset:51200
	ds_read_b128 v[210:213], v197 offset:52224
	ds_read_b128 v[214:217], v197 offset:53248
	ds_read_b128 v[218:221], v197 offset:54272
	ds_read_b128 v[222:225], v197 offset:55296
	ds_read_b128 v[226:229], v197 offset:56320
	global_load_lds_dwordx4 v156, s[98:99]
	s_add_i32 m0, s57, 0x2000
	s_add_u32 s38, s38, 0x100080
	s_addc_u32 s39, s39, 0
	s_add_i32 s56, s56, s97
	global_load_lds_dwordx4 v160, s[98:99]
	s_mov_b32 m0, s56
	s_nop 0
	global_load_lds_dwordx4 v156, s[38:39]
	s_add_i32 m0, s56, 0x2000
	s_nop 0
	global_load_lds_dwordx4 v160, s[38:39]
	s_mov_b32 m0, s43
	s_nop 0
	global_load_lds_dwordx4 v154, s[100:101]
	s_mov_b32 m0, s90
	s_nop 0
	global_load_lds_dwordx4 v158, s[100:101]
	s_waitcnt vmcnt(8)
	s_waitcnt lgkmcnt(0)
	s_setprio 1
	s_barrier
	v_mfma_f32_16x16x32_bf16 v[62:65], v[130:133], v[198:201], v[62:65]
	v_mfma_f32_16x16x32_bf16 v[58:61], v[138:141], v[198:201], v[58:61]
	v_mfma_f32_16x16x32_bf16 v[38:41], v[130:133], v[206:209], v[38:41]
	v_mfma_f32_16x16x32_bf16 v[34:37], v[138:141], v[206:209], v[34:37]
	v_mfma_f32_16x16x32_bf16 v[22:25], v[130:133], v[214:217], v[22:25]
	v_mfma_f32_16x16x32_bf16 v[18:21], v[138:141], v[214:217], v[18:21]
	v_mfma_f32_16x16x32_bf16 v[6:9], v[130:133], v[222:225], v[6:9]
	v_mfma_f32_16x16x32_bf16 v[2:5], v[138:141], v[222:225], v[2:5]
	v_mfma_f32_16x16x32_bf16 v[62:65], v[134:137], v[202:205], v[62:65]
	v_mfma_f32_16x16x32_bf16 v[58:61], v[142:145], v[202:205], v[58:61]
	v_mfma_f32_16x16x32_bf16 v[38:41], v[134:137], v[210:213], v[38:41]
	v_mfma_f32_16x16x32_bf16 v[34:37], v[142:145], v[210:213], v[34:37]
	v_mfma_f32_16x16x32_bf16 v[22:25], v[134:137], v[218:221], v[22:25]
	v_mfma_f32_16x16x32_bf16 v[18:21], v[142:145], v[218:221], v[18:21]
	v_mfma_f32_16x16x32_bf16 v[6:9], v[134:137], v[226:229], v[6:9]
	v_mfma_f32_16x16x32_bf16 v[2:5], v[142:145], v[226:229], v[2:5]
	s_setprio 0
	s_setprio 1
	v_mfma_f32_16x16x32_bf16 v[78:81], v[168:171], v[198:201], v[78:81]
	v_mfma_f32_16x16x32_bf16 v[74:77], v[176:179], v[198:201], v[74:77]
	v_mfma_f32_16x16x32_bf16 v[46:49], v[168:171], v[206:209], v[46:49]
	v_mfma_f32_16x16x32_bf16 v[42:45], v[176:179], v[206:209], v[42:45]
	v_mfma_f32_16x16x32_bf16 v[30:33], v[168:171], v[214:217], v[30:33]
	v_mfma_f32_16x16x32_bf16 v[26:29], v[176:179], v[214:217], v[26:29]
	v_mfma_f32_16x16x32_bf16 v[14:17], v[168:171], v[222:225], v[14:17]
	v_mfma_f32_16x16x32_bf16 v[10:13], v[176:179], v[222:225], v[10:13]
	v_mfma_f32_16x16x32_bf16 v[78:81], v[172:175], v[202:205], v[78:81]
	v_mfma_f32_16x16x32_bf16 v[74:77], v[180:183], v[202:205], v[74:77]
	v_mfma_f32_16x16x32_bf16 v[46:49], v[172:175], v[210:213], v[46:49]
	v_mfma_f32_16x16x32_bf16 v[42:45], v[180:183], v[210:213], v[42:45]
	v_mfma_f32_16x16x32_bf16 v[30:33], v[172:175], v[218:221], v[30:33]
	v_mfma_f32_16x16x32_bf16 v[26:29], v[180:183], v[218:221], v[26:29]
	v_mfma_f32_16x16x32_bf16 v[14:17], v[172:175], v[226:229], v[14:17]
	v_mfma_f32_16x16x32_bf16 v[10:13], v[180:183], v[226:229], v[10:13]
	s_barrier
	s_setprio 0
	s_add_u32 s40, s40, 0x100
	s_addc_u32 s49, s49, 0
	s_add_u32 s10, s10, 0x100
	s_addc_u32 s11, s11, 0
	s_cmp_ge_u32 vcc_lo, s19
	s_mov_b32 s38, vcc_lo
	s_cbranch_scc0 .LBB0_262

.LBB0_1692:
	s_ashr_i32 s13, s12, 31
	s_lshl_b64 s[16:17], s[12:13], 18
	s_add_u32 s16, s45, s16
	s_addc_u32 s17, s44, s17
	s_and_b64 s[26:27], s[26:27], exec
	s_cselect_b32 s13, s17, s25
	s_cselect_b32 s15, s16, s24
	s_add_u32 s34, s24, 0x100
	s_addc_u32 s35, s25, 0
	s_add_u32 s22, s22, 0x80080
	s_addc_u32 s23, s23, 0
	s_mov_b32 s36, -2
	ds_read_b128 v[128:131], v169
	ds_read_b128 v[132:135], v169 offset:1024
	ds_read_b128 v[136:139], v169 offset:2048
	ds_read_b128 v[140:143], v169 offset:3072
	ds_read_b128 v[158:161], v170
	ds_read_b128 v[162:165], v170 offset:1024
	ds_read_b128 v[172:175], v170 offset:2048
	ds_read_b128 v[176:179], v170 offset:3072
	s_add_u32 s24, s22, 0xfff80080
	s_addc_u32 s25, s23, -1
	s_cmp_eq_u32 s36, 4
	s_cselect_b32 s27, s5, s25
	s_cselect_b32 s26, s4, s24
	s_cselect_b32 s25, s13, s35
	s_cselect_b32 s24, s15, s34
	s_add_i32 m0, s94, 0xc000
	ds_read_b128 v[180:183], v171
	ds_read_b128 v[184:187], v171 offset:1024
	ds_read_b128 v[188:191], v171 offset:2048
	ds_read_b128 v[192:195], v171 offset:3072
	ds_read_b128 v[196:199], v171 offset:4096
	ds_read_b128 v[200:203], v171 offset:5120
	ds_read_b128 v[204:207], v171 offset:6144
	ds_read_b128 v[208:211], v171 offset:7168
	global_load_lds_dwordx4 v152, s[22:23]
	s_add_i32 m0, s94, 0xe000
	s_nop 0
	global_load_lds_dwordx4 v154, s[22:23]
	s_waitcnt vmcnt(8)
	s_waitcnt lgkmcnt(0)
	s_setprio 1
	s_barrier
	v_mfma_f32_16x16x32_bf16 v[80:83], v[128:131], v[180:183], 0
	v_mfma_f32_16x16x32_bf16 v[92:95], v[136:139], v[180:183], 0
	v_mfma_f32_16x16x32_bf16 v[84:87], v[128:131], v[188:191], 0
	v_mfma_f32_16x16x32_bf16 v[96:99], v[136:139], v[188:191], 0
	v_mfma_f32_16x16x32_bf16 v[88:91], v[128:131], v[196:199], 0
	v_mfma_f32_16x16x32_bf16 v[100:103], v[136:139], v[196:199], 0
	v_mfma_f32_16x16x32_bf16 v[72:75], v[128:131], v[204:207], 0
	v_mfma_f32_16x16x32_bf16 v[76:79], v[136:139], v[204:207], 0
	v_mfma_f32_16x16x32_bf16 v[80:83], v[132:135], v[184:187], v[80:83]
	v_mfma_f32_16x16x32_bf16 v[92:95], v[140:143], v[184:187], v[92:95]
	v_mfma_f32_16x16x32_bf16 v[84:87], v[132:135], v[192:195], v[84:87]
	v_mfma_f32_16x16x32_bf16 v[96:99], v[140:143], v[192:195], v[96:99]
	v_mfma_f32_16x16x32_bf16 v[88:91], v[132:135], v[200:203], v[88:91]
	v_mfma_f32_16x16x32_bf16 v[100:103], v[140:143], v[200:203], v[100:103]
	v_mfma_f32_16x16x32_bf16 v[72:75], v[132:135], v[208:211], v[72:75]
	v_mfma_f32_16x16x32_bf16 v[76:79], v[140:143], v[208:211], v[76:79]
	s_setprio 0
	s_setprio 1
	v_mfma_f32_16x16x32_bf16 v[104:107], v[158:161], v[180:183], 0
	v_mfma_f32_16x16x32_bf16 v[116:119], v[172:175], v[180:183], 0
	v_mfma_f32_16x16x32_bf16 v[108:111], v[158:161], v[188:191], 0
	v_mfma_f32_16x16x32_bf16 v[120:123], v[172:175], v[188:191], 0
	v_mfma_f32_16x16x32_bf16 v[112:115], v[158:161], v[196:199], 0
	v_mfma_f32_16x16x32_bf16 v[124:127], v[172:175], v[196:199], 0
	v_mfma_f32_16x16x32_bf16 v[68:71], v[158:161], v[204:207], 0
	v_mfma_f32_16x16x32_bf16 v[64:67], v[172:175], v[204:207], 0
	v_mfma_f32_16x16x32_bf16 v[104:107], v[162:165], v[184:187], v[104:107]
	v_mfma_f32_16x16x32_bf16 v[116:119], v[176:179], v[184:187], v[116:119]
	v_mfma_f32_16x16x32_bf16 v[108:111], v[162:165], v[192:195], v[108:111]
	v_mfma_f32_16x16x32_bf16 v[120:123], v[176:179], v[192:195], v[120:123]
	v_mfma_f32_16x16x32_bf16 v[112:115], v[162:165], v[200:203], v[112:115]
	v_mfma_f32_16x16x32_bf16 v[124:127], v[176:179], v[200:203], v[124:127]
	v_mfma_f32_16x16x32_bf16 v[68:71], v[162:165], v[208:211], v[68:71]
	v_mfma_f32_16x16x32_bf16 v[64:67], v[176:179], v[208:211], v[64:67]
	s_barrier
	s_setprio 0
	s_add_i32 s37, s31, s97
	s_add_u32 s98, s24, 0x80
	s_addc_u32 s99, s25, 0
	s_mov_b32 m0, s37
	ds_read_b128 v[180:183], v171 offset:16384
	ds_read_b128 v[184:187], v171 offset:17408
	ds_read_b128 v[188:191], v171 offset:18432
	ds_read_b128 v[192:195], v171 offset:19456
	ds_read_b128 v[196:199], v171 offset:20480
	ds_read_b128 v[200:203], v171 offset:21504
	ds_read_b128 v[204:207], v171 offset:22528
	ds_read_b128 v[208:211], v171 offset:23552
	global_load_lds_dwordx4 v148, s[24:25]
	s_add_i32 m0, s37, 0x2000
	s_add_u32 s38, s24, 0x20000
	s_addc_u32 s39, s25, 0
	s_add_i32 s37, s33, s97
	global_load_lds_dwordx4 v144, s[24:25]
	s_mov_b32 m0, s37
	s_add_u32 s100, s26, 0x80
	s_addc_u32 s101, s27, 0
	global_load_lds_dwordx4 v148, s[38:39]
	s_add_i32 m0, s37, 0x2000
	s_nop 0
	global_load_lds_dwordx4 v144, s[38:39]
	s_mov_b32 m0, s94
	s_nop 0
	global_load_lds_dwordx4 v150, s[26:27]
	s_mov_b32 m0, s3
	s_nop 0
	global_load_lds_dwordx4 v146, s[26:27]
	s_waitcnt vmcnt(8)
	s_waitcnt lgkmcnt(0)
	s_setprio 1
	s_barrier
	v_mfma_f32_16x16x32_bf16 v[48:51], v[128:131], v[180:183], 0
	v_mfma_f32_16x16x32_bf16 v[52:55], v[136:139], v[180:183], 0
	v_mfma_f32_16x16x32_bf16 v[32:35], v[128:131], v[188:191], 0
	v_mfma_f32_16x16x32_bf16 v[36:39], v[136:139], v[188:191], 0
	v_mfma_f32_16x16x32_bf16 v[16:19], v[128:131], v[196:199], 0
	v_mfma_f32_16x16x32_bf16 v[20:23], v[136:139], v[196:199], 0
	v_mfma_f32_16x16x32_bf16 v[0:3], v[128:131], v[204:207], 0
	v_mfma_f32_16x16x32_bf16 v[4:7], v[136:139], v[204:207], 0
	v_mfma_f32_16x16x32_bf16 v[48:51], v[132:135], v[184:187], v[48:51]
	v_mfma_f32_16x16x32_bf16 v[52:55], v[140:143], v[184:187], v[52:55]
	v_mfma_f32_16x16x32_bf16 v[32:35], v[132:135], v[192:195], v[32:35]
	v_mfma_f32_16x16x32_bf16 v[36:39], v[140:143], v[192:195], v[36:39]
	v_mfma_f32_16x16x32_bf16 v[16:19], v[132:135], v[200:203], v[16:19]
	v_mfma_f32_16x16x32_bf16 v[20:23], v[140:143], v[200:203], v[20:23]
	v_mfma_f32_16x16x32_bf16 v[0:3], v[132:135], v[208:211], v[0:3]
	v_mfma_f32_16x16x32_bf16 v[4:7], v[140:143], v[208:211], v[4:7]
	s_setprio 0
	s_setprio 1
	v_mfma_f32_16x16x32_bf16 v[56:59], v[158:161], v[180:183], 0
	v_mfma_f32_16x16x32_bf16 v[60:63], v[172:175], v[180:183], 0
	v_mfma_f32_16x16x32_bf16 v[40:43], v[158:161], v[188:191], 0
	v_mfma_f32_16x16x32_bf16 v[44:47], v[172:175], v[188:191], 0
	v_mfma_f32_16x16x32_bf16 v[24:27], v[158:161], v[196:199], 0
	v_mfma_f32_16x16x32_bf16 v[28:31], v[172:175], v[196:199], 0
	v_mfma_f32_16x16x32_bf16 v[8:11], v[158:161], v[204:207], 0
	v_mfma_f32_16x16x32_bf16 v[12:15], v[172:175], v[204:207], 0
	v_mfma_f32_16x16x32_bf16 v[56:59], v[162:165], v[184:187], v[56:59]
	v_mfma_f32_16x16x32_bf16 v[60:63], v[176:179], v[184:187], v[60:63]
	v_mfma_f32_16x16x32_bf16 v[40:43], v[162:165], v[192:195], v[40:43]
	v_mfma_f32_16x16x32_bf16 v[44:47], v[176:179], v[192:195], v[44:47]
	v_mfma_f32_16x16x32_bf16 v[24:27], v[162:165], v[200:203], v[24:27]
	v_mfma_f32_16x16x32_bf16 v[28:31], v[176:179], v[200:203], v[28:31]
	v_mfma_f32_16x16x32_bf16 v[8:11], v[162:165], v[208:211], v[8:11]
	v_mfma_f32_16x16x32_bf16 v[12:15], v[176:179], v[208:211], v[12:15]
	s_barrier
	s_setprio 0
	s_add_i32 s37, 0, 0x18000
	s_add_i32 s38, 0, 0x1c000
	v_add_u32_e32 v140, s37, v167
	v_add_u32_e32 v176, s38, v167
	ds_read_b128 v[128:131], v140
	ds_read_b128 v[132:135], v140 offset:1024
	ds_read_b128 v[136:139], v140 offset:2048
	ds_read_b128 v[140:143], v140 offset:3072
	ds_read_b128 v[158:161], v176
	ds_read_b128 v[162:165], v176 offset:1024
	ds_read_b128 v[172:175], v176 offset:2048
	ds_read_b128 v[176:179], v176 offset:3072
	s_add_u32 s26, s26, 0x80000
	s_addc_u32 s27, s27, 0
	s_mov_b32 m0, s7
	ds_read_b128 v[180:183], v171 offset:32768
	ds_read_b128 v[184:187], v171 offset:33792
	ds_read_b128 v[188:191], v171 offset:34816
	ds_read_b128 v[192:195], v171 offset:35840
	ds_read_b128 v[196:199], v171 offset:36864
	ds_read_b128 v[200:203], v171 offset:37888
	ds_read_b128 v[204:207], v171 offset:38912
	ds_read_b128 v[208:211], v171 offset:39936
	global_load_lds_dwordx4 v150, s[26:27]
	s_mov_b32 m0, s19
	s_nop 0
	global_load_lds_dwordx4 v146, s[26:27]
	s_waitcnt vmcnt(8)
	s_waitcnt lgkmcnt(0)
	s_setprio 1
	s_barrier
	v_mfma_f32_16x16x32_bf16 v[80:83], v[128:131], v[180:183], v[80:83]
	v_mfma_f32_16x16x32_bf16 v[92:95], v[136:139], v[180:183], v[92:95]
	v_mfma_f32_16x16x32_bf16 v[84:87], v[128:131], v[188:191], v[84:87]
	v_mfma_f32_16x16x32_bf16 v[96:99], v[136:139], v[188:191], v[96:99]
	v_mfma_f32_16x16x32_bf16 v[88:91], v[128:131], v[196:199], v[88:91]
	v_mfma_f32_16x16x32_bf16 v[100:103], v[136:139], v[196:199], v[100:103]
	v_mfma_f32_16x16x32_bf16 v[72:75], v[128:131], v[204:207], v[72:75]
	v_mfma_f32_16x16x32_bf16 v[76:79], v[136:139], v[204:207], v[76:79]
	v_mfma_f32_16x16x32_bf16 v[80:83], v[132:135], v[184:187], v[80:83]
	v_mfma_f32_16x16x32_bf16 v[92:95], v[140:143], v[184:187], v[92:95]
	v_mfma_f32_16x16x32_bf16 v[84:87], v[132:135], v[192:195], v[84:87]
	v_mfma_f32_16x16x32_bf16 v[96:99], v[140:143], v[192:195], v[96:99]
	v_mfma_f32_16x16x32_bf16 v[88:91], v[132:135], v[200:203], v[88:91]
	v_mfma_f32_16x16x32_bf16 v[100:103], v[140:143], v[200:203], v[100:103]
	v_mfma_f32_16x16x32_bf16 v[72:75], v[132:135], v[208:211], v[72:75]
	v_mfma_f32_16x16x32_bf16 v[76:79], v[140:143], v[208:211], v[76:79]
	s_setprio 0
	s_setprio 1
	v_mfma_f32_16x16x32_bf16 v[104:107], v[158:161], v[180:183], v[104:107]
	v_mfma_f32_16x16x32_bf16 v[116:119], v[172:175], v[180:183], v[116:119]
	v_mfma_f32_16x16x32_bf16 v[108:111], v[158:161], v[188:191], v[108:111]
	v_mfma_f32_16x16x32_bf16 v[120:123], v[172:175], v[188:191], v[120:123]
	v_mfma_f32_16x16x32_bf16 v[112:115], v[158:161], v[196:199], v[112:115]
	v_mfma_f32_16x16x32_bf16 v[124:127], v[172:175], v[196:199], v[124:127]
	v_mfma_f32_16x16x32_bf16 v[68:71], v[158:161], v[204:207], v[68:71]
	v_mfma_f32_16x16x32_bf16 v[64:67], v[172:175], v[204:207], v[64:67]
	v_mfma_f32_16x16x32_bf16 v[104:107], v[162:165], v[184:187], v[104:107]
	v_mfma_f32_16x16x32_bf16 v[116:119], v[176:179], v[184:187], v[116:119]
	v_mfma_f32_16x16x32_bf16 v[108:111], v[162:165], v[192:195], v[108:111]
	v_mfma_f32_16x16x32_bf16 v[120:123], v[176:179], v[192:195], v[120:123]
	v_mfma_f32_16x16x32_bf16 v[112:115], v[162:165], v[200:203], v[112:115]
	v_mfma_f32_16x16x32_bf16 v[124:127], v[176:179], v[200:203], v[124:127]
	v_mfma_f32_16x16x32_bf16 v[68:71], v[162:165], v[208:211], v[68:71]
	v_mfma_f32_16x16x32_bf16 v[64:67], v[176:179], v[208:211], v[64:67]
	s_barrier
	s_setprio 0
	s_add_i32 s26, s37, s97
	s_mov_b32 m0, s26
	ds_read_b128 v[180:183], v171 offset:49152
	ds_read_b128 v[184:187], v171 offset:50176
	ds_read_b128 v[188:191], v171 offset:51200
	ds_read_b128 v[192:195], v171 offset:52224
	ds_read_b128 v[196:199], v171 offset:53248
	ds_read_b128 v[200:203], v171 offset:54272
	ds_read_b128 v[204:207], v171 offset:55296
	ds_read_b128 v[208:211], v171 offset:56320
	global_load_lds_dwordx4 v148, s[98:99]
	s_add_i32 m0, s26, 0x2000
	s_add_u32 s24, s24, 0x20080
	s_addc_u32 s25, s25, 0
	s_add_i32 s26, s38, s97
	global_load_lds_dwordx4 v144, s[98:99]
	s_mov_b32 m0, s26
	s_nop 0
	global_load_lds_dwordx4 v148, s[24:25]
	s_add_i32 m0, s26, 0x2000
	s_nop 0
	global_load_lds_dwordx4 v144, s[24:25]
	s_mov_b32 m0, s28
	s_nop 0
	global_load_lds_dwordx4 v150, s[100:101]
	s_mov_b32 m0, s29
	s_nop 0
	global_load_lds_dwordx4 v146, s[100:101]
	s_waitcnt vmcnt(8)
	s_waitcnt lgkmcnt(0)
	s_setprio 1
	s_barrier
	v_mfma_f32_16x16x32_bf16 v[48:51], v[128:131], v[180:183], v[48:51]
	v_mfma_f32_16x16x32_bf16 v[52:55], v[136:139], v[180:183], v[52:55]
	v_mfma_f32_16x16x32_bf16 v[32:35], v[128:131], v[188:191], v[32:35]
	v_mfma_f32_16x16x32_bf16 v[36:39], v[136:139], v[188:191], v[36:39]
	v_mfma_f32_16x16x32_bf16 v[16:19], v[128:131], v[196:199], v[16:19]
	v_mfma_f32_16x16x32_bf16 v[20:23], v[136:139], v[196:199], v[20:23]
	v_mfma_f32_16x16x32_bf16 v[0:3], v[128:131], v[204:207], v[0:3]
	v_mfma_f32_16x16x32_bf16 v[4:7], v[136:139], v[204:207], v[4:7]
	v_mfma_f32_16x16x32_bf16 v[48:51], v[132:135], v[184:187], v[48:51]
	v_mfma_f32_16x16x32_bf16 v[52:55], v[140:143], v[184:187], v[52:55]
	v_mfma_f32_16x16x32_bf16 v[32:35], v[132:135], v[192:195], v[32:35]
	v_mfma_f32_16x16x32_bf16 v[36:39], v[140:143], v[192:195], v[36:39]
	v_mfma_f32_16x16x32_bf16 v[16:19], v[132:135], v[200:203], v[16:19]
	v_mfma_f32_16x16x32_bf16 v[20:23], v[140:143], v[200:203], v[20:23]
	v_mfma_f32_16x16x32_bf16 v[0:3], v[132:135], v[208:211], v[0:3]
	v_mfma_f32_16x16x32_bf16 v[4:7], v[140:143], v[208:211], v[4:7]
	s_setprio 0
	s_setprio 1
	v_mfma_f32_16x16x32_bf16 v[56:59], v[158:161], v[180:183], v[56:59]
	v_mfma_f32_16x16x32_bf16 v[60:63], v[172:175], v[180:183], v[60:63]
	v_mfma_f32_16x16x32_bf16 v[40:43], v[158:161], v[188:191], v[40:43]
	v_mfma_f32_16x16x32_bf16 v[44:47], v[172:175], v[188:191], v[44:47]
	v_mfma_f32_16x16x32_bf16 v[24:27], v[158:161], v[196:199], v[24:27]
	v_mfma_f32_16x16x32_bf16 v[28:31], v[172:175], v[196:199], v[28:31]
	v_mfma_f32_16x16x32_bf16 v[8:11], v[158:161], v[204:207], v[8:11]
	v_mfma_f32_16x16x32_bf16 v[12:15], v[172:175], v[204:207], v[12:15]
	v_mfma_f32_16x16x32_bf16 v[56:59], v[162:165], v[184:187], v[56:59]
	v_mfma_f32_16x16x32_bf16 v[60:63], v[176:179], v[184:187], v[60:63]
	v_mfma_f32_16x16x32_bf16 v[40:43], v[162:165], v[192:195], v[40:43]
	v_mfma_f32_16x16x32_bf16 v[44:47], v[176:179], v[192:195], v[44:47]
	v_mfma_f32_16x16x32_bf16 v[24:27], v[162:165], v[200:203], v[24:27]
	v_mfma_f32_16x16x32_bf16 v[28:31], v[176:179], v[200:203], v[28:31]
	v_mfma_f32_16x16x32_bf16 v[8:11], v[162:165], v[208:211], v[8:11]
	v_mfma_f32_16x16x32_bf16 v[12:15], v[176:179], v[208:211], v[12:15]
	s_barrier
	s_setprio 0
	s_add_i32 s36, s36, 2
	s_add_u32 s34, s34, 0x100
	s_addc_u32 s35, s35, 0
	s_add_u32 s22, s22, 0x100
	s_addc_u32 s23, s23, 0
	s_cmp_gt_u32 s36, 5
	s_cbranch_scc1 .Lpeel_done_1
.LBB0_1693:
	ds_read_b128 v[128:131], v169
	ds_read_b128 v[132:135], v169 offset:1024
	ds_read_b128 v[136:139], v169 offset:2048
	ds_read_b128 v[140:143], v169 offset:3072
	ds_read_b128 v[158:161], v170
	ds_read_b128 v[162:165], v170 offset:1024
	ds_read_b128 v[172:175], v170 offset:2048
	ds_read_b128 v[176:179], v170 offset:3072
	s_add_u32 s24, s22, 0xfff80080
	s_addc_u32 s25, s23, -1
	s_cmp_eq_u32 s36, 4
	s_cselect_b32 s27, s5, s25
	s_cselect_b32 s26, s4, s24
	s_cselect_b32 s25, s13, s35
	s_cselect_b32 s24, s15, s34
	s_add_i32 m0, s94, 0xc000
	ds_read_b128 v[180:183], v171
	ds_read_b128 v[184:187], v171 offset:1024
	ds_read_b128 v[188:191], v171 offset:2048
	ds_read_b128 v[192:195], v171 offset:3072
	ds_read_b128 v[196:199], v171 offset:4096
	ds_read_b128 v[200:203], v171 offset:5120
	ds_read_b128 v[204:207], v171 offset:6144
	ds_read_b128 v[208:211], v171 offset:7168
	global_load_lds_dwordx4 v152, s[22:23]
	s_add_i32 m0, s94, 0xe000
	s_nop 0
	global_load_lds_dwordx4 v154, s[22:23]
	s_waitcnt vmcnt(8)
	s_waitcnt lgkmcnt(0)
	s_setprio 1
	s_barrier
	v_mfma_f32_16x16x32_bf16 v[80:83], v[128:131], v[180:183], v[80:83]
	v_mfma_f32_16x16x32_bf16 v[92:95], v[136:139], v[180:183], v[92:95]
	v_mfma_f32_16x16x32_bf16 v[84:87], v[128:131], v[188:191], v[84:87]
	v_mfma_f32_16x16x32_bf16 v[96:99], v[136:139], v[188:191], v[96:99]
	v_mfma_f32_16x16x32_bf16 v[88:91], v[128:131], v[196:199], v[88:91]
	v_mfma_f32_16x16x32_bf16 v[100:103], v[136:139], v[196:199], v[100:103]
	v_mfma_f32_16x16x32_bf16 v[72:75], v[128:131], v[204:207], v[72:75]
	v_mfma_f32_16x16x32_bf16 v[76:79], v[136:139], v[204:207], v[76:79]
	v_mfma_f32_16x16x32_bf16 v[80:83], v[132:135], v[184:187], v[80:83]
	v_mfma_f32_16x16x32_bf16 v[92:95], v[140:143], v[184:187], v[92:95]
	v_mfma_f32_16x16x32_bf16 v[84:87], v[132:135], v[192:195], v[84:87]
	v_mfma_f32_16x16x32_bf16 v[96:99], v[140:143], v[192:195], v[96:99]
	v_mfma_f32_16x16x32_bf16 v[88:91], v[132:135], v[200:203], v[88:91]
	v_mfma_f32_16x16x32_bf16 v[100:103], v[140:143], v[200:203], v[100:103]
	v_mfma_f32_16x16x32_bf16 v[72:75], v[132:135], v[208:211], v[72:75]
	v_mfma_f32_16x16x32_bf16 v[76:79], v[140:143], v[208:211], v[76:79]
	s_setprio 0
	s_setprio 1
	v_mfma_f32_16x16x32_bf16 v[104:107], v[158:161], v[180:183], v[104:107]
	v_mfma_f32_16x16x32_bf16 v[116:119], v[172:175], v[180:183], v[116:119]
	v_mfma_f32_16x16x32_bf16 v[108:111], v[158:161], v[188:191], v[108:111]
	v_mfma_f32_16x16x32_bf16 v[120:123], v[172:175], v[188:191], v[120:123]
	v_mfma_f32_16x16x32_bf16 v[112:115], v[158:161], v[196:199], v[112:115]
	v_mfma_f32_16x16x32_bf16 v[124:127], v[172:175], v[196:199], v[124:127]
	v_mfma_f32_16x16x32_bf16 v[68:71], v[158:161], v[204:207], v[68:71]
	v_mfma_f32_16x16x32_bf16 v[64:67], v[172:175], v[204:207], v[64:67]
	v_mfma_f32_16x16x32_bf16 v[104:107], v[162:165], v[184:187], v[104:107]
	v_mfma_f32_16x16x32_bf16 v[116:119], v[176:179], v[184:187], v[116:119]
	v_mfma_f32_16x16x32_bf16 v[108:111], v[162:165], v[192:195], v[108:111]
	v_mfma_f32_16x16x32_bf16 v[120:123], v[176:179], v[192:195], v[120:123]
	v_mfma_f32_16x16x32_bf16 v[112:115], v[162:165], v[200:203], v[112:115]
	v_mfma_f32_16x16x32_bf16 v[124:127], v[176:179], v[200:203], v[124:127]
	v_mfma_f32_16x16x32_bf16 v[68:71], v[162:165], v[208:211], v[68:71]
	v_mfma_f32_16x16x32_bf16 v[64:67], v[176:179], v[208:211], v[64:67]
	s_barrier
	s_setprio 0
	s_add_i32 s37, s31, s97
	s_add_u32 s98, s24, 0x80
	s_addc_u32 s99, s25, 0
	s_mov_b32 m0, s37
	ds_read_b128 v[180:183], v171 offset:16384
	ds_read_b128 v[184:187], v171 offset:17408
	ds_read_b128 v[188:191], v171 offset:18432
	ds_read_b128 v[192:195], v171 offset:19456
	ds_read_b128 v[196:199], v171 offset:20480
	ds_read_b128 v[200:203], v171 offset:21504
	ds_read_b128 v[204:207], v171 offset:22528
	ds_read_b128 v[208:211], v171 offset:23552
	global_load_lds_dwordx4 v148, s[24:25]
	s_add_i32 m0, s37, 0x2000
	s_add_u32 s38, s24, 0x20000
	s_addc_u32 s39, s25, 0
	s_add_i32 s37, s33, s97
	global_load_lds_dwordx4 v144, s[24:25]
	s_mov_b32 m0, s37
	s_add_u32 s100, s26, 0x80
	s_addc_u32 s101, s27, 0
	global_load_lds_dwordx4 v148, s[38:39]
	s_add_i32 m0, s37, 0x2000
	s_nop 0
	global_load_lds_dwordx4 v144, s[38:39]
	s_mov_b32 m0, s94
	s_nop 0
	global_load_lds_dwordx4 v150, s[26:27]
	s_mov_b32 m0, s3
	s_nop 0
	global_load_lds_dwordx4 v146, s[26:27]
	s_waitcnt vmcnt(8)
	s_waitcnt lgkmcnt(0)
	s_setprio 1
	s_barrier
	v_mfma_f32_16x16x32_bf16 v[48:51], v[128:131], v[180:183], v[48:51]
	v_mfma_f32_16x16x32_bf16 v[52:55], v[136:139], v[180:183], v[52:55]
	v_mfma_f32_16x16x32_bf16 v[32:35], v[128:131], v[188:191], v[32:35]
	v_mfma_f32_16x16x32_bf16 v[36:39], v[136:139], v[188:191], v[36:39]
	v_mfma_f32_16x16x32_bf16 v[16:19], v[128:131], v[196:199], v[16:19]
	v_mfma_f32_16x16x32_bf16 v[20:23], v[136:139], v[196:199], v[20:23]
	v_mfma_f32_16x16x32_bf16 v[0:3], v[128:131], v[204:207], v[0:3]
	v_mfma_f32_16x16x32_bf16 v[4:7], v[136:139], v[204:207], v[4:7]
	v_mfma_f32_16x16x32_bf16 v[48:51], v[132:135], v[184:187], v[48:51]
	v_mfma_f32_16x16x32_bf16 v[52:55], v[140:143], v[184:187], v[52:55]
	v_mfma_f32_16x16x32_bf16 v[32:35], v[132:135], v[192:195], v[32:35]
	v_mfma_f32_16x16x32_bf16 v[36:39], v[140:143], v[192:195], v[36:39]
	v_mfma_f32_16x16x32_bf16 v[16:19], v[132:135], v[200:203], v[16:19]
	v_mfma_f32_16x16x32_bf16 v[20:23], v[140:143], v[200:203], v[20:23]
	v_mfma_f32_16x16x32_bf16 v[0:3], v[132:135], v[208:211], v[0:3]
	v_mfma_f32_16x16x32_bf16 v[4:7], v[140:143], v[208:211], v[4:7]
	s_setprio 0
	s_setprio 1
	v_mfma_f32_16x16x32_bf16 v[56:59], v[158:161], v[180:183], v[56:59]
	v_mfma_f32_16x16x32_bf16 v[60:63], v[172:175], v[180:183], v[60:63]
	v_mfma_f32_16x16x32_bf16 v[40:43], v[158:161], v[188:191], v[40:43]
	v_mfma_f32_16x16x32_bf16 v[44:47], v[172:175], v[188:191], v[44:47]
	v_mfma_f32_16x16x32_bf16 v[24:27], v[158:161], v[196:199], v[24:27]
	v_mfma_f32_16x16x32_bf16 v[28:31], v[172:175], v[196:199], v[28:31]
	v_mfma_f32_16x16x32_bf16 v[8:11], v[158:161], v[204:207], v[8:11]
	v_mfma_f32_16x16x32_bf16 v[12:15], v[172:175], v[204:207], v[12:15]
	v_mfma_f32_16x16x32_bf16 v[56:59], v[162:165], v[184:187], v[56:59]
	v_mfma_f32_16x16x32_bf16 v[60:63], v[176:179], v[184:187], v[60:63]
	v_mfma_f32_16x16x32_bf16 v[40:43], v[162:165], v[192:195], v[40:43]
	v_mfma_f32_16x16x32_bf16 v[44:47], v[176:179], v[192:195], v[44:47]
	v_mfma_f32_16x16x32_bf16 v[24:27], v[162:165], v[200:203], v[24:27]
	v_mfma_f32_16x16x32_bf16 v[28:31], v[176:179], v[200:203], v[28:31]
	v_mfma_f32_16x16x32_bf16 v[8:11], v[162:165], v[208:211], v[8:11]
	v_mfma_f32_16x16x32_bf16 v[12:15], v[176:179], v[208:211], v[12:15]
	s_barrier
	s_setprio 0
	s_add_i32 s37, 0, 0x18000
	s_add_i32 s38, 0, 0x1c000
	v_add_u32_e32 v140, s37, v167
	v_add_u32_e32 v176, s38, v167
	ds_read_b128 v[128:131], v140
	ds_read_b128 v[132:135], v140 offset:1024
	ds_read_b128 v[136:139], v140 offset:2048
	ds_read_b128 v[140:143], v140 offset:3072
	ds_read_b128 v[158:161], v176
	ds_read_b128 v[162:165], v176 offset:1024
	ds_read_b128 v[172:175], v176 offset:2048
	ds_read_b128 v[176:179], v176 offset:3072
	s_add_u32 s26, s26, 0x80000
	s_addc_u32 s27, s27, 0
	s_mov_b32 m0, s7
	ds_read_b128 v[180:183], v171 offset:32768
	ds_read_b128 v[184:187], v171 offset:33792
	ds_read_b128 v[188:191], v171 offset:34816
	ds_read_b128 v[192:195], v171 offset:35840
	ds_read_b128 v[196:199], v171 offset:36864
	ds_read_b128 v[200:203], v171 offset:37888
	ds_read_b128 v[204:207], v171 offset:38912
	ds_read_b128 v[208:211], v171 offset:39936
	global_load_lds_dwordx4 v150, s[26:27]
	s_mov_b32 m0, s19
	s_nop 0
	global_load_lds_dwordx4 v146, s[26:27]
	s_waitcnt vmcnt(8)
	s_waitcnt lgkmcnt(0)
	s_setprio 1
	s_barrier
	v_mfma_f32_16x16x32_bf16 v[80:83], v[128:131], v[180:183], v[80:83]
	v_mfma_f32_16x16x32_bf16 v[92:95], v[136:139], v[180:183], v[92:95]
	v_mfma_f32_16x16x32_bf16 v[84:87], v[128:131], v[188:191], v[84:87]
	v_mfma_f32_16x16x32_bf16 v[96:99], v[136:139], v[188:191], v[96:99]
	v_mfma_f32_16x16x32_bf16 v[88:91], v[128:131], v[196:199], v[88:91]
	v_mfma_f32_16x16x32_bf16 v[100:103], v[136:139], v[196:199], v[100:103]
	v_mfma_f32_16x16x32_bf16 v[72:75], v[128:131], v[204:207], v[72:75]
	v_mfma_f32_16x16x32_bf16 v[76:79], v[136:139], v[204:207], v[76:79]
	v_mfma_f32_16x16x32_bf16 v[80:83], v[132:135], v[184:187], v[80:83]
	v_mfma_f32_16x16x32_bf16 v[92:95], v[140:143], v[184:187], v[92:95]
	v_mfma_f32_16x16x32_bf16 v[84:87], v[132:135], v[192:195], v[84:87]
	v_mfma_f32_16x16x32_bf16 v[96:99], v[140:143], v[192:195], v[96:99]
	v_mfma_f32_16x16x32_bf16 v[88:91], v[132:135], v[200:203], v[88:91]
	v_mfma_f32_16x16x32_bf16 v[100:103], v[140:143], v[200:203], v[100:103]
	v_mfma_f32_16x16x32_bf16 v[72:75], v[132:135], v[208:211], v[72:75]
	v_mfma_f32_16x16x32_bf16 v[76:79], v[140:143], v[208:211], v[76:79]
	s_setprio 0
	s_setprio 1
	v_mfma_f32_16x16x32_bf16 v[104:107], v[158:161], v[180:183], v[104:107]
	v_mfma_f32_16x16x32_bf16 v[116:119], v[172:175], v[180:183], v[116:119]
	v_mfma_f32_16x16x32_bf16 v[108:111], v[158:161], v[188:191], v[108:111]
	v_mfma_f32_16x16x32_bf16 v[120:123], v[172:175], v[188:191], v[120:123]
	v_mfma_f32_16x16x32_bf16 v[112:115], v[158:161], v[196:199], v[112:115]
	v_mfma_f32_16x16x32_bf16 v[124:127], v[172:175], v[196:199], v[124:127]
	v_mfma_f32_16x16x32_bf16 v[68:71], v[158:161], v[204:207], v[68:71]
	v_mfma_f32_16x16x32_bf16 v[64:67], v[172:175], v[204:207], v[64:67]
	v_mfma_f32_16x16x32_bf16 v[104:107], v[162:165], v[184:187], v[104:107]
	v_mfma_f32_16x16x32_bf16 v[116:119], v[176:179], v[184:187], v[116:119]
	v_mfma_f32_16x16x32_bf16 v[108:111], v[162:165], v[192:195], v[108:111]
	v_mfma_f32_16x16x32_bf16 v[120:123], v[176:179], v[192:195], v[120:123]
	v_mfma_f32_16x16x32_bf16 v[112:115], v[162:165], v[200:203], v[112:115]
	v_mfma_f32_16x16x32_bf16 v[124:127], v[176:179], v[200:203], v[124:127]
	v_mfma_f32_16x16x32_bf16 v[68:71], v[162:165], v[208:211], v[68:71]
	v_mfma_f32_16x16x32_bf16 v[64:67], v[176:179], v[208:211], v[64:67]
	s_barrier
	s_setprio 0
	s_add_i32 s26, s37, s97
	s_mov_b32 m0, s26
	ds_read_b128 v[180:183], v171 offset:49152
	ds_read_b128 v[184:187], v171 offset:50176
	ds_read_b128 v[188:191], v171 offset:51200
	ds_read_b128 v[192:195], v171 offset:52224
	ds_read_b128 v[196:199], v171 offset:53248
	ds_read_b128 v[200:203], v171 offset:54272
	ds_read_b128 v[204:207], v171 offset:55296
	ds_read_b128 v[208:211], v171 offset:56320
	global_load_lds_dwordx4 v148, s[98:99]
	s_add_i32 m0, s26, 0x2000
	s_add_u32 s24, s24, 0x20080
	s_addc_u32 s25, s25, 0
	s_add_i32 s26, s38, s97
	global_load_lds_dwordx4 v144, s[98:99]
	s_mov_b32 m0, s26
	s_nop 0
	global_load_lds_dwordx4 v148, s[24:25]
	s_add_i32 m0, s26, 0x2000
	s_nop 0
	global_load_lds_dwordx4 v144, s[24:25]
	s_mov_b32 m0, s28
	s_nop 0
	global_load_lds_dwordx4 v150, s[100:101]
	s_mov_b32 m0, s29
	s_nop 0
	global_load_lds_dwordx4 v146, s[100:101]
	s_waitcnt vmcnt(8)
	s_waitcnt lgkmcnt(0)
	s_setprio 1
	s_barrier
	v_mfma_f32_16x16x32_bf16 v[48:51], v[128:131], v[180:183], v[48:51]
	v_mfma_f32_16x16x32_bf16 v[52:55], v[136:139], v[180:183], v[52:55]
	v_mfma_f32_16x16x32_bf16 v[32:35], v[128:131], v[188:191], v[32:35]
	v_mfma_f32_16x16x32_bf16 v[36:39], v[136:139], v[188:191], v[36:39]
	v_mfma_f32_16x16x32_bf16 v[16:19], v[128:131], v[196:199], v[16:19]
	v_mfma_f32_16x16x32_bf16 v[20:23], v[136:139], v[196:199], v[20:23]
	v_mfma_f32_16x16x32_bf16 v[0:3], v[128:131], v[204:207], v[0:3]
	v_mfma_f32_16x16x32_bf16 v[4:7], v[136:139], v[204:207], v[4:7]
	v_mfma_f32_16x16x32_bf16 v[48:51], v[132:135], v[184:187], v[48:51]
	v_mfma_f32_16x16x32_bf16 v[52:55], v[140:143], v[184:187], v[52:55]
	v_mfma_f32_16x16x32_bf16 v[32:35], v[132:135], v[192:195], v[32:35]
	v_mfma_f32_16x16x32_bf16 v[36:39], v[140:143], v[192:195], v[36:39]
	v_mfma_f32_16x16x32_bf16 v[16:19], v[132:135], v[200:203], v[16:19]
	v_mfma_f32_16x16x32_bf16 v[20:23], v[140:143], v[200:203], v[20:23]
	v_mfma_f32_16x16x32_bf16 v[0:3], v[132:135], v[208:211], v[0:3]
	v_mfma_f32_16x16x32_bf16 v[4:7], v[140:143], v[208:211], v[4:7]
	s_setprio 0
	s_setprio 1
	v_mfma_f32_16x16x32_bf16 v[56:59], v[158:161], v[180:183], v[56:59]
	v_mfma_f32_16x16x32_bf16 v[60:63], v[172:175], v[180:183], v[60:63]
	v_mfma_f32_16x16x32_bf16 v[40:43], v[158:161], v[188:191], v[40:43]
	v_mfma_f32_16x16x32_bf16 v[44:47], v[172:175], v[188:191], v[44:47]
	v_mfma_f32_16x16x32_bf16 v[24:27], v[158:161], v[196:199], v[24:27]
	v_mfma_f32_16x16x32_bf16 v[28:31], v[172:175], v[196:199], v[28:31]
	v_mfma_f32_16x16x32_bf16 v[8:11], v[158:161], v[204:207], v[8:11]
	v_mfma_f32_16x16x32_bf16 v[12:15], v[172:175], v[204:207], v[12:15]
	v_mfma_f32_16x16x32_bf16 v[56:59], v[162:165], v[184:187], v[56:59]
	v_mfma_f32_16x16x32_bf16 v[60:63], v[176:179], v[184:187], v[60:63]
	v_mfma_f32_16x16x32_bf16 v[40:43], v[162:165], v[192:195], v[40:43]
	v_mfma_f32_16x16x32_bf16 v[44:47], v[176:179], v[192:195], v[44:47]
	v_mfma_f32_16x16x32_bf16 v[24:27], v[162:165], v[200:203], v[24:27]
	v_mfma_f32_16x16x32_bf16 v[28:31], v[176:179], v[200:203], v[28:31]
	v_mfma_f32_16x16x32_bf16 v[8:11], v[162:165], v[208:211], v[8:11]
	v_mfma_f32_16x16x32_bf16 v[12:15], v[176:179], v[208:211], v[12:15]
	s_barrier
	s_setprio 0
	s_add_i32 s36, s36, 2
	s_add_u32 s34, s34, 0x100
	s_addc_u32 s35, s35, 0
	s_add_u32 s22, s22, 0x100
	s_addc_u32 s23, s23, 0
	s_cmp_gt_u32 s36, 5
	s_cbranch_scc0 .LBB0_1693

.LBB0_2019:
	s_cmp_lt_u32 s5, 0x3fffffff
	s_cselect_b64 s[40:41], -1, 0
	s_ashr_i32 s23, s22, 31
	s_and_b64 s[40:41], s[36:37], s[40:41]
	s_lshl_b64 s[36:37], s[22:23], 21
	s_add_u32 s5, s86, s36
	s_addc_u32 s21, s87, s37
	s_add_u32 s36, s5, s38
	s_addc_u32 s37, s21, s39
	s_and_b64 s[48:49], s[40:41], exec
	s_cselect_b32 s5, s37, s47
	s_cselect_b32 s23, s36, s46
	s_ashr_i32 s21, s20, 31
	s_lshl_b64 s[48:49], s[20:21], 21
	v_readlane_b32 s68, v254, 13
	v_readlane_b32 s69, v254, 14
	s_add_u32 s21, s68, s48
	s_addc_u32 s43, s69, s49
	s_add_u32 s38, s21, s38
	s_addc_u32 s39, s43, s39
	s_and_b64 s[48:49], s[40:41], exec
	s_cselect_b32 s21, s39, s45
	s_cselect_b32 s43, s38, s44
	s_add_i32 s68, s67, -2
	s_add_u32 s69, s44, 0x100
	s_addc_u32 s70, s45, 0
	s_add_u32 s44, s46, 0x100080
	s_addc_u32 s45, s47, 0
	s_mov_b32 s46, 0
	s_waitcnt vmcnt(0)
	ds_read_b128 v[128:131], v244
	ds_read_b128 v[132:135], v244 offset:1024
	ds_read_b128 v[136:139], v244 offset:2048
	ds_read_b128 v[140:143], v244 offset:3072
	ds_read_b128 v[144:147], v245
	ds_read_b128 v[148:151], v245 offset:1024
	ds_read_b128 v[152:155], v245 offset:2048
	ds_read_b128 v[156:159], v245 offset:3072
	s_add_i32 s71, s46, 2
	s_add_u32 s47, s44, 0xfff00080
	s_addc_u32 s48, s45, -1
	s_cmp_eq_u32 s68, s46
	s_cselect_b32 s46, s43, s69
	s_cselect_b32 s49, s5, s48
	s_cselect_b32 s48, s23, s47
	s_cselect_b32 s47, s21, s70
	s_add_i32 m0, s94, 0xc000
	ds_read_b128 v[160:163], v246
	ds_read_b128 v[164:167], v246 offset:1024
	ds_read_b128 v[168:171], v246 offset:2048
	ds_read_b128 v[172:175], v246 offset:3072
	ds_read_b128 v[176:179], v246 offset:4096
	ds_read_b128 v[180:183], v246 offset:5120
	ds_read_b128 v[184:187], v246 offset:6144
	ds_read_b128 v[188:191], v246 offset:7168
	global_load_lds_dwordx4 v218, s[44:45]
	s_add_i32 m0, s94, 0xe000
	s_nop 0
	global_load_lds_dwordx4 v220, s[44:45]
	s_waitcnt vmcnt(8)
	s_waitcnt lgkmcnt(0)
	s_setprio 1
	s_barrier
	v_mfma_f32_16x16x32_bf16 v[112:115], v[128:131], v[160:163], 0
	v_mfma_f32_16x16x32_bf16 v[116:119], v[136:139], v[160:163], 0
	v_mfma_f32_16x16x32_bf16 v[100:103], v[128:131], v[168:171], 0
	v_mfma_f32_16x16x32_bf16 v[96:99], v[136:139], v[168:171], 0
	v_mfma_f32_16x16x32_bf16 v[84:87], v[128:131], v[176:179], 0
	v_mfma_f32_16x16x32_bf16 v[80:83], v[136:139], v[176:179], 0
	v_mfma_f32_16x16x32_bf16 v[52:55], v[128:131], v[184:187], 0
	v_mfma_f32_16x16x32_bf16 v[48:51], v[136:139], v[184:187], 0
	v_mfma_f32_16x16x32_bf16 v[112:115], v[132:135], v[164:167], v[112:115]
	v_mfma_f32_16x16x32_bf16 v[116:119], v[140:143], v[164:167], v[116:119]
	v_mfma_f32_16x16x32_bf16 v[100:103], v[132:135], v[172:175], v[100:103]
	v_mfma_f32_16x16x32_bf16 v[96:99], v[140:143], v[172:175], v[96:99]
	v_mfma_f32_16x16x32_bf16 v[84:87], v[132:135], v[180:183], v[84:87]
	v_mfma_f32_16x16x32_bf16 v[80:83], v[140:143], v[180:183], v[80:83]
	v_mfma_f32_16x16x32_bf16 v[52:55], v[132:135], v[188:191], v[52:55]
	v_mfma_f32_16x16x32_bf16 v[48:51], v[140:143], v[188:191], v[48:51]
	s_setprio 0
	s_setprio 1
	v_mfma_f32_16x16x32_bf16 v[124:127], v[144:147], v[160:163], 0
	v_mfma_f32_16x16x32_bf16 v[120:123], v[152:155], v[160:163], 0
	v_mfma_f32_16x16x32_bf16 v[108:111], v[144:147], v[168:171], 0
	v_mfma_f32_16x16x32_bf16 v[104:107], v[152:155], v[168:171], 0
	v_mfma_f32_16x16x32_bf16 v[92:95], v[144:147], v[176:179], 0
	v_mfma_f32_16x16x32_bf16 v[88:91], v[152:155], v[176:179], 0
	v_mfma_f32_16x16x32_bf16 v[68:71], v[144:147], v[184:187], 0
	v_mfma_f32_16x16x32_bf16 v[64:67], v[152:155], v[184:187], 0
	v_mfma_f32_16x16x32_bf16 v[124:127], v[148:151], v[164:167], v[124:127]
	v_mfma_f32_16x16x32_bf16 v[120:123], v[156:159], v[164:167], v[120:123]
	v_mfma_f32_16x16x32_bf16 v[108:111], v[148:151], v[172:175], v[108:111]
	v_mfma_f32_16x16x32_bf16 v[104:107], v[156:159], v[172:175], v[104:107]
	v_mfma_f32_16x16x32_bf16 v[92:95], v[148:151], v[180:183], v[92:95]
	v_mfma_f32_16x16x32_bf16 v[88:91], v[156:159], v[180:183], v[88:91]
	v_mfma_f32_16x16x32_bf16 v[68:71], v[148:151], v[188:191], v[68:71]
	v_mfma_f32_16x16x32_bf16 v[64:67], v[156:159], v[188:191], v[64:67]
	s_barrier
	s_setprio 0
	s_add_i32 s76, s60, s97
	s_add_u32 s98, s46, 0x80
	s_addc_u32 s99, s47, 0
	s_mov_b32 m0, s76
	ds_read_b128 v[160:163], v246 offset:16384
	ds_read_b128 v[164:167], v246 offset:17408
	ds_read_b128 v[168:171], v246 offset:18432
	ds_read_b128 v[172:175], v246 offset:19456
	ds_read_b128 v[176:179], v246 offset:20480
	ds_read_b128 v[180:183], v246 offset:21504
	ds_read_b128 v[184:187], v246 offset:22528
	ds_read_b128 v[188:191], v246 offset:23552
	global_load_lds_dwordx4 v210, s[46:47]
	s_add_i32 m0, s76, 0x2000
	s_add_u32 s76, s46, 0x100000
	s_addc_u32 s77, s47, 0
	s_add_i32 s78, s61, s97
	global_load_lds_dwordx4 v214, s[46:47]
	s_mov_b32 m0, s78
	s_add_u32 s100, s48, 0x80
	s_addc_u32 s101, s49, 0
	global_load_lds_dwordx4 v210, s[76:77]
	s_add_i32 m0, s78, 0x2000
	s_nop 0
	global_load_lds_dwordx4 v214, s[76:77]
	s_mov_b32 m0, s94
	s_nop 0
	global_load_lds_dwordx4 v208, s[48:49]
	s_mov_b32 m0, s2
	s_nop 0
	global_load_lds_dwordx4 v212, s[48:49]
	s_waitcnt vmcnt(8)
	s_waitcnt lgkmcnt(0)
	s_setprio 1
	s_barrier
	v_mfma_f32_16x16x32_bf16 v[60:63], v[128:131], v[160:163], 0
	v_mfma_f32_16x16x32_bf16 v[56:59], v[136:139], v[160:163], 0
	v_mfma_f32_16x16x32_bf16 v[36:39], v[128:131], v[168:171], 0
	v_mfma_f32_16x16x32_bf16 v[32:35], v[136:139], v[168:171], 0
	v_mfma_f32_16x16x32_bf16 v[20:23], v[128:131], v[176:179], 0
	v_mfma_f32_16x16x32_bf16 v[16:19], v[136:139], v[176:179], 0
	v_mfma_f32_16x16x32_bf16 v[4:7], v[128:131], v[184:187], 0
	v_mfma_f32_16x16x32_bf16 v[0:3], v[136:139], v[184:187], 0
	v_mfma_f32_16x16x32_bf16 v[60:63], v[132:135], v[164:167], v[60:63]
	v_mfma_f32_16x16x32_bf16 v[56:59], v[140:143], v[164:167], v[56:59]
	v_mfma_f32_16x16x32_bf16 v[36:39], v[132:135], v[172:175], v[36:39]
	v_mfma_f32_16x16x32_bf16 v[32:35], v[140:143], v[172:175], v[32:35]
	v_mfma_f32_16x16x32_bf16 v[20:23], v[132:135], v[180:183], v[20:23]
	v_mfma_f32_16x16x32_bf16 v[16:19], v[140:143], v[180:183], v[16:19]
	v_mfma_f32_16x16x32_bf16 v[4:7], v[132:135], v[188:191], v[4:7]
	v_mfma_f32_16x16x32_bf16 v[0:3], v[140:143], v[188:191], v[0:3]
	s_setprio 0
	s_setprio 1
	v_mfma_f32_16x16x32_bf16 v[76:79], v[144:147], v[160:163], 0
	v_mfma_f32_16x16x32_bf16 v[72:75], v[152:155], v[160:163], 0
	v_mfma_f32_16x16x32_bf16 v[44:47], v[144:147], v[168:171], 0
	v_mfma_f32_16x16x32_bf16 v[40:43], v[152:155], v[168:171], 0
	v_mfma_f32_16x16x32_bf16 v[28:31], v[144:147], v[176:179], 0
	v_mfma_f32_16x16x32_bf16 v[24:27], v[152:155], v[176:179], 0
	v_mfma_f32_16x16x32_bf16 v[12:15], v[144:147], v[184:187], 0
	v_mfma_f32_16x16x32_bf16 v[8:11], v[152:155], v[184:187], 0
	v_mfma_f32_16x16x32_bf16 v[76:79], v[148:151], v[164:167], v[76:79]
	v_mfma_f32_16x16x32_bf16 v[72:75], v[156:159], v[164:167], v[72:75]
	v_mfma_f32_16x16x32_bf16 v[44:47], v[148:151], v[172:175], v[44:47]
	v_mfma_f32_16x16x32_bf16 v[40:43], v[156:159], v[172:175], v[40:43]
	v_mfma_f32_16x16x32_bf16 v[28:31], v[148:151], v[180:183], v[28:31]
	v_mfma_f32_16x16x32_bf16 v[24:27], v[156:159], v[180:183], v[24:27]
	v_mfma_f32_16x16x32_bf16 v[12:15], v[148:151], v[188:191], v[12:15]
	v_mfma_f32_16x16x32_bf16 v[8:11], v[156:159], v[188:191], v[8:11]
	s_barrier
	s_setprio 0
	s_add_i32 s76, 0, 0x18000
	s_add_i32 s77, 0, 0x1c000
	v_add_u32_e32 v140, s76, v243
	v_add_u32_e32 v156, s77, v243
	ds_read_b128 v[128:131], v140
	ds_read_b128 v[132:135], v140 offset:1024
	ds_read_b128 v[136:139], v140 offset:2048
	ds_read_b128 v[140:143], v140 offset:3072
	ds_read_b128 v[144:147], v156
	ds_read_b128 v[148:151], v156 offset:1024
	ds_read_b128 v[152:155], v156 offset:2048
	ds_read_b128 v[156:159], v156 offset:3072
	s_add_u32 s48, s48, 0x100000
	s_addc_u32 s49, s49, 0
	s_mov_b32 m0, s3
	ds_read_b128 v[160:163], v246 offset:32768
	ds_read_b128 v[164:167], v246 offset:33792
	ds_read_b128 v[168:171], v246 offset:34816
	ds_read_b128 v[172:175], v246 offset:35840
	ds_read_b128 v[176:179], v246 offset:36864
	ds_read_b128 v[180:183], v246 offset:37888
	ds_read_b128 v[184:187], v246 offset:38912
	ds_read_b128 v[188:191], v246 offset:39936
	global_load_lds_dwordx4 v208, s[48:49]
	s_mov_b32 m0, s33
	s_nop 0
	global_load_lds_dwordx4 v212, s[48:49]
	s_waitcnt vmcnt(8)
	s_waitcnt lgkmcnt(0)
	s_setprio 1
	s_barrier
	v_mfma_f32_16x16x32_bf16 v[112:115], v[128:131], v[160:163], v[112:115]
	v_mfma_f32_16x16x32_bf16 v[116:119], v[136:139], v[160:163], v[116:119]
	v_mfma_f32_16x16x32_bf16 v[100:103], v[128:131], v[168:171], v[100:103]
	v_mfma_f32_16x16x32_bf16 v[96:99], v[136:139], v[168:171], v[96:99]
	v_mfma_f32_16x16x32_bf16 v[84:87], v[128:131], v[176:179], v[84:87]
	v_mfma_f32_16x16x32_bf16 v[80:83], v[136:139], v[176:179], v[80:83]
	v_mfma_f32_16x16x32_bf16 v[52:55], v[128:131], v[184:187], v[52:55]
	v_mfma_f32_16x16x32_bf16 v[48:51], v[136:139], v[184:187], v[48:51]
	v_mfma_f32_16x16x32_bf16 v[112:115], v[132:135], v[164:167], v[112:115]
	v_mfma_f32_16x16x32_bf16 v[116:119], v[140:143], v[164:167], v[116:119]
	v_mfma_f32_16x16x32_bf16 v[100:103], v[132:135], v[172:175], v[100:103]
	v_mfma_f32_16x16x32_bf16 v[96:99], v[140:143], v[172:175], v[96:99]
	v_mfma_f32_16x16x32_bf16 v[84:87], v[132:135], v[180:183], v[84:87]
	v_mfma_f32_16x16x32_bf16 v[80:83], v[140:143], v[180:183], v[80:83]
	v_mfma_f32_16x16x32_bf16 v[52:55], v[132:135], v[188:191], v[52:55]
	v_mfma_f32_16x16x32_bf16 v[48:51], v[140:143], v[188:191], v[48:51]
	s_setprio 0
	s_setprio 1
	v_mfma_f32_16x16x32_bf16 v[124:127], v[144:147], v[160:163], v[124:127]
	v_mfma_f32_16x16x32_bf16 v[120:123], v[152:155], v[160:163], v[120:123]
	v_mfma_f32_16x16x32_bf16 v[108:111], v[144:147], v[168:171], v[108:111]
	v_mfma_f32_16x16x32_bf16 v[104:107], v[152:155], v[168:171], v[104:107]
	v_mfma_f32_16x16x32_bf16 v[92:95], v[144:147], v[176:179], v[92:95]
	v_mfma_f32_16x16x32_bf16 v[88:91], v[152:155], v[176:179], v[88:91]
	v_mfma_f32_16x16x32_bf16 v[68:71], v[144:147], v[184:187], v[68:71]
	v_mfma_f32_16x16x32_bf16 v[64:67], v[152:155], v[184:187], v[64:67]
	v_mfma_f32_16x16x32_bf16 v[124:127], v[148:151], v[164:167], v[124:127]
	v_mfma_f32_16x16x32_bf16 v[120:123], v[156:159], v[164:167], v[120:123]
	v_mfma_f32_16x16x32_bf16 v[108:111], v[148:151], v[172:175], v[108:111]
	v_mfma_f32_16x16x32_bf16 v[104:107], v[156:159], v[172:175], v[104:107]
	v_mfma_f32_16x16x32_bf16 v[92:95], v[148:151], v[180:183], v[92:95]
	v_mfma_f32_16x16x32_bf16 v[88:91], v[156:159], v[180:183], v[88:91]
	v_mfma_f32_16x16x32_bf16 v[68:71], v[148:151], v[188:191], v[68:71]
	v_mfma_f32_16x16x32_bf16 v[64:67], v[156:159], v[188:191], v[64:67]
	s_barrier
	s_setprio 0
	s_add_i32 s48, s76, s97
	s_mov_b32 m0, s48
	ds_read_b128 v[160:163], v246 offset:49152
	ds_read_b128 v[164:167], v246 offset:50176
	ds_read_b128 v[168:171], v246 offset:51200
	ds_read_b128 v[172:175], v246 offset:52224
	ds_read_b128 v[176:179], v246 offset:53248
	ds_read_b128 v[180:183], v246 offset:54272
	ds_read_b128 v[184:187], v246 offset:55296
	ds_read_b128 v[188:191], v246 offset:56320
	global_load_lds_dwordx4 v210, s[98:99]
	s_add_i32 m0, s48, 0x2000
	s_add_u32 s46, s46, 0x100080
	s_addc_u32 s47, s47, 0
	s_add_i32 s48, s77, s97
	global_load_lds_dwordx4 v214, s[98:99]
	s_mov_b32 m0, s48
	s_nop 0
	global_load_lds_dwordx4 v210, s[46:47]
	s_add_i32 m0, s48, 0x2000
	s_nop 0
	global_load_lds_dwordx4 v214, s[46:47]
	s_mov_b32 m0, s54
	s_nop 0
	global_load_lds_dwordx4 v208, s[100:101]
	s_mov_b32 m0, s55
	s_nop 0
	global_load_lds_dwordx4 v212, s[100:101]
	s_waitcnt vmcnt(8)
	s_waitcnt lgkmcnt(0)
	s_setprio 1
	s_barrier
	v_mfma_f32_16x16x32_bf16 v[60:63], v[128:131], v[160:163], v[60:63]
	v_mfma_f32_16x16x32_bf16 v[56:59], v[136:139], v[160:163], v[56:59]
	v_mfma_f32_16x16x32_bf16 v[36:39], v[128:131], v[168:171], v[36:39]
	v_mfma_f32_16x16x32_bf16 v[32:35], v[136:139], v[168:171], v[32:35]
	v_mfma_f32_16x16x32_bf16 v[20:23], v[128:131], v[176:179], v[20:23]
	v_mfma_f32_16x16x32_bf16 v[16:19], v[136:139], v[176:179], v[16:19]
	v_mfma_f32_16x16x32_bf16 v[4:7], v[128:131], v[184:187], v[4:7]
	v_mfma_f32_16x16x32_bf16 v[0:3], v[136:139], v[184:187], v[0:3]
	v_mfma_f32_16x16x32_bf16 v[60:63], v[132:135], v[164:167], v[60:63]
	v_mfma_f32_16x16x32_bf16 v[56:59], v[140:143], v[164:167], v[56:59]
	v_mfma_f32_16x16x32_bf16 v[36:39], v[132:135], v[172:175], v[36:39]
	v_mfma_f32_16x16x32_bf16 v[32:35], v[140:143], v[172:175], v[32:35]
	v_mfma_f32_16x16x32_bf16 v[20:23], v[132:135], v[180:183], v[20:23]
	v_mfma_f32_16x16x32_bf16 v[16:19], v[140:143], v[180:183], v[16:19]
	v_mfma_f32_16x16x32_bf16 v[4:7], v[132:135], v[188:191], v[4:7]
	v_mfma_f32_16x16x32_bf16 v[0:3], v[140:143], v[188:191], v[0:3]
	s_setprio 0
	s_setprio 1
	v_mfma_f32_16x16x32_bf16 v[76:79], v[144:147], v[160:163], v[76:79]
	v_mfma_f32_16x16x32_bf16 v[72:75], v[152:155], v[160:163], v[72:75]
	v_mfma_f32_16x16x32_bf16 v[44:47], v[144:147], v[168:171], v[44:47]
	v_mfma_f32_16x16x32_bf16 v[40:43], v[152:155], v[168:171], v[40:43]
	v_mfma_f32_16x16x32_bf16 v[28:31], v[144:147], v[176:179], v[28:31]
	v_mfma_f32_16x16x32_bf16 v[24:27], v[152:155], v[176:179], v[24:27]
	v_mfma_f32_16x16x32_bf16 v[12:15], v[144:147], v[184:187], v[12:15]
	v_mfma_f32_16x16x32_bf16 v[8:11], v[152:155], v[184:187], v[8:11]
	v_mfma_f32_16x16x32_bf16 v[76:79], v[148:151], v[164:167], v[76:79]
	v_mfma_f32_16x16x32_bf16 v[72:75], v[156:159], v[164:167], v[72:75]
	v_mfma_f32_16x16x32_bf16 v[44:47], v[148:151], v[172:175], v[44:47]
	v_mfma_f32_16x16x32_bf16 v[40:43], v[156:159], v[172:175], v[40:43]
	v_mfma_f32_16x16x32_bf16 v[28:31], v[148:151], v[180:183], v[28:31]
	v_mfma_f32_16x16x32_bf16 v[24:27], v[156:159], v[180:183], v[24:27]
	v_mfma_f32_16x16x32_bf16 v[12:15], v[148:151], v[188:191], v[12:15]
	v_mfma_f32_16x16x32_bf16 v[8:11], v[156:159], v[188:191], v[8:11]
	s_barrier
	s_setprio 0
	s_add_u32 s69, s69, 0x100
	s_addc_u32 s70, s70, 0
	s_add_u32 s44, s44, 0x100
	s_addc_u32 s45, s45, 0
	s_cmp_ge_u32 s71, s67
	s_mov_b32 s46, s71
	s_cbranch_scc1 .Lpeel_done_2
.LBB0_2020:
	ds_read_b128 v[128:131], v244
	ds_read_b128 v[132:135], v244 offset:1024
	ds_read_b128 v[136:139], v244 offset:2048
	ds_read_b128 v[140:143], v244 offset:3072
	ds_read_b128 v[144:147], v245
	ds_read_b128 v[148:151], v245 offset:1024
	ds_read_b128 v[152:155], v245 offset:2048
	ds_read_b128 v[156:159], v245 offset:3072
	s_add_i32 s71, s46, 2
	s_add_u32 s47, s44, 0xfff00080
	s_addc_u32 s48, s45, -1
	s_cmp_eq_u32 s68, s46
	s_cselect_b32 s46, s43, s69
	s_cselect_b32 s49, s5, s48
	s_cselect_b32 s48, s23, s47
	s_cselect_b32 s47, s21, s70
	s_add_i32 m0, s94, 0xc000
	ds_read_b128 v[160:163], v246
	ds_read_b128 v[164:167], v246 offset:1024
	ds_read_b128 v[168:171], v246 offset:2048
	ds_read_b128 v[172:175], v246 offset:3072
	ds_read_b128 v[176:179], v246 offset:4096
	ds_read_b128 v[180:183], v246 offset:5120
	ds_read_b128 v[184:187], v246 offset:6144
	ds_read_b128 v[188:191], v246 offset:7168
	global_load_lds_dwordx4 v218, s[44:45]
	s_add_i32 m0, s94, 0xe000
	s_nop 0
	global_load_lds_dwordx4 v220, s[44:45]
	s_waitcnt vmcnt(8)
	s_waitcnt lgkmcnt(0)
	s_setprio 1
	s_barrier
	v_mfma_f32_16x16x32_bf16 v[112:115], v[128:131], v[160:163], v[112:115]
	v_mfma_f32_16x16x32_bf16 v[116:119], v[136:139], v[160:163], v[116:119]
	v_mfma_f32_16x16x32_bf16 v[100:103], v[128:131], v[168:171], v[100:103]
	v_mfma_f32_16x16x32_bf16 v[96:99], v[136:139], v[168:171], v[96:99]
	v_mfma_f32_16x16x32_bf16 v[84:87], v[128:131], v[176:179], v[84:87]
	v_mfma_f32_16x16x32_bf16 v[80:83], v[136:139], v[176:179], v[80:83]
	v_mfma_f32_16x16x32_bf16 v[52:55], v[128:131], v[184:187], v[52:55]
	v_mfma_f32_16x16x32_bf16 v[48:51], v[136:139], v[184:187], v[48:51]
	v_mfma_f32_16x16x32_bf16 v[112:115], v[132:135], v[164:167], v[112:115]
	v_mfma_f32_16x16x32_bf16 v[116:119], v[140:143], v[164:167], v[116:119]
	v_mfma_f32_16x16x32_bf16 v[100:103], v[132:135], v[172:175], v[100:103]
	v_mfma_f32_16x16x32_bf16 v[96:99], v[140:143], v[172:175], v[96:99]
	v_mfma_f32_16x16x32_bf16 v[84:87], v[132:135], v[180:183], v[84:87]
	v_mfma_f32_16x16x32_bf16 v[80:83], v[140:143], v[180:183], v[80:83]
	v_mfma_f32_16x16x32_bf16 v[52:55], v[132:135], v[188:191], v[52:55]
	v_mfma_f32_16x16x32_bf16 v[48:51], v[140:143], v[188:191], v[48:51]
	s_setprio 0
	s_setprio 1
	v_mfma_f32_16x16x32_bf16 v[124:127], v[144:147], v[160:163], v[124:127]
	v_mfma_f32_16x16x32_bf16 v[120:123], v[152:155], v[160:163], v[120:123]
	v_mfma_f32_16x16x32_bf16 v[108:111], v[144:147], v[168:171], v[108:111]
	v_mfma_f32_16x16x32_bf16 v[104:107], v[152:155], v[168:171], v[104:107]
	v_mfma_f32_16x16x32_bf16 v[92:95], v[144:147], v[176:179], v[92:95]
	v_mfma_f32_16x16x32_bf16 v[88:91], v[152:155], v[176:179], v[88:91]
	v_mfma_f32_16x16x32_bf16 v[68:71], v[144:147], v[184:187], v[68:71]
	v_mfma_f32_16x16x32_bf16 v[64:67], v[152:155], v[184:187], v[64:67]
	v_mfma_f32_16x16x32_bf16 v[124:127], v[148:151], v[164:167], v[124:127]
	v_mfma_f32_16x16x32_bf16 v[120:123], v[156:159], v[164:167], v[120:123]
	v_mfma_f32_16x16x32_bf16 v[108:111], v[148:151], v[172:175], v[108:111]
	v_mfma_f32_16x16x32_bf16 v[104:107], v[156:159], v[172:175], v[104:107]
	v_mfma_f32_16x16x32_bf16 v[92:95], v[148:151], v[180:183], v[92:95]
	v_mfma_f32_16x16x32_bf16 v[88:91], v[156:159], v[180:183], v[88:91]
	v_mfma_f32_16x16x32_bf16 v[68:71], v[148:151], v[188:191], v[68:71]
	v_mfma_f32_16x16x32_bf16 v[64:67], v[156:159], v[188:191], v[64:67]
	s_barrier
	s_setprio 0
	s_add_i32 s76, s60, s97
	s_add_u32 s98, s46, 0x80
	s_addc_u32 s99, s47, 0
	s_mov_b32 m0, s76
	ds_read_b128 v[160:163], v246 offset:16384
	ds_read_b128 v[164:167], v246 offset:17408
	ds_read_b128 v[168:171], v246 offset:18432
	ds_read_b128 v[172:175], v246 offset:19456
	ds_read_b128 v[176:179], v246 offset:20480
	ds_read_b128 v[180:183], v246 offset:21504
	ds_read_b128 v[184:187], v246 offset:22528
	ds_read_b128 v[188:191], v246 offset:23552
	global_load_lds_dwordx4 v210, s[46:47]
	s_add_i32 m0, s76, 0x2000
	s_add_u32 s76, s46, 0x100000
	s_addc_u32 s77, s47, 0
	s_add_i32 s78, s61, s97
	global_load_lds_dwordx4 v214, s[46:47]
	s_mov_b32 m0, s78
	s_add_u32 s100, s48, 0x80
	s_addc_u32 s101, s49, 0
	global_load_lds_dwordx4 v210, s[76:77]
	s_add_i32 m0, s78, 0x2000
	s_nop 0
	global_load_lds_dwordx4 v214, s[76:77]
	s_mov_b32 m0, s94
	s_nop 0
	global_load_lds_dwordx4 v208, s[48:49]
	s_mov_b32 m0, s2
	s_nop 0
	global_load_lds_dwordx4 v212, s[48:49]
	s_waitcnt vmcnt(8)
	s_waitcnt lgkmcnt(0)
	s_setprio 1
	s_barrier
	v_mfma_f32_16x16x32_bf16 v[60:63], v[128:131], v[160:163], v[60:63]
	v_mfma_f32_16x16x32_bf16 v[56:59], v[136:139], v[160:163], v[56:59]
	v_mfma_f32_16x16x32_bf16 v[36:39], v[128:131], v[168:171], v[36:39]
	v_mfma_f32_16x16x32_bf16 v[32:35], v[136:139], v[168:171], v[32:35]
	v_mfma_f32_16x16x32_bf16 v[20:23], v[128:131], v[176:179], v[20:23]
	v_mfma_f32_16x16x32_bf16 v[16:19], v[136:139], v[176:179], v[16:19]
	v_mfma_f32_16x16x32_bf16 v[4:7], v[128:131], v[184:187], v[4:7]
	v_mfma_f32_16x16x32_bf16 v[0:3], v[136:139], v[184:187], v[0:3]
	v_mfma_f32_16x16x32_bf16 v[60:63], v[132:135], v[164:167], v[60:63]
	v_mfma_f32_16x16x32_bf16 v[56:59], v[140:143], v[164:167], v[56:59]
	v_mfma_f32_16x16x32_bf16 v[36:39], v[132:135], v[172:175], v[36:39]
	v_mfma_f32_16x16x32_bf16 v[32:35], v[140:143], v[172:175], v[32:35]
	v_mfma_f32_16x16x32_bf16 v[20:23], v[132:135], v[180:183], v[20:23]
	v_mfma_f32_16x16x32_bf16 v[16:19], v[140:143], v[180:183], v[16:19]
	v_mfma_f32_16x16x32_bf16 v[4:7], v[132:135], v[188:191], v[4:7]
	v_mfma_f32_16x16x32_bf16 v[0:3], v[140:143], v[188:191], v[0:3]
	s_setprio 0
	s_setprio 1
	v_mfma_f32_16x16x32_bf16 v[76:79], v[144:147], v[160:163], v[76:79]
	v_mfma_f32_16x16x32_bf16 v[72:75], v[152:155], v[160:163], v[72:75]
	v_mfma_f32_16x16x32_bf16 v[44:47], v[144:147], v[168:171], v[44:47]
	v_mfma_f32_16x16x32_bf16 v[40:43], v[152:155], v[168:171], v[40:43]
	v_mfma_f32_16x16x32_bf16 v[28:31], v[144:147], v[176:179], v[28:31]
	v_mfma_f32_16x16x32_bf16 v[24:27], v[152:155], v[176:179], v[24:27]
	v_mfma_f32_16x16x32_bf16 v[12:15], v[144:147], v[184:187], v[12:15]
	v_mfma_f32_16x16x32_bf16 v[8:11], v[152:155], v[184:187], v[8:11]
	v_mfma_f32_16x16x32_bf16 v[76:79], v[148:151], v[164:167], v[76:79]
	v_mfma_f32_16x16x32_bf16 v[72:75], v[156:159], v[164:167], v[72:75]
	v_mfma_f32_16x16x32_bf16 v[44:47], v[148:151], v[172:175], v[44:47]
	v_mfma_f32_16x16x32_bf16 v[40:43], v[156:159], v[172:175], v[40:43]
	v_mfma_f32_16x16x32_bf16 v[28:31], v[148:151], v[180:183], v[28:31]
	v_mfma_f32_16x16x32_bf16 v[24:27], v[156:159], v[180:183], v[24:27]
	v_mfma_f32_16x16x32_bf16 v[12:15], v[148:151], v[188:191], v[12:15]
	v_mfma_f32_16x16x32_bf16 v[8:11], v[156:159], v[188:191], v[8:11]
	s_barrier
	s_setprio 0
	s_add_i32 s76, 0, 0x18000
	s_add_i32 s77, 0, 0x1c000
	v_add_u32_e32 v140, s76, v243
	v_add_u32_e32 v156, s77, v243
	ds_read_b128 v[128:131], v140
	ds_read_b128 v[132:135], v140 offset:1024
	ds_read_b128 v[136:139], v140 offset:2048
	ds_read_b128 v[140:143], v140 offset:3072
	ds_read_b128 v[144:147], v156
	ds_read_b128 v[148:151], v156 offset:1024
	ds_read_b128 v[152:155], v156 offset:2048
	ds_read_b128 v[156:159], v156 offset:3072
	s_add_u32 s48, s48, 0x100000
	s_addc_u32 s49, s49, 0
	s_mov_b32 m0, s3
	ds_read_b128 v[160:163], v246 offset:32768
	ds_read_b128 v[164:167], v246 offset:33792
	ds_read_b128 v[168:171], v246 offset:34816
	ds_read_b128 v[172:175], v246 offset:35840
	ds_read_b128 v[176:179], v246 offset:36864
	ds_read_b128 v[180:183], v246 offset:37888
	ds_read_b128 v[184:187], v246 offset:38912
	ds_read_b128 v[188:191], v246 offset:39936
	global_load_lds_dwordx4 v208, s[48:49]
	s_mov_b32 m0, s33
	s_nop 0
	global_load_lds_dwordx4 v212, s[48:49]
	s_waitcnt vmcnt(8)
	s_waitcnt lgkmcnt(0)
	s_setprio 1
	s_barrier
	v_mfma_f32_16x16x32_bf16 v[112:115], v[128:131], v[160:163], v[112:115]
	v_mfma_f32_16x16x32_bf16 v[116:119], v[136:139], v[160:163], v[116:119]
	v_mfma_f32_16x16x32_bf16 v[100:103], v[128:131], v[168:171], v[100:103]
	v_mfma_f32_16x16x32_bf16 v[96:99], v[136:139], v[168:171], v[96:99]
	v_mfma_f32_16x16x32_bf16 v[84:87], v[128:131], v[176:179], v[84:87]
	v_mfma_f32_16x16x32_bf16 v[80:83], v[136:139], v[176:179], v[80:83]
	v_mfma_f32_16x16x32_bf16 v[52:55], v[128:131], v[184:187], v[52:55]
	v_mfma_f32_16x16x32_bf16 v[48:51], v[136:139], v[184:187], v[48:51]
	v_mfma_f32_16x16x32_bf16 v[112:115], v[132:135], v[164:167], v[112:115]
	v_mfma_f32_16x16x32_bf16 v[116:119], v[140:143], v[164:167], v[116:119]
	v_mfma_f32_16x16x32_bf16 v[100:103], v[132:135], v[172:175], v[100:103]
	v_mfma_f32_16x16x32_bf16 v[96:99], v[140:143], v[172:175], v[96:99]
	v_mfma_f32_16x16x32_bf16 v[84:87], v[132:135], v[180:183], v[84:87]
	v_mfma_f32_16x16x32_bf16 v[80:83], v[140:143], v[180:183], v[80:83]
	v_mfma_f32_16x16x32_bf16 v[52:55], v[132:135], v[188:191], v[52:55]
	v_mfma_f32_16x16x32_bf16 v[48:51], v[140:143], v[188:191], v[48:51]
	s_setprio 0
	s_setprio 1
	v_mfma_f32_16x16x32_bf16 v[124:127], v[144:147], v[160:163], v[124:127]
	v_mfma_f32_16x16x32_bf16 v[120:123], v[152:155], v[160:163], v[120:123]
	v_mfma_f32_16x16x32_bf16 v[108:111], v[144:147], v[168:171], v[108:111]
	v_mfma_f32_16x16x32_bf16 v[104:107], v[152:155], v[168:171], v[104:107]
	v_mfma_f32_16x16x32_bf16 v[92:95], v[144:147], v[176:179], v[92:95]
	v_mfma_f32_16x16x32_bf16 v[88:91], v[152:155], v[176:179], v[88:91]
	v_mfma_f32_16x16x32_bf16 v[68:71], v[144:147], v[184:187], v[68:71]
	v_mfma_f32_16x16x32_bf16 v[64:67], v[152:155], v[184:187], v[64:67]
	v_mfma_f32_16x16x32_bf16 v[124:127], v[148:151], v[164:167], v[124:127]
	v_mfma_f32_16x16x32_bf16 v[120:123], v[156:159], v[164:167], v[120:123]
	v_mfma_f32_16x16x32_bf16 v[108:111], v[148:151], v[172:175], v[108:111]
	v_mfma_f32_16x16x32_bf16 v[104:107], v[156:159], v[172:175], v[104:107]
	v_mfma_f32_16x16x32_bf16 v[92:95], v[148:151], v[180:183], v[92:95]
	v_mfma_f32_16x16x32_bf16 v[88:91], v[156:159], v[180:183], v[88:91]
	v_mfma_f32_16x16x32_bf16 v[68:71], v[148:151], v[188:191], v[68:71]
	v_mfma_f32_16x16x32_bf16 v[64:67], v[156:159], v[188:191], v[64:67]
	s_barrier
	s_setprio 0
	s_add_i32 s48, s76, s97
	s_mov_b32 m0, s48
	ds_read_b128 v[160:163], v246 offset:49152
	ds_read_b128 v[164:167], v246 offset:50176
	ds_read_b128 v[168:171], v246 offset:51200
	ds_read_b128 v[172:175], v246 offset:52224
	ds_read_b128 v[176:179], v246 offset:53248
	ds_read_b128 v[180:183], v246 offset:54272
	ds_read_b128 v[184:187], v246 offset:55296
	ds_read_b128 v[188:191], v246 offset:56320
	global_load_lds_dwordx4 v210, s[98:99]
	s_add_i32 m0, s48, 0x2000
	s_add_u32 s46, s46, 0x100080
	s_addc_u32 s47, s47, 0
	s_add_i32 s48, s77, s97
	global_load_lds_dwordx4 v214, s[98:99]
	s_mov_b32 m0, s48
	s_nop 0
	global_load_lds_dwordx4 v210, s[46:47]
	s_add_i32 m0, s48, 0x2000
	s_nop 0
	global_load_lds_dwordx4 v214, s[46:47]
	s_mov_b32 m0, s54
	s_nop 0
	global_load_lds_dwordx4 v208, s[100:101]
	s_mov_b32 m0, s55
	s_nop 0
	global_load_lds_dwordx4 v212, s[100:101]
	s_waitcnt vmcnt(8)
	s_waitcnt lgkmcnt(0)
	s_setprio 1
	s_barrier
	v_mfma_f32_16x16x32_bf16 v[60:63], v[128:131], v[160:163], v[60:63]
	v_mfma_f32_16x16x32_bf16 v[56:59], v[136:139], v[160:163], v[56:59]
	v_mfma_f32_16x16x32_bf16 v[36:39], v[128:131], v[168:171], v[36:39]
	v_mfma_f32_16x16x32_bf16 v[32:35], v[136:139], v[168:171], v[32:35]
	v_mfma_f32_16x16x32_bf16 v[20:23], v[128:131], v[176:179], v[20:23]
	v_mfma_f32_16x16x32_bf16 v[16:19], v[136:139], v[176:179], v[16:19]
	v_mfma_f32_16x16x32_bf16 v[4:7], v[128:131], v[184:187], v[4:7]
	v_mfma_f32_16x16x32_bf16 v[0:3], v[136:139], v[184:187], v[0:3]
	v_mfma_f32_16x16x32_bf16 v[60:63], v[132:135], v[164:167], v[60:63]
	v_mfma_f32_16x16x32_bf16 v[56:59], v[140:143], v[164:167], v[56:59]
	v_mfma_f32_16x16x32_bf16 v[36:39], v[132:135], v[172:175], v[36:39]
	v_mfma_f32_16x16x32_bf16 v[32:35], v[140:143], v[172:175], v[32:35]
	v_mfma_f32_16x16x32_bf16 v[20:23], v[132:135], v[180:183], v[20:23]
	v_mfma_f32_16x16x32_bf16 v[16:19], v[140:143], v[180:183], v[16:19]
	v_mfma_f32_16x16x32_bf16 v[4:7], v[132:135], v[188:191], v[4:7]
	v_mfma_f32_16x16x32_bf16 v[0:3], v[140:143], v[188:191], v[0:3]
	s_setprio 0
	s_setprio 1
	v_mfma_f32_16x16x32_bf16 v[76:79], v[144:147], v[160:163], v[76:79]
	v_mfma_f32_16x16x32_bf16 v[72:75], v[152:155], v[160:163], v[72:75]
	v_mfma_f32_16x16x32_bf16 v[44:47], v[144:147], v[168:171], v[44:47]
	v_mfma_f32_16x16x32_bf16 v[40:43], v[152:155], v[168:171], v[40:43]
	v_mfma_f32_16x16x32_bf16 v[28:31], v[144:147], v[176:179], v[28:31]
	v_mfma_f32_16x16x32_bf16 v[24:27], v[152:155], v[176:179], v[24:27]
	v_mfma_f32_16x16x32_bf16 v[12:15], v[144:147], v[184:187], v[12:15]
	v_mfma_f32_16x16x32_bf16 v[8:11], v[152:155], v[184:187], v[8:11]
	v_mfma_f32_16x16x32_bf16 v[76:79], v[148:151], v[164:167], v[76:79]
	v_mfma_f32_16x16x32_bf16 v[72:75], v[156:159], v[164:167], v[72:75]
	v_mfma_f32_16x16x32_bf16 v[44:47], v[148:151], v[172:175], v[44:47]
	v_mfma_f32_16x16x32_bf16 v[40:43], v[156:159], v[172:175], v[40:43]
	v_mfma_f32_16x16x32_bf16 v[28:31], v[148:151], v[180:183], v[28:31]
	v_mfma_f32_16x16x32_bf16 v[24:27], v[156:159], v[180:183], v[24:27]
	v_mfma_f32_16x16x32_bf16 v[12:15], v[148:151], v[188:191], v[12:15]
	v_mfma_f32_16x16x32_bf16 v[8:11], v[156:159], v[188:191], v[8:11]
	s_barrier
	s_setprio 0
	s_add_u32 s69, s69, 0x100
	s_addc_u32 s70, s70, 0
	s_add_u32 s44, s44, 0x100
	s_addc_u32 s45, s45, 0
	s_cmp_ge_u32 s71, s67
	s_mov_b32 s46, s71
	s_cbranch_scc0 .LBB0_2020

.LBB0_2288:
	s_ashr_i32 s25, s24, 31
	s_lshl_b64 s[86:87], s[24:25], 21
	v_readlane_b32 s88, v254, 52
	v_readlane_b32 s89, v254, 53
	s_add_u32 s5, s88, s86
	s_addc_u32 s25, s89, s87
	s_add_u32 s38, s5, s38
	s_addc_u32 s39, s25, s39
	s_and_b64 s[48:49], s[48:49], exec
	s_cselect_b32 s5, s39, s45
	s_cselect_b32 s25, s38, s44
	s_add_i32 s43, s84, -2
	s_add_u32 s85, s44, 0x100
	s_addc_u32 s86, s45, 0
	s_add_u32 s44, s46, 0x100080
	s_addc_u32 s45, s47, 0
	s_mov_b32 s46, 0
	ds_read_b128 v[148:151], v159
	ds_read_b128 v[164:167], v159 offset:1024
	ds_read_b128 v[168:171], v159 offset:2048
	ds_read_b128 v[172:175], v159 offset:3072
	ds_read_b128 v[176:179], v160
	ds_read_b128 v[180:183], v160 offset:1024
	ds_read_b128 v[184:187], v160 offset:2048
	ds_read_b128 v[188:191], v160 offset:3072
	s_add_i32 s87, s46, 2
	s_add_u32 s47, s44, 0xfff00080
	s_addc_u32 s48, s45, -1
	s_cmp_eq_u32 s43, s46
	s_cselect_b32 s46, s25, s85
	s_cselect_b32 s49, s37, s48
	s_cselect_b32 s48, s36, s47
	s_cselect_b32 s47, s5, s86
	s_add_i32 m0, s94, 0xc000
	ds_read_b128 v[192:195], v161
	ds_read_b128 v[196:199], v161 offset:1024
	ds_read_b128 v[200:203], v161 offset:2048
	ds_read_b128 v[204:207], v161 offset:3072
	ds_read_b128 v[208:211], v161 offset:4096
	ds_read_b128 v[212:215], v161 offset:5120
	ds_read_b128 v[216:219], v161 offset:6144
	ds_read_b128 v[220:223], v161 offset:7168
	global_load_lds_dwordx4 v142, s[44:45]
	s_add_i32 m0, s94, 0xe000
	s_nop 0
	global_load_lds_dwordx4 v144, s[44:45]
	s_waitcnt vmcnt(8)
	s_waitcnt lgkmcnt(0)
	s_setprio 1
	s_barrier
	v_mfma_f32_16x16x32_bf16 v[112:115], v[148:151], v[192:195], 0
	v_mfma_f32_16x16x32_bf16 v[116:119], v[168:171], v[192:195], 0
	v_mfma_f32_16x16x32_bf16 v[100:103], v[148:151], v[200:203], 0
	v_mfma_f32_16x16x32_bf16 v[96:99], v[168:171], v[200:203], 0
	v_mfma_f32_16x16x32_bf16 v[84:87], v[148:151], v[208:211], 0
	v_mfma_f32_16x16x32_bf16 v[80:83], v[168:171], v[208:211], 0
	v_mfma_f32_16x16x32_bf16 v[52:55], v[148:151], v[216:219], 0
	v_mfma_f32_16x16x32_bf16 v[48:51], v[168:171], v[216:219], 0
	v_mfma_f32_16x16x32_bf16 v[112:115], v[164:167], v[196:199], v[112:115]
	v_mfma_f32_16x16x32_bf16 v[116:119], v[172:175], v[196:199], v[116:119]
	v_mfma_f32_16x16x32_bf16 v[100:103], v[164:167], v[204:207], v[100:103]
	v_mfma_f32_16x16x32_bf16 v[96:99], v[172:175], v[204:207], v[96:99]
	v_mfma_f32_16x16x32_bf16 v[84:87], v[164:167], v[212:215], v[84:87]
	v_mfma_f32_16x16x32_bf16 v[80:83], v[172:175], v[212:215], v[80:83]
	v_mfma_f32_16x16x32_bf16 v[52:55], v[164:167], v[220:223], v[52:55]
	v_mfma_f32_16x16x32_bf16 v[48:51], v[172:175], v[220:223], v[48:51]
	s_setprio 0
	s_setprio 1
	v_mfma_f32_16x16x32_bf16 v[124:127], v[176:179], v[192:195], 0
	v_mfma_f32_16x16x32_bf16 v[120:123], v[184:187], v[192:195], 0
	v_mfma_f32_16x16x32_bf16 v[108:111], v[176:179], v[200:203], 0
	v_mfma_f32_16x16x32_bf16 v[104:107], v[184:187], v[200:203], 0
	v_mfma_f32_16x16x32_bf16 v[92:95], v[176:179], v[208:211], 0
	v_mfma_f32_16x16x32_bf16 v[88:91], v[184:187], v[208:211], 0
	v_mfma_f32_16x16x32_bf16 v[68:71], v[176:179], v[216:219], 0
	v_mfma_f32_16x16x32_bf16 v[64:67], v[184:187], v[216:219], 0
	v_mfma_f32_16x16x32_bf16 v[124:127], v[180:183], v[196:199], v[124:127]
	v_mfma_f32_16x16x32_bf16 v[120:123], v[188:191], v[196:199], v[120:123]
	v_mfma_f32_16x16x32_bf16 v[108:111], v[180:183], v[204:207], v[108:111]
	v_mfma_f32_16x16x32_bf16 v[104:107], v[188:191], v[204:207], v[104:107]
	v_mfma_f32_16x16x32_bf16 v[92:95], v[180:183], v[212:215], v[92:95]
	v_mfma_f32_16x16x32_bf16 v[88:91], v[188:191], v[212:215], v[88:91]
	v_mfma_f32_16x16x32_bf16 v[68:71], v[180:183], v[220:223], v[68:71]
	v_mfma_f32_16x16x32_bf16 v[64:67], v[188:191], v[220:223], v[64:67]
	s_barrier
	s_setprio 0
	s_add_i32 s88, s77, s97
	s_add_u32 s98, s46, 0x80
	s_addc_u32 s99, s47, 0
	s_mov_b32 m0, s88
	ds_read_b128 v[192:195], v161 offset:16384
	ds_read_b128 v[196:199], v161 offset:17408
	ds_read_b128 v[200:203], v161 offset:18432
	ds_read_b128 v[204:207], v161 offset:19456
	ds_read_b128 v[208:211], v161 offset:20480
	ds_read_b128 v[212:215], v161 offset:21504
	ds_read_b128 v[216:219], v161 offset:22528
	ds_read_b128 v[220:223], v161 offset:23552
	global_load_lds_dwordx4 v132, s[46:47]
	s_add_i32 m0, s88, 0x2000
	s_add_u32 s88, s46, 0x100000
	s_addc_u32 s89, s47, 0
	s_add_i32 s90, s78, s97
	global_load_lds_dwordx4 v136, s[46:47]
	s_mov_b32 m0, s90
	s_add_u32 s100, s48, 0x80
	s_addc_u32 s101, s49, 0
	global_load_lds_dwordx4 v132, s[88:89]
	s_add_i32 m0, s90, 0x2000
	s_nop 0
	global_load_lds_dwordx4 v136, s[88:89]
	s_mov_b32 m0, s94
	s_nop 0
	global_load_lds_dwordx4 v130, s[48:49]
	s_mov_b32 m0, s52
	s_nop 0
	global_load_lds_dwordx4 v134, s[48:49]
	s_waitcnt vmcnt(8)
	s_waitcnt lgkmcnt(0)
	s_setprio 1
	s_barrier
	v_mfma_f32_16x16x32_bf16 v[60:63], v[148:151], v[192:195], 0
	v_mfma_f32_16x16x32_bf16 v[56:59], v[168:171], v[192:195], 0
	v_mfma_f32_16x16x32_bf16 v[36:39], v[148:151], v[200:203], 0
	v_mfma_f32_16x16x32_bf16 v[32:35], v[168:171], v[200:203], 0
	v_mfma_f32_16x16x32_bf16 v[20:23], v[148:151], v[208:211], 0
	v_mfma_f32_16x16x32_bf16 v[16:19], v[168:171], v[208:211], 0
	v_mfma_f32_16x16x32_bf16 v[4:7], v[148:151], v[216:219], 0
	v_mfma_f32_16x16x32_bf16 v[0:3], v[168:171], v[216:219], 0
	v_mfma_f32_16x16x32_bf16 v[60:63], v[164:167], v[196:199], v[60:63]
	v_mfma_f32_16x16x32_bf16 v[56:59], v[172:175], v[196:199], v[56:59]
	v_mfma_f32_16x16x32_bf16 v[36:39], v[164:167], v[204:207], v[36:39]
	v_mfma_f32_16x16x32_bf16 v[32:35], v[172:175], v[204:207], v[32:35]
	v_mfma_f32_16x16x32_bf16 v[20:23], v[164:167], v[212:215], v[20:23]
	v_mfma_f32_16x16x32_bf16 v[16:19], v[172:175], v[212:215], v[16:19]
	v_mfma_f32_16x16x32_bf16 v[4:7], v[164:167], v[220:223], v[4:7]
	v_mfma_f32_16x16x32_bf16 v[0:3], v[172:175], v[220:223], v[0:3]
	s_setprio 0
	s_setprio 1
	v_mfma_f32_16x16x32_bf16 v[76:79], v[176:179], v[192:195], 0
	v_mfma_f32_16x16x32_bf16 v[72:75], v[184:187], v[192:195], 0
	v_mfma_f32_16x16x32_bf16 v[44:47], v[176:179], v[200:203], 0
	v_mfma_f32_16x16x32_bf16 v[40:43], v[184:187], v[200:203], 0
	v_mfma_f32_16x16x32_bf16 v[28:31], v[176:179], v[208:211], 0
	v_mfma_f32_16x16x32_bf16 v[24:27], v[184:187], v[208:211], 0
	v_mfma_f32_16x16x32_bf16 v[12:15], v[176:179], v[216:219], 0
	v_mfma_f32_16x16x32_bf16 v[8:11], v[184:187], v[216:219], 0
	v_mfma_f32_16x16x32_bf16 v[76:79], v[180:183], v[196:199], v[76:79]
	v_mfma_f32_16x16x32_bf16 v[72:75], v[188:191], v[196:199], v[72:75]
	v_mfma_f32_16x16x32_bf16 v[44:47], v[180:183], v[204:207], v[44:47]
	v_mfma_f32_16x16x32_bf16 v[40:43], v[188:191], v[204:207], v[40:43]
	v_mfma_f32_16x16x32_bf16 v[28:31], v[180:183], v[212:215], v[28:31]
	v_mfma_f32_16x16x32_bf16 v[24:27], v[188:191], v[212:215], v[24:27]
	v_mfma_f32_16x16x32_bf16 v[12:15], v[180:183], v[220:223], v[12:15]
	v_mfma_f32_16x16x32_bf16 v[8:11], v[188:191], v[220:223], v[8:11]
	s_barrier
	s_setprio 0
	s_add_i32 s88, 0, 0x18000
	v_add_u32_e32 v163, s88, v157
	s_add_i32 s89, 0, 0x1c000
	ds_read_b128 v[148:151], v163
	ds_read_b128 v[164:167], v163 offset:1024
	ds_read_b128 v[168:171], v163 offset:2048
	ds_read_b128 v[172:175], v163 offset:3072
	v_add_u32_e32 v163, s89, v157
	ds_read_b128 v[176:179], v163
	ds_read_b128 v[180:183], v163 offset:1024
	ds_read_b128 v[184:187], v163 offset:2048
	ds_read_b128 v[188:191], v163 offset:3072
	s_add_u32 s48, s48, 0x100000
	s_addc_u32 s49, s49, 0
	s_mov_b32 m0, s53
	ds_read_b128 v[192:195], v161 offset:32768
	ds_read_b128 v[196:199], v161 offset:33792
	ds_read_b128 v[200:203], v161 offset:34816
	ds_read_b128 v[204:207], v161 offset:35840
	ds_read_b128 v[208:211], v161 offset:36864
	ds_read_b128 v[212:215], v161 offset:37888
	ds_read_b128 v[216:219], v161 offset:38912
	ds_read_b128 v[220:223], v161 offset:39936
	global_load_lds_dwordx4 v130, s[48:49]
	s_mov_b32 m0, s54
	s_nop 0
	global_load_lds_dwordx4 v134, s[48:49]
	s_waitcnt vmcnt(8)
	s_waitcnt lgkmcnt(0)
	s_setprio 1
	s_barrier
	v_mfma_f32_16x16x32_bf16 v[112:115], v[148:151], v[192:195], v[112:115]
	v_mfma_f32_16x16x32_bf16 v[116:119], v[168:171], v[192:195], v[116:119]
	v_mfma_f32_16x16x32_bf16 v[100:103], v[148:151], v[200:203], v[100:103]
	v_mfma_f32_16x16x32_bf16 v[96:99], v[168:171], v[200:203], v[96:99]
	v_mfma_f32_16x16x32_bf16 v[84:87], v[148:151], v[208:211], v[84:87]
	v_mfma_f32_16x16x32_bf16 v[80:83], v[168:171], v[208:211], v[80:83]
	v_mfma_f32_16x16x32_bf16 v[52:55], v[148:151], v[216:219], v[52:55]
	v_mfma_f32_16x16x32_bf16 v[48:51], v[168:171], v[216:219], v[48:51]
	v_mfma_f32_16x16x32_bf16 v[112:115], v[164:167], v[196:199], v[112:115]
	v_mfma_f32_16x16x32_bf16 v[116:119], v[172:175], v[196:199], v[116:119]
	v_mfma_f32_16x16x32_bf16 v[100:103], v[164:167], v[204:207], v[100:103]
	v_mfma_f32_16x16x32_bf16 v[96:99], v[172:175], v[204:207], v[96:99]
	v_mfma_f32_16x16x32_bf16 v[84:87], v[164:167], v[212:215], v[84:87]
	v_mfma_f32_16x16x32_bf16 v[80:83], v[172:175], v[212:215], v[80:83]
	v_mfma_f32_16x16x32_bf16 v[52:55], v[164:167], v[220:223], v[52:55]
	v_mfma_f32_16x16x32_bf16 v[48:51], v[172:175], v[220:223], v[48:51]
	s_setprio 0
	s_setprio 1
	v_mfma_f32_16x16x32_bf16 v[124:127], v[176:179], v[192:195], v[124:127]
	v_mfma_f32_16x16x32_bf16 v[120:123], v[184:187], v[192:195], v[120:123]
	v_mfma_f32_16x16x32_bf16 v[108:111], v[176:179], v[200:203], v[108:111]
	v_mfma_f32_16x16x32_bf16 v[104:107], v[184:187], v[200:203], v[104:107]
	v_mfma_f32_16x16x32_bf16 v[92:95], v[176:179], v[208:211], v[92:95]
	v_mfma_f32_16x16x32_bf16 v[88:91], v[184:187], v[208:211], v[88:91]
	v_mfma_f32_16x16x32_bf16 v[68:71], v[176:179], v[216:219], v[68:71]
	v_mfma_f32_16x16x32_bf16 v[64:67], v[184:187], v[216:219], v[64:67]
	v_mfma_f32_16x16x32_bf16 v[124:127], v[180:183], v[196:199], v[124:127]
	v_mfma_f32_16x16x32_bf16 v[120:123], v[188:191], v[196:199], v[120:123]
	v_mfma_f32_16x16x32_bf16 v[108:111], v[180:183], v[204:207], v[108:111]
	v_mfma_f32_16x16x32_bf16 v[104:107], v[188:191], v[204:207], v[104:107]
	v_mfma_f32_16x16x32_bf16 v[92:95], v[180:183], v[212:215], v[92:95]
	v_mfma_f32_16x16x32_bf16 v[88:91], v[188:191], v[212:215], v[88:91]
	v_mfma_f32_16x16x32_bf16 v[68:71], v[180:183], v[220:223], v[68:71]
	v_mfma_f32_16x16x32_bf16 v[64:67], v[188:191], v[220:223], v[64:67]
	s_barrier
	s_setprio 0
	s_add_i32 s48, s88, s97
	s_mov_b32 m0, s48
	ds_read_b128 v[192:195], v161 offset:49152
	ds_read_b128 v[196:199], v161 offset:50176
	ds_read_b128 v[200:203], v161 offset:51200
	ds_read_b128 v[204:207], v161 offset:52224
	ds_read_b128 v[208:211], v161 offset:53248
	ds_read_b128 v[212:215], v161 offset:54272
	ds_read_b128 v[216:219], v161 offset:55296
	ds_read_b128 v[220:223], v161 offset:56320
	global_load_lds_dwordx4 v132, s[98:99]
	s_add_i32 m0, s48, 0x2000
	s_add_u32 s46, s46, 0x100080
	s_addc_u32 s47, s47, 0
	s_add_i32 s48, s89, s97
	global_load_lds_dwordx4 v136, s[98:99]
	s_mov_b32 m0, s48
	s_nop 0
	global_load_lds_dwordx4 v132, s[46:47]
	s_add_i32 m0, s48, 0x2000
	s_nop 0
	global_load_lds_dwordx4 v136, s[46:47]
	s_mov_b32 m0, s68
	s_nop 0
	global_load_lds_dwordx4 v130, s[100:101]
	s_mov_b32 m0, s69
	s_nop 0
	global_load_lds_dwordx4 v134, s[100:101]
	s_waitcnt vmcnt(8)
	s_waitcnt lgkmcnt(0)
	s_setprio 1
	s_barrier
	v_mfma_f32_16x16x32_bf16 v[60:63], v[148:151], v[192:195], v[60:63]
	v_mfma_f32_16x16x32_bf16 v[56:59], v[168:171], v[192:195], v[56:59]
	v_mfma_f32_16x16x32_bf16 v[36:39], v[148:151], v[200:203], v[36:39]
	v_mfma_f32_16x16x32_bf16 v[32:35], v[168:171], v[200:203], v[32:35]
	v_mfma_f32_16x16x32_bf16 v[20:23], v[148:151], v[208:211], v[20:23]
	v_mfma_f32_16x16x32_bf16 v[16:19], v[168:171], v[208:211], v[16:19]
	v_mfma_f32_16x16x32_bf16 v[4:7], v[148:151], v[216:219], v[4:7]
	v_mfma_f32_16x16x32_bf16 v[0:3], v[168:171], v[216:219], v[0:3]
	v_mfma_f32_16x16x32_bf16 v[60:63], v[164:167], v[196:199], v[60:63]
	v_mfma_f32_16x16x32_bf16 v[56:59], v[172:175], v[196:199], v[56:59]
	v_mfma_f32_16x16x32_bf16 v[36:39], v[164:167], v[204:207], v[36:39]
	v_mfma_f32_16x16x32_bf16 v[32:35], v[172:175], v[204:207], v[32:35]
	v_mfma_f32_16x16x32_bf16 v[20:23], v[164:167], v[212:215], v[20:23]
	v_mfma_f32_16x16x32_bf16 v[16:19], v[172:175], v[212:215], v[16:19]
	v_mfma_f32_16x16x32_bf16 v[4:7], v[164:167], v[220:223], v[4:7]
	v_mfma_f32_16x16x32_bf16 v[0:3], v[172:175], v[220:223], v[0:3]
	s_setprio 0
	s_setprio 1
	v_mfma_f32_16x16x32_bf16 v[76:79], v[176:179], v[192:195], v[76:79]
	v_mfma_f32_16x16x32_bf16 v[72:75], v[184:187], v[192:195], v[72:75]
	v_mfma_f32_16x16x32_bf16 v[44:47], v[176:179], v[200:203], v[44:47]
	v_mfma_f32_16x16x32_bf16 v[40:43], v[184:187], v[200:203], v[40:43]
	v_mfma_f32_16x16x32_bf16 v[28:31], v[176:179], v[208:211], v[28:31]
	v_mfma_f32_16x16x32_bf16 v[24:27], v[184:187], v[208:211], v[24:27]
	v_mfma_f32_16x16x32_bf16 v[12:15], v[176:179], v[216:219], v[12:15]
	v_mfma_f32_16x16x32_bf16 v[8:11], v[184:187], v[216:219], v[8:11]
	v_mfma_f32_16x16x32_bf16 v[76:79], v[180:183], v[196:199], v[76:79]
	v_mfma_f32_16x16x32_bf16 v[72:75], v[188:191], v[196:199], v[72:75]
	v_mfma_f32_16x16x32_bf16 v[44:47], v[180:183], v[204:207], v[44:47]
	v_mfma_f32_16x16x32_bf16 v[40:43], v[188:191], v[204:207], v[40:43]
	v_mfma_f32_16x16x32_bf16 v[28:31], v[180:183], v[212:215], v[28:31]
	v_mfma_f32_16x16x32_bf16 v[24:27], v[188:191], v[212:215], v[24:27]
	v_mfma_f32_16x16x32_bf16 v[12:15], v[180:183], v[220:223], v[12:15]
	v_mfma_f32_16x16x32_bf16 v[8:11], v[188:191], v[220:223], v[8:11]
	s_barrier
	s_setprio 0
	s_add_u32 s85, s85, 0x100
	s_addc_u32 s86, s86, 0
	s_add_u32 s44, s44, 0x100
	s_addc_u32 s45, s45, 0
	s_cmp_ge_u32 s87, s84
	s_mov_b32 s46, s87
	s_cbranch_scc1 .Lpeel_done_3
.LBB0_2289:
	ds_read_b128 v[148:151], v159
	ds_read_b128 v[164:167], v159 offset:1024
	ds_read_b128 v[168:171], v159 offset:2048
	ds_read_b128 v[172:175], v159 offset:3072
	ds_read_b128 v[176:179], v160
	ds_read_b128 v[180:183], v160 offset:1024
	ds_read_b128 v[184:187], v160 offset:2048
	ds_read_b128 v[188:191], v160 offset:3072
	s_add_i32 s87, s46, 2
	s_add_u32 s47, s44, 0xfff00080
	s_addc_u32 s48, s45, -1
	s_cmp_eq_u32 s43, s46
	s_cselect_b32 s46, s25, s85
	s_cselect_b32 s49, s37, s48
	s_cselect_b32 s48, s36, s47
	s_cselect_b32 s47, s5, s86
	s_add_i32 m0, s94, 0xc000
	ds_read_b128 v[192:195], v161
	ds_read_b128 v[196:199], v161 offset:1024
	ds_read_b128 v[200:203], v161 offset:2048
	ds_read_b128 v[204:207], v161 offset:3072
	ds_read_b128 v[208:211], v161 offset:4096
	ds_read_b128 v[212:215], v161 offset:5120
	ds_read_b128 v[216:219], v161 offset:6144
	ds_read_b128 v[220:223], v161 offset:7168
	global_load_lds_dwordx4 v142, s[44:45]
	s_add_i32 m0, s94, 0xe000
	s_nop 0
	global_load_lds_dwordx4 v144, s[44:45]
	s_waitcnt vmcnt(8)
	s_waitcnt lgkmcnt(0)
	s_setprio 1
	s_barrier
	v_mfma_f32_16x16x32_bf16 v[112:115], v[148:151], v[192:195], v[112:115]
	v_mfma_f32_16x16x32_bf16 v[116:119], v[168:171], v[192:195], v[116:119]
	v_mfma_f32_16x16x32_bf16 v[100:103], v[148:151], v[200:203], v[100:103]
	v_mfma_f32_16x16x32_bf16 v[96:99], v[168:171], v[200:203], v[96:99]
	v_mfma_f32_16x16x32_bf16 v[84:87], v[148:151], v[208:211], v[84:87]
	v_mfma_f32_16x16x32_bf16 v[80:83], v[168:171], v[208:211], v[80:83]
	v_mfma_f32_16x16x32_bf16 v[52:55], v[148:151], v[216:219], v[52:55]
	v_mfma_f32_16x16x32_bf16 v[48:51], v[168:171], v[216:219], v[48:51]
	v_mfma_f32_16x16x32_bf16 v[112:115], v[164:167], v[196:199], v[112:115]
	v_mfma_f32_16x16x32_bf16 v[116:119], v[172:175], v[196:199], v[116:119]
	v_mfma_f32_16x16x32_bf16 v[100:103], v[164:167], v[204:207], v[100:103]
	v_mfma_f32_16x16x32_bf16 v[96:99], v[172:175], v[204:207], v[96:99]
	v_mfma_f32_16x16x32_bf16 v[84:87], v[164:167], v[212:215], v[84:87]
	v_mfma_f32_16x16x32_bf16 v[80:83], v[172:175], v[212:215], v[80:83]
	v_mfma_f32_16x16x32_bf16 v[52:55], v[164:167], v[220:223], v[52:55]
	v_mfma_f32_16x16x32_bf16 v[48:51], v[172:175], v[220:223], v[48:51]
	s_setprio 0
	s_setprio 1
	v_mfma_f32_16x16x32_bf16 v[124:127], v[176:179], v[192:195], v[124:127]
	v_mfma_f32_16x16x32_bf16 v[120:123], v[184:187], v[192:195], v[120:123]
	v_mfma_f32_16x16x32_bf16 v[108:111], v[176:179], v[200:203], v[108:111]
	v_mfma_f32_16x16x32_bf16 v[104:107], v[184:187], v[200:203], v[104:107]
	v_mfma_f32_16x16x32_bf16 v[92:95], v[176:179], v[208:211], v[92:95]
	v_mfma_f32_16x16x32_bf16 v[88:91], v[184:187], v[208:211], v[88:91]
	v_mfma_f32_16x16x32_bf16 v[68:71], v[176:179], v[216:219], v[68:71]
	v_mfma_f32_16x16x32_bf16 v[64:67], v[184:187], v[216:219], v[64:67]
	v_mfma_f32_16x16x32_bf16 v[124:127], v[180:183], v[196:199], v[124:127]
	v_mfma_f32_16x16x32_bf16 v[120:123], v[188:191], v[196:199], v[120:123]
	v_mfma_f32_16x16x32_bf16 v[108:111], v[180:183], v[204:207], v[108:111]
	v_mfma_f32_16x16x32_bf16 v[104:107], v[188:191], v[204:207], v[104:107]
	v_mfma_f32_16x16x32_bf16 v[92:95], v[180:183], v[212:215], v[92:95]
	v_mfma_f32_16x16x32_bf16 v[88:91], v[188:191], v[212:215], v[88:91]
	v_mfma_f32_16x16x32_bf16 v[68:71], v[180:183], v[220:223], v[68:71]
	v_mfma_f32_16x16x32_bf16 v[64:67], v[188:191], v[220:223], v[64:67]
	s_barrier
	s_setprio 0
	s_add_i32 s88, s77, s97
	s_add_u32 s98, s46, 0x80
	s_addc_u32 s99, s47, 0
	s_mov_b32 m0, s88
	ds_read_b128 v[192:195], v161 offset:16384
	ds_read_b128 v[196:199], v161 offset:17408
	ds_read_b128 v[200:203], v161 offset:18432
	ds_read_b128 v[204:207], v161 offset:19456
	ds_read_b128 v[208:211], v161 offset:20480
	ds_read_b128 v[212:215], v161 offset:21504
	ds_read_b128 v[216:219], v161 offset:22528
	ds_read_b128 v[220:223], v161 offset:23552
	global_load_lds_dwordx4 v132, s[46:47]
	s_add_i32 m0, s88, 0x2000
	s_add_u32 s88, s46, 0x100000
	s_addc_u32 s89, s47, 0
	s_add_i32 s90, s78, s97
	global_load_lds_dwordx4 v136, s[46:47]
	s_mov_b32 m0, s90
	s_add_u32 s100, s48, 0x80
	s_addc_u32 s101, s49, 0
	global_load_lds_dwordx4 v132, s[88:89]
	s_add_i32 m0, s90, 0x2000
	s_nop 0
	global_load_lds_dwordx4 v136, s[88:89]
	s_mov_b32 m0, s94
	s_nop 0
	global_load_lds_dwordx4 v130, s[48:49]
	s_mov_b32 m0, s52
	s_nop 0
	global_load_lds_dwordx4 v134, s[48:49]
	s_waitcnt vmcnt(8)
	s_waitcnt lgkmcnt(0)
	s_setprio 1
	s_barrier
	v_mfma_f32_16x16x32_bf16 v[60:63], v[148:151], v[192:195], v[60:63]
	v_mfma_f32_16x16x32_bf16 v[56:59], v[168:171], v[192:195], v[56:59]
	v_mfma_f32_16x16x32_bf16 v[36:39], v[148:151], v[200:203], v[36:39]
	v_mfma_f32_16x16x32_bf16 v[32:35], v[168:171], v[200:203], v[32:35]
	v_mfma_f32_16x16x32_bf16 v[20:23], v[148:151], v[208:211], v[20:23]
	v_mfma_f32_16x16x32_bf16 v[16:19], v[168:171], v[208:211], v[16:19]
	v_mfma_f32_16x16x32_bf16 v[4:7], v[148:151], v[216:219], v[4:7]
	v_mfma_f32_16x16x32_bf16 v[0:3], v[168:171], v[216:219], v[0:3]
	v_mfma_f32_16x16x32_bf16 v[60:63], v[164:167], v[196:199], v[60:63]
	v_mfma_f32_16x16x32_bf16 v[56:59], v[172:175], v[196:199], v[56:59]
	v_mfma_f32_16x16x32_bf16 v[36:39], v[164:167], v[204:207], v[36:39]
	v_mfma_f32_16x16x32_bf16 v[32:35], v[172:175], v[204:207], v[32:35]
	v_mfma_f32_16x16x32_bf16 v[20:23], v[164:167], v[212:215], v[20:23]
	v_mfma_f32_16x16x32_bf16 v[16:19], v[172:175], v[212:215], v[16:19]
	v_mfma_f32_16x16x32_bf16 v[4:7], v[164:167], v[220:223], v[4:7]
	v_mfma_f32_16x16x32_bf16 v[0:3], v[172:175], v[220:223], v[0:3]
	s_setprio 0
	s_setprio 1
	v_mfma_f32_16x16x32_bf16 v[76:79], v[176:179], v[192:195], v[76:79]
	v_mfma_f32_16x16x32_bf16 v[72:75], v[184:187], v[192:195], v[72:75]
	v_mfma_f32_16x16x32_bf16 v[44:47], v[176:179], v[200:203], v[44:47]
	v_mfma_f32_16x16x32_bf16 v[40:43], v[184:187], v[200:203], v[40:43]
	v_mfma_f32_16x16x32_bf16 v[28:31], v[176:179], v[208:211], v[28:31]
	v_mfma_f32_16x16x32_bf16 v[24:27], v[184:187], v[208:211], v[24:27]
	v_mfma_f32_16x16x32_bf16 v[12:15], v[176:179], v[216:219], v[12:15]
	v_mfma_f32_16x16x32_bf16 v[8:11], v[184:187], v[216:219], v[8:11]
	v_mfma_f32_16x16x32_bf16 v[76:79], v[180:183], v[196:199], v[76:79]
	v_mfma_f32_16x16x32_bf16 v[72:75], v[188:191], v[196:199], v[72:75]
	v_mfma_f32_16x16x32_bf16 v[44:47], v[180:183], v[204:207], v[44:47]
	v_mfma_f32_16x16x32_bf16 v[40:43], v[188:191], v[204:207], v[40:43]
	v_mfma_f32_16x16x32_bf16 v[28:31], v[180:183], v[212:215], v[28:31]
	v_mfma_f32_16x16x32_bf16 v[24:27], v[188:191], v[212:215], v[24:27]
	v_mfma_f32_16x16x32_bf16 v[12:15], v[180:183], v[220:223], v[12:15]
	v_mfma_f32_16x16x32_bf16 v[8:11], v[188:191], v[220:223], v[8:11]
	s_barrier
	s_setprio 0
	s_add_i32 s88, 0, 0x18000
	v_add_u32_e32 v163, s88, v157
	s_add_i32 s89, 0, 0x1c000
	ds_read_b128 v[148:151], v163
	ds_read_b128 v[164:167], v163 offset:1024
	ds_read_b128 v[168:171], v163 offset:2048
	ds_read_b128 v[172:175], v163 offset:3072
	v_add_u32_e32 v163, s89, v157
	ds_read_b128 v[176:179], v163
	ds_read_b128 v[180:183], v163 offset:1024
	ds_read_b128 v[184:187], v163 offset:2048
	ds_read_b128 v[188:191], v163 offset:3072
	s_add_u32 s48, s48, 0x100000
	s_addc_u32 s49, s49, 0
	s_mov_b32 m0, s53
	ds_read_b128 v[192:195], v161 offset:32768
	ds_read_b128 v[196:199], v161 offset:33792
	ds_read_b128 v[200:203], v161 offset:34816
	ds_read_b128 v[204:207], v161 offset:35840
	ds_read_b128 v[208:211], v161 offset:36864
	ds_read_b128 v[212:215], v161 offset:37888
	ds_read_b128 v[216:219], v161 offset:38912
	ds_read_b128 v[220:223], v161 offset:39936
	global_load_lds_dwordx4 v130, s[48:49]
	s_mov_b32 m0, s54
	s_nop 0
	global_load_lds_dwordx4 v134, s[48:49]
	s_waitcnt vmcnt(8)
	s_waitcnt lgkmcnt(0)
	s_setprio 1
	s_barrier
	v_mfma_f32_16x16x32_bf16 v[112:115], v[148:151], v[192:195], v[112:115]
	v_mfma_f32_16x16x32_bf16 v[116:119], v[168:171], v[192:195], v[116:119]
	v_mfma_f32_16x16x32_bf16 v[100:103], v[148:151], v[200:203], v[100:103]
	v_mfma_f32_16x16x32_bf16 v[96:99], v[168:171], v[200:203], v[96:99]
	v_mfma_f32_16x16x32_bf16 v[84:87], v[148:151], v[208:211], v[84:87]
	v_mfma_f32_16x16x32_bf16 v[80:83], v[168:171], v[208:211], v[80:83]
	v_mfma_f32_16x16x32_bf16 v[52:55], v[148:151], v[216:219], v[52:55]
	v_mfma_f32_16x16x32_bf16 v[48:51], v[168:171], v[216:219], v[48:51]
	v_mfma_f32_16x16x32_bf16 v[112:115], v[164:167], v[196:199], v[112:115]
	v_mfma_f32_16x16x32_bf16 v[116:119], v[172:175], v[196:199], v[116:119]
	v_mfma_f32_16x16x32_bf16 v[100:103], v[164:167], v[204:207], v[100:103]
	v_mfma_f32_16x16x32_bf16 v[96:99], v[172:175], v[204:207], v[96:99]
	v_mfma_f32_16x16x32_bf16 v[84:87], v[164:167], v[212:215], v[84:87]
	v_mfma_f32_16x16x32_bf16 v[80:83], v[172:175], v[212:215], v[80:83]
	v_mfma_f32_16x16x32_bf16 v[52:55], v[164:167], v[220:223], v[52:55]
	v_mfma_f32_16x16x32_bf16 v[48:51], v[172:175], v[220:223], v[48:51]
	s_setprio 0
	s_setprio 1
	v_mfma_f32_16x16x32_bf16 v[124:127], v[176:179], v[192:195], v[124:127]
	v_mfma_f32_16x16x32_bf16 v[120:123], v[184:187], v[192:195], v[120:123]
	v_mfma_f32_16x16x32_bf16 v[108:111], v[176:179], v[200:203], v[108:111]
	v_mfma_f32_16x16x32_bf16 v[104:107], v[184:187], v[200:203], v[104:107]
	v_mfma_f32_16x16x32_bf16 v[92:95], v[176:179], v[208:211], v[92:95]
	v_mfma_f32_16x16x32_bf16 v[88:91], v[184:187], v[208:211], v[88:91]
	v_mfma_f32_16x16x32_bf16 v[68:71], v[176:179], v[216:219], v[68:71]
	v_mfma_f32_16x16x32_bf16 v[64:67], v[184:187], v[216:219], v[64:67]
	v_mfma_f32_16x16x32_bf16 v[124:127], v[180:183], v[196:199], v[124:127]
	v_mfma_f32_16x16x32_bf16 v[120:123], v[188:191], v[196:199], v[120:123]
	v_mfma_f32_16x16x32_bf16 v[108:111], v[180:183], v[204:207], v[108:111]
	v_mfma_f32_16x16x32_bf16 v[104:107], v[188:191], v[204:207], v[104:107]
	v_mfma_f32_16x16x32_bf16 v[92:95], v[180:183], v[212:215], v[92:95]
	v_mfma_f32_16x16x32_bf16 v[88:91], v[188:191], v[212:215], v[88:91]
	v_mfma_f32_16x16x32_bf16 v[68:71], v[180:183], v[220:223], v[68:71]
	v_mfma_f32_16x16x32_bf16 v[64:67], v[188:191], v[220:223], v[64:67]
	s_barrier
	s_setprio 0
	s_add_i32 s48, s88, s97
	s_mov_b32 m0, s48
	ds_read_b128 v[192:195], v161 offset:49152
	ds_read_b128 v[196:199], v161 offset:50176
	ds_read_b128 v[200:203], v161 offset:51200
	ds_read_b128 v[204:207], v161 offset:52224
	ds_read_b128 v[208:211], v161 offset:53248
	ds_read_b128 v[212:215], v161 offset:54272
	ds_read_b128 v[216:219], v161 offset:55296
	ds_read_b128 v[220:223], v161 offset:56320
	global_load_lds_dwordx4 v132, s[98:99]
	s_add_i32 m0, s48, 0x2000
	s_add_u32 s46, s46, 0x100080
	s_addc_u32 s47, s47, 0
	s_add_i32 s48, s89, s97
	global_load_lds_dwordx4 v136, s[98:99]
	s_mov_b32 m0, s48
	s_nop 0
	global_load_lds_dwordx4 v132, s[46:47]
	s_add_i32 m0, s48, 0x2000
	s_nop 0
	global_load_lds_dwordx4 v136, s[46:47]
	s_mov_b32 m0, s68
	s_nop 0
	global_load_lds_dwordx4 v130, s[100:101]
	s_mov_b32 m0, s69
	s_nop 0
	global_load_lds_dwordx4 v134, s[100:101]
	s_waitcnt vmcnt(8)
	s_waitcnt lgkmcnt(0)
	s_setprio 1
	s_barrier
	v_mfma_f32_16x16x32_bf16 v[60:63], v[148:151], v[192:195], v[60:63]
	v_mfma_f32_16x16x32_bf16 v[56:59], v[168:171], v[192:195], v[56:59]
	v_mfma_f32_16x16x32_bf16 v[36:39], v[148:151], v[200:203], v[36:39]
	v_mfma_f32_16x16x32_bf16 v[32:35], v[168:171], v[200:203], v[32:35]
	v_mfma_f32_16x16x32_bf16 v[20:23], v[148:151], v[208:211], v[20:23]
	v_mfma_f32_16x16x32_bf16 v[16:19], v[168:171], v[208:211], v[16:19]
	v_mfma_f32_16x16x32_bf16 v[4:7], v[148:151], v[216:219], v[4:7]
	v_mfma_f32_16x16x32_bf16 v[0:3], v[168:171], v[216:219], v[0:3]
	v_mfma_f32_16x16x32_bf16 v[60:63], v[164:167], v[196:199], v[60:63]
	v_mfma_f32_16x16x32_bf16 v[56:59], v[172:175], v[196:199], v[56:59]
	v_mfma_f32_16x16x32_bf16 v[36:39], v[164:167], v[204:207], v[36:39]
	v_mfma_f32_16x16x32_bf16 v[32:35], v[172:175], v[204:207], v[32:35]
	v_mfma_f32_16x16x32_bf16 v[20:23], v[164:167], v[212:215], v[20:23]
	v_mfma_f32_16x16x32_bf16 v[16:19], v[172:175], v[212:215], v[16:19]
	v_mfma_f32_16x16x32_bf16 v[4:7], v[164:167], v[220:223], v[4:7]
	v_mfma_f32_16x16x32_bf16 v[0:3], v[172:175], v[220:223], v[0:3]
	s_setprio 0
	s_setprio 1
	v_mfma_f32_16x16x32_bf16 v[76:79], v[176:179], v[192:195], v[76:79]
	v_mfma_f32_16x16x32_bf16 v[72:75], v[184:187], v[192:195], v[72:75]
	v_mfma_f32_16x16x32_bf16 v[44:47], v[176:179], v[200:203], v[44:47]
	v_mfma_f32_16x16x32_bf16 v[40:43], v[184:187], v[200:203], v[40:43]
	v_mfma_f32_16x16x32_bf16 v[28:31], v[176:179], v[208:211], v[28:31]
	v_mfma_f32_16x16x32_bf16 v[24:27], v[184:187], v[208:211], v[24:27]
	v_mfma_f32_16x16x32_bf16 v[12:15], v[176:179], v[216:219], v[12:15]
	v_mfma_f32_16x16x32_bf16 v[8:11], v[184:187], v[216:219], v[8:11]
	v_mfma_f32_16x16x32_bf16 v[76:79], v[180:183], v[196:199], v[76:79]
	v_mfma_f32_16x16x32_bf16 v[72:75], v[188:191], v[196:199], v[72:75]
	v_mfma_f32_16x16x32_bf16 v[44:47], v[180:183], v[204:207], v[44:47]
	v_mfma_f32_16x16x32_bf16 v[40:43], v[188:191], v[204:207], v[40:43]
	v_mfma_f32_16x16x32_bf16 v[28:31], v[180:183], v[212:215], v[28:31]
	v_mfma_f32_16x16x32_bf16 v[24:27], v[188:191], v[212:215], v[24:27]
	v_mfma_f32_16x16x32_bf16 v[12:15], v[180:183], v[220:223], v[12:15]
	v_mfma_f32_16x16x32_bf16 v[8:11], v[188:191], v[220:223], v[8:11]
	s_barrier
	s_setprio 0
	s_add_u32 s85, s85, 0x100
	s_addc_u32 s86, s86, 0
	s_add_u32 s44, s44, 0x100
	s_addc_u32 s45, s45, 0
	s_cmp_ge_u32 s87, s84
	s_mov_b32 s46, s87
	s_cbranch_scc0 .LBB0_2289

.LBB0_2452:
	s_cmp_lt_u32 s35, 0x3fffffff
	s_cselect_b64 s[38:39], -1, 0
	s_ashr_i32 s35, s34, 31
	s_and_b64 s[38:39], s[4:5], s[38:39]
	s_lshl_b64 s[4:5], s[34:35], 23
	s_add_u32 s4, s2, s4
	s_addc_u32 s5, s3, s5
	s_add_u32 s4, s4, s36
	s_addc_u32 s5, s5, s37
	s_and_b64 s[48:49], s[38:39], exec
	s_cselect_b32 s35, s5, s47
	s_cselect_b32 s41, s4, s46
	s_ashr_i32 s31, s30, 31
	s_lshl_b64 s[48:49], s[30:31], 23
	v_readlane_b32 s78, v254, 54
	v_readlane_b32 s79, v254, 55
	s_add_u32 s31, s78, s48
	s_addc_u32 s43, s79, s49
	s_add_u32 s36, s31, s36
	s_addc_u32 s37, s43, s37
	s_and_b64 s[48:49], s[38:39], exec
	s_cselect_b32 s31, s37, s45
	s_cselect_b32 s43, s36, s44
	s_add_i32 s75, s76, -2
	s_add_u32 s77, s44, 0x100
	s_addc_u32 s78, s45, 0
	s_add_u32 s44, s46, 0x400080
	s_addc_u32 s45, s47, 0
	s_mov_b32 s46, 0
	ds_read_b128 v[128:131], v228
	ds_read_b128 v[132:135], v228 offset:1024
	ds_read_b128 v[136:139], v228 offset:2048
	ds_read_b128 v[140:143], v228 offset:3072
	ds_read_b128 v[144:147], v229
	ds_read_b128 v[148:151], v229 offset:1024
	ds_read_b128 v[152:155], v229 offset:2048
	ds_read_b128 v[156:159], v229 offset:3072
	s_add_i32 s79, s46, 2
	s_add_u32 s47, s44, 0xffc00080
	s_addc_u32 s48, s45, -1
	s_cmp_eq_u32 s75, s46
	s_cselect_b32 s46, s43, s77
	s_cselect_b32 s49, s35, s48
	s_cselect_b32 s48, s41, s47
	s_cselect_b32 s47, s31, s78
	s_add_i32 m0, s94, 0xc000
	ds_read_b128 v[160:163], v230
	ds_read_b128 v[164:167], v230 offset:1024
	ds_read_b128 v[168:171], v230 offset:2048
	ds_read_b128 v[172:175], v230 offset:3072
	ds_read_b128 v[176:179], v230 offset:4096
	ds_read_b128 v[180:183], v230 offset:5120
	ds_read_b128 v[184:187], v230 offset:6144
	ds_read_b128 v[188:191], v230 offset:7168
	global_load_lds_dwordx4 v202, s[44:45]
	s_add_i32 m0, s94, 0xe000
	s_nop 0
	global_load_lds_dwordx4 v204, s[44:45]
	s_waitcnt vmcnt(8)
	s_waitcnt lgkmcnt(0)
	s_setprio 1
	s_barrier
	v_mfma_f32_16x16x32_bf16 v[112:115], v[128:131], v[160:163], 0
	v_mfma_f32_16x16x32_bf16 v[116:119], v[136:139], v[160:163], 0
	v_mfma_f32_16x16x32_bf16 v[100:103], v[128:131], v[168:171], 0
	v_mfma_f32_16x16x32_bf16 v[96:99], v[136:139], v[168:171], 0
	v_mfma_f32_16x16x32_bf16 v[84:87], v[128:131], v[176:179], 0
	v_mfma_f32_16x16x32_bf16 v[80:83], v[136:139], v[176:179], 0
	v_mfma_f32_16x16x32_bf16 v[52:55], v[128:131], v[184:187], 0
	v_mfma_f32_16x16x32_bf16 v[48:51], v[136:139], v[184:187], 0
	v_mfma_f32_16x16x32_bf16 v[112:115], v[132:135], v[164:167], v[112:115]
	v_mfma_f32_16x16x32_bf16 v[116:119], v[140:143], v[164:167], v[116:119]
	v_mfma_f32_16x16x32_bf16 v[100:103], v[132:135], v[172:175], v[100:103]
	v_mfma_f32_16x16x32_bf16 v[96:99], v[140:143], v[172:175], v[96:99]
	v_mfma_f32_16x16x32_bf16 v[84:87], v[132:135], v[180:183], v[84:87]
	v_mfma_f32_16x16x32_bf16 v[80:83], v[140:143], v[180:183], v[80:83]
	v_mfma_f32_16x16x32_bf16 v[52:55], v[132:135], v[188:191], v[52:55]
	v_mfma_f32_16x16x32_bf16 v[48:51], v[140:143], v[188:191], v[48:51]
	s_setprio 0
	s_setprio 1
	v_mfma_f32_16x16x32_bf16 v[124:127], v[144:147], v[160:163], 0
	v_mfma_f32_16x16x32_bf16 v[120:123], v[152:155], v[160:163], 0
	v_mfma_f32_16x16x32_bf16 v[108:111], v[144:147], v[168:171], 0
	v_mfma_f32_16x16x32_bf16 v[104:107], v[152:155], v[168:171], 0
	v_mfma_f32_16x16x32_bf16 v[92:95], v[144:147], v[176:179], 0
	v_mfma_f32_16x16x32_bf16 v[88:91], v[152:155], v[176:179], 0
	v_mfma_f32_16x16x32_bf16 v[68:71], v[144:147], v[184:187], 0
	v_mfma_f32_16x16x32_bf16 v[64:67], v[152:155], v[184:187], 0
	v_mfma_f32_16x16x32_bf16 v[124:127], v[148:151], v[164:167], v[124:127]
	v_mfma_f32_16x16x32_bf16 v[120:123], v[156:159], v[164:167], v[120:123]
	v_mfma_f32_16x16x32_bf16 v[108:111], v[148:151], v[172:175], v[108:111]
	v_mfma_f32_16x16x32_bf16 v[104:107], v[156:159], v[172:175], v[104:107]
	v_mfma_f32_16x16x32_bf16 v[92:95], v[148:151], v[180:183], v[92:95]
	v_mfma_f32_16x16x32_bf16 v[88:91], v[156:159], v[180:183], v[88:91]
	v_mfma_f32_16x16x32_bf16 v[68:71], v[148:151], v[188:191], v[68:71]
	v_mfma_f32_16x16x32_bf16 v[64:67], v[156:159], v[188:191], v[64:67]
	s_barrier
	s_setprio 0
	s_add_i32 s80, s68, s97
	s_add_u32 s98, s46, 0x80
	s_addc_u32 s99, s47, 0
	s_mov_b32 m0, s80
	ds_read_b128 v[160:163], v230 offset:16384
	ds_read_b128 v[164:167], v230 offset:17408
	ds_read_b128 v[168:171], v230 offset:18432
	ds_read_b128 v[172:175], v230 offset:19456
	ds_read_b128 v[176:179], v230 offset:20480
	ds_read_b128 v[180:183], v230 offset:21504
	ds_read_b128 v[184:187], v230 offset:22528
	ds_read_b128 v[188:191], v230 offset:23552
	global_load_lds_dwordx4 v194, s[46:47]
	s_add_i32 m0, s80, 0x2000
	s_add_u32 s80, s46, 0x400000
	s_addc_u32 s81, s47, 0
	s_add_i32 s84, s69, s97
	global_load_lds_dwordx4 v198, s[46:47]
	s_mov_b32 m0, s84
	s_add_u32 s100, s48, 0x80
	s_addc_u32 s101, s49, 0
	global_load_lds_dwordx4 v194, s[80:81]
	s_add_i32 m0, s84, 0x2000
	s_nop 0
	global_load_lds_dwordx4 v198, s[80:81]
	s_mov_b32 m0, s94
	s_nop 0
	global_load_lds_dwordx4 v192, s[48:49]
	s_mov_b32 m0, s51
	s_nop 0
	global_load_lds_dwordx4 v196, s[48:49]
	s_waitcnt vmcnt(8)
	s_waitcnt lgkmcnt(0)
	s_setprio 1
	s_barrier
	v_mfma_f32_16x16x32_bf16 v[60:63], v[128:131], v[160:163], 0
	v_mfma_f32_16x16x32_bf16 v[56:59], v[136:139], v[160:163], 0
	v_mfma_f32_16x16x32_bf16 v[36:39], v[128:131], v[168:171], 0
	v_mfma_f32_16x16x32_bf16 v[32:35], v[136:139], v[168:171], 0
	v_mfma_f32_16x16x32_bf16 v[20:23], v[128:131], v[176:179], 0
	v_mfma_f32_16x16x32_bf16 v[16:19], v[136:139], v[176:179], 0
	v_mfma_f32_16x16x32_bf16 v[4:7], v[128:131], v[184:187], 0
	v_mfma_f32_16x16x32_bf16 v[0:3], v[136:139], v[184:187], 0
	v_mfma_f32_16x16x32_bf16 v[60:63], v[132:135], v[164:167], v[60:63]
	v_mfma_f32_16x16x32_bf16 v[56:59], v[140:143], v[164:167], v[56:59]
	v_mfma_f32_16x16x32_bf16 v[36:39], v[132:135], v[172:175], v[36:39]
	v_mfma_f32_16x16x32_bf16 v[32:35], v[140:143], v[172:175], v[32:35]
	v_mfma_f32_16x16x32_bf16 v[20:23], v[132:135], v[180:183], v[20:23]
	v_mfma_f32_16x16x32_bf16 v[16:19], v[140:143], v[180:183], v[16:19]
	v_mfma_f32_16x16x32_bf16 v[4:7], v[132:135], v[188:191], v[4:7]
	v_mfma_f32_16x16x32_bf16 v[0:3], v[140:143], v[188:191], v[0:3]
	s_setprio 0
	s_setprio 1
	v_mfma_f32_16x16x32_bf16 v[76:79], v[144:147], v[160:163], 0
	v_mfma_f32_16x16x32_bf16 v[72:75], v[152:155], v[160:163], 0
	v_mfma_f32_16x16x32_bf16 v[44:47], v[144:147], v[168:171], 0
	v_mfma_f32_16x16x32_bf16 v[40:43], v[152:155], v[168:171], 0
	v_mfma_f32_16x16x32_bf16 v[28:31], v[144:147], v[176:179], 0
	v_mfma_f32_16x16x32_bf16 v[24:27], v[152:155], v[176:179], 0
	v_mfma_f32_16x16x32_bf16 v[12:15], v[144:147], v[184:187], 0
	v_mfma_f32_16x16x32_bf16 v[8:11], v[152:155], v[184:187], 0
	v_mfma_f32_16x16x32_bf16 v[76:79], v[148:151], v[164:167], v[76:79]
	v_mfma_f32_16x16x32_bf16 v[72:75], v[156:159], v[164:167], v[72:75]
	v_mfma_f32_16x16x32_bf16 v[44:47], v[148:151], v[172:175], v[44:47]
	v_mfma_f32_16x16x32_bf16 v[40:43], v[156:159], v[172:175], v[40:43]
	v_mfma_f32_16x16x32_bf16 v[28:31], v[148:151], v[180:183], v[28:31]
	v_mfma_f32_16x16x32_bf16 v[24:27], v[156:159], v[180:183], v[24:27]
	v_mfma_f32_16x16x32_bf16 v[12:15], v[148:151], v[188:191], v[12:15]
	v_mfma_f32_16x16x32_bf16 v[8:11], v[156:159], v[188:191], v[8:11]
	s_barrier
	s_setprio 0
	s_add_i32 s80, 0, 0x18000
	s_add_i32 s81, 0, 0x1c000
	v_add_u32_e32 v140, s80, v226
	v_add_u32_e32 v156, s81, v226
	ds_read_b128 v[128:131], v140
	ds_read_b128 v[132:135], v140 offset:1024
	ds_read_b128 v[136:139], v140 offset:2048
	ds_read_b128 v[140:143], v140 offset:3072
	ds_read_b128 v[144:147], v156
	ds_read_b128 v[148:151], v156 offset:1024
	ds_read_b128 v[152:155], v156 offset:2048
	ds_read_b128 v[156:159], v156 offset:3072
	s_add_u32 s48, s48, 0x400000
	s_addc_u32 s49, s49, 0
	s_mov_b32 m0, s52
	ds_read_b128 v[160:163], v230 offset:32768
	ds_read_b128 v[164:167], v230 offset:33792
	ds_read_b128 v[168:171], v230 offset:34816
	ds_read_b128 v[172:175], v230 offset:35840
	ds_read_b128 v[176:179], v230 offset:36864
	ds_read_b128 v[180:183], v230 offset:37888
	ds_read_b128 v[184:187], v230 offset:38912
	ds_read_b128 v[188:191], v230 offset:39936
	global_load_lds_dwordx4 v192, s[48:49]
	s_mov_b32 m0, s53
	s_nop 0
	global_load_lds_dwordx4 v196, s[48:49]
	s_waitcnt vmcnt(8)
	s_waitcnt lgkmcnt(0)
	s_setprio 1
	s_barrier
	v_mfma_f32_16x16x32_bf16 v[112:115], v[128:131], v[160:163], v[112:115]
	v_mfma_f32_16x16x32_bf16 v[116:119], v[136:139], v[160:163], v[116:119]
	v_mfma_f32_16x16x32_bf16 v[100:103], v[128:131], v[168:171], v[100:103]
	v_mfma_f32_16x16x32_bf16 v[96:99], v[136:139], v[168:171], v[96:99]
	v_mfma_f32_16x16x32_bf16 v[84:87], v[128:131], v[176:179], v[84:87]
	v_mfma_f32_16x16x32_bf16 v[80:83], v[136:139], v[176:179], v[80:83]
	v_mfma_f32_16x16x32_bf16 v[52:55], v[128:131], v[184:187], v[52:55]
	v_mfma_f32_16x16x32_bf16 v[48:51], v[136:139], v[184:187], v[48:51]
	v_mfma_f32_16x16x32_bf16 v[112:115], v[132:135], v[164:167], v[112:115]
	v_mfma_f32_16x16x32_bf16 v[116:119], v[140:143], v[164:167], v[116:119]
	v_mfma_f32_16x16x32_bf16 v[100:103], v[132:135], v[172:175], v[100:103]
	v_mfma_f32_16x16x32_bf16 v[96:99], v[140:143], v[172:175], v[96:99]
	v_mfma_f32_16x16x32_bf16 v[84:87], v[132:135], v[180:183], v[84:87]
	v_mfma_f32_16x16x32_bf16 v[80:83], v[140:143], v[180:183], v[80:83]
	v_mfma_f32_16x16x32_bf16 v[52:55], v[132:135], v[188:191], v[52:55]
	v_mfma_f32_16x16x32_bf16 v[48:51], v[140:143], v[188:191], v[48:51]
	s_setprio 0
	s_setprio 1
	v_mfma_f32_16x16x32_bf16 v[124:127], v[144:147], v[160:163], v[124:127]
	v_mfma_f32_16x16x32_bf16 v[120:123], v[152:155], v[160:163], v[120:123]
	v_mfma_f32_16x16x32_bf16 v[108:111], v[144:147], v[168:171], v[108:111]
	v_mfma_f32_16x16x32_bf16 v[104:107], v[152:155], v[168:171], v[104:107]
	v_mfma_f32_16x16x32_bf16 v[92:95], v[144:147], v[176:179], v[92:95]
	v_mfma_f32_16x16x32_bf16 v[88:91], v[152:155], v[176:179], v[88:91]
	v_mfma_f32_16x16x32_bf16 v[68:71], v[144:147], v[184:187], v[68:71]
	v_mfma_f32_16x16x32_bf16 v[64:67], v[152:155], v[184:187], v[64:67]
	v_mfma_f32_16x16x32_bf16 v[124:127], v[148:151], v[164:167], v[124:127]
	v_mfma_f32_16x16x32_bf16 v[120:123], v[156:159], v[164:167], v[120:123]
	v_mfma_f32_16x16x32_bf16 v[108:111], v[148:151], v[172:175], v[108:111]
	v_mfma_f32_16x16x32_bf16 v[104:107], v[156:159], v[172:175], v[104:107]
	v_mfma_f32_16x16x32_bf16 v[92:95], v[148:151], v[180:183], v[92:95]
	v_mfma_f32_16x16x32_bf16 v[88:91], v[156:159], v[180:183], v[88:91]
	v_mfma_f32_16x16x32_bf16 v[68:71], v[148:151], v[188:191], v[68:71]
	v_mfma_f32_16x16x32_bf16 v[64:67], v[156:159], v[188:191], v[64:67]
	s_barrier
	s_setprio 0
	s_add_i32 s48, s80, s97
	s_mov_b32 m0, s48
	ds_read_b128 v[160:163], v230 offset:49152
	ds_read_b128 v[164:167], v230 offset:50176
	ds_read_b128 v[168:171], v230 offset:51200
	ds_read_b128 v[172:175], v230 offset:52224
	ds_read_b128 v[176:179], v230 offset:53248
	ds_read_b128 v[180:183], v230 offset:54272
	ds_read_b128 v[184:187], v230 offset:55296
	ds_read_b128 v[188:191], v230 offset:56320
	global_load_lds_dwordx4 v194, s[98:99]
	s_add_i32 m0, s48, 0x2000
	s_add_u32 s46, s46, 0x400080
	s_addc_u32 s47, s47, 0
	s_add_i32 s48, s81, s97
	global_load_lds_dwordx4 v198, s[98:99]
	s_mov_b32 m0, s48
	s_nop 0
	global_load_lds_dwordx4 v194, s[46:47]
	s_add_i32 m0, s48, 0x2000
	s_nop 0
	global_load_lds_dwordx4 v198, s[46:47]
	s_mov_b32 m0, s54
	s_nop 0
	global_load_lds_dwordx4 v192, s[100:101]
	s_mov_b32 m0, s55
	s_nop 0
	global_load_lds_dwordx4 v196, s[100:101]
	s_waitcnt vmcnt(8)
	s_waitcnt lgkmcnt(0)
	s_setprio 1
	s_barrier
	v_mfma_f32_16x16x32_bf16 v[60:63], v[128:131], v[160:163], v[60:63]
	v_mfma_f32_16x16x32_bf16 v[56:59], v[136:139], v[160:163], v[56:59]
	v_mfma_f32_16x16x32_bf16 v[36:39], v[128:131], v[168:171], v[36:39]
	v_mfma_f32_16x16x32_bf16 v[32:35], v[136:139], v[168:171], v[32:35]
	v_mfma_f32_16x16x32_bf16 v[20:23], v[128:131], v[176:179], v[20:23]
	v_mfma_f32_16x16x32_bf16 v[16:19], v[136:139], v[176:179], v[16:19]
	v_mfma_f32_16x16x32_bf16 v[4:7], v[128:131], v[184:187], v[4:7]
	v_mfma_f32_16x16x32_bf16 v[0:3], v[136:139], v[184:187], v[0:3]
	v_mfma_f32_16x16x32_bf16 v[60:63], v[132:135], v[164:167], v[60:63]
	v_mfma_f32_16x16x32_bf16 v[56:59], v[140:143], v[164:167], v[56:59]
	v_mfma_f32_16x16x32_bf16 v[36:39], v[132:135], v[172:175], v[36:39]
	v_mfma_f32_16x16x32_bf16 v[32:35], v[140:143], v[172:175], v[32:35]
	v_mfma_f32_16x16x32_bf16 v[20:23], v[132:135], v[180:183], v[20:23]
	v_mfma_f32_16x16x32_bf16 v[16:19], v[140:143], v[180:183], v[16:19]
	v_mfma_f32_16x16x32_bf16 v[4:7], v[132:135], v[188:191], v[4:7]
	v_mfma_f32_16x16x32_bf16 v[0:3], v[140:143], v[188:191], v[0:3]
	s_setprio 0
	s_setprio 1
	v_mfma_f32_16x16x32_bf16 v[76:79], v[144:147], v[160:163], v[76:79]
	v_mfma_f32_16x16x32_bf16 v[72:75], v[152:155], v[160:163], v[72:75]
	v_mfma_f32_16x16x32_bf16 v[44:47], v[144:147], v[168:171], v[44:47]
	v_mfma_f32_16x16x32_bf16 v[40:43], v[152:155], v[168:171], v[40:43]
	v_mfma_f32_16x16x32_bf16 v[28:31], v[144:147], v[176:179], v[28:31]
	v_mfma_f32_16x16x32_bf16 v[24:27], v[152:155], v[176:179], v[24:27]
	v_mfma_f32_16x16x32_bf16 v[12:15], v[144:147], v[184:187], v[12:15]
	v_mfma_f32_16x16x32_bf16 v[8:11], v[152:155], v[184:187], v[8:11]
	v_mfma_f32_16x16x32_bf16 v[76:79], v[148:151], v[164:167], v[76:79]
	v_mfma_f32_16x16x32_bf16 v[72:75], v[156:159], v[164:167], v[72:75]
	v_mfma_f32_16x16x32_bf16 v[44:47], v[148:151], v[172:175], v[44:47]
	v_mfma_f32_16x16x32_bf16 v[40:43], v[156:159], v[172:175], v[40:43]
	v_mfma_f32_16x16x32_bf16 v[28:31], v[148:151], v[180:183], v[28:31]
	v_mfma_f32_16x16x32_bf16 v[24:27], v[156:159], v[180:183], v[24:27]
	v_mfma_f32_16x16x32_bf16 v[12:15], v[148:151], v[188:191], v[12:15]
	v_mfma_f32_16x16x32_bf16 v[8:11], v[156:159], v[188:191], v[8:11]
	s_barrier
	s_setprio 0
	s_add_u32 s77, s77, 0x100
	s_addc_u32 s78, s78, 0
	s_add_u32 s44, s44, 0x100
	s_addc_u32 s45, s45, 0
	s_cmp_ge_u32 s79, s76
	s_mov_b32 s46, s79
	s_cbranch_scc1 .Lpeel_done_4
.LBB0_2453:
	ds_read_b128 v[128:131], v228
	ds_read_b128 v[132:135], v228 offset:1024
	ds_read_b128 v[136:139], v228 offset:2048
	ds_read_b128 v[140:143], v228 offset:3072
	ds_read_b128 v[144:147], v229
	ds_read_b128 v[148:151], v229 offset:1024
	ds_read_b128 v[152:155], v229 offset:2048
	ds_read_b128 v[156:159], v229 offset:3072
	s_add_i32 s79, s46, 2
	s_add_u32 s47, s44, 0xffc00080
	s_addc_u32 s48, s45, -1
	s_cmp_eq_u32 s75, s46
	s_cselect_b32 s46, s43, s77
	s_cselect_b32 s49, s35, s48
	s_cselect_b32 s48, s41, s47
	s_cselect_b32 s47, s31, s78
	s_add_i32 m0, s94, 0xc000
	ds_read_b128 v[160:163], v230
	ds_read_b128 v[164:167], v230 offset:1024
	ds_read_b128 v[168:171], v230 offset:2048
	ds_read_b128 v[172:175], v230 offset:3072
	ds_read_b128 v[176:179], v230 offset:4096
	ds_read_b128 v[180:183], v230 offset:5120
	ds_read_b128 v[184:187], v230 offset:6144
	ds_read_b128 v[188:191], v230 offset:7168
	global_load_lds_dwordx4 v202, s[44:45]
	s_add_i32 m0, s94, 0xe000
	s_nop 0
	global_load_lds_dwordx4 v204, s[44:45]
	s_waitcnt vmcnt(8)
	s_waitcnt lgkmcnt(0)
	s_setprio 1
	s_barrier
	v_mfma_f32_16x16x32_bf16 v[112:115], v[128:131], v[160:163], v[112:115]
	v_mfma_f32_16x16x32_bf16 v[116:119], v[136:139], v[160:163], v[116:119]
	v_mfma_f32_16x16x32_bf16 v[100:103], v[128:131], v[168:171], v[100:103]
	v_mfma_f32_16x16x32_bf16 v[96:99], v[136:139], v[168:171], v[96:99]
	v_mfma_f32_16x16x32_bf16 v[84:87], v[128:131], v[176:179], v[84:87]
	v_mfma_f32_16x16x32_bf16 v[80:83], v[136:139], v[176:179], v[80:83]
	v_mfma_f32_16x16x32_bf16 v[52:55], v[128:131], v[184:187], v[52:55]
	v_mfma_f32_16x16x32_bf16 v[48:51], v[136:139], v[184:187], v[48:51]
	v_mfma_f32_16x16x32_bf16 v[112:115], v[132:135], v[164:167], v[112:115]
	v_mfma_f32_16x16x32_bf16 v[116:119], v[140:143], v[164:167], v[116:119]
	v_mfma_f32_16x16x32_bf16 v[100:103], v[132:135], v[172:175], v[100:103]
	v_mfma_f32_16x16x32_bf16 v[96:99], v[140:143], v[172:175], v[96:99]
	v_mfma_f32_16x16x32_bf16 v[84:87], v[132:135], v[180:183], v[84:87]
	v_mfma_f32_16x16x32_bf16 v[80:83], v[140:143], v[180:183], v[80:83]
	v_mfma_f32_16x16x32_bf16 v[52:55], v[132:135], v[188:191], v[52:55]
	v_mfma_f32_16x16x32_bf16 v[48:51], v[140:143], v[188:191], v[48:51]
	s_setprio 0
	s_setprio 1
	v_mfma_f32_16x16x32_bf16 v[124:127], v[144:147], v[160:163], v[124:127]
	v_mfma_f32_16x16x32_bf16 v[120:123], v[152:155], v[160:163], v[120:123]
	v_mfma_f32_16x16x32_bf16 v[108:111], v[144:147], v[168:171], v[108:111]
	v_mfma_f32_16x16x32_bf16 v[104:107], v[152:155], v[168:171], v[104:107]
	v_mfma_f32_16x16x32_bf16 v[92:95], v[144:147], v[176:179], v[92:95]
	v_mfma_f32_16x16x32_bf16 v[88:91], v[152:155], v[176:179], v[88:91]
	v_mfma_f32_16x16x32_bf16 v[68:71], v[144:147], v[184:187], v[68:71]
	v_mfma_f32_16x16x32_bf16 v[64:67], v[152:155], v[184:187], v[64:67]
	v_mfma_f32_16x16x32_bf16 v[124:127], v[148:151], v[164:167], v[124:127]
	v_mfma_f32_16x16x32_bf16 v[120:123], v[156:159], v[164:167], v[120:123]
	v_mfma_f32_16x16x32_bf16 v[108:111], v[148:151], v[172:175], v[108:111]
	v_mfma_f32_16x16x32_bf16 v[104:107], v[156:159], v[172:175], v[104:107]
	v_mfma_f32_16x16x32_bf16 v[92:95], v[148:151], v[180:183], v[92:95]
	v_mfma_f32_16x16x32_bf16 v[88:91], v[156:159], v[180:183], v[88:91]
	v_mfma_f32_16x16x32_bf16 v[68:71], v[148:151], v[188:191], v[68:71]
	v_mfma_f32_16x16x32_bf16 v[64:67], v[156:159], v[188:191], v[64:67]
	s_barrier
	s_setprio 0
	s_add_i32 s80, s68, s97
	s_add_u32 s98, s46, 0x80
	s_addc_u32 s99, s47, 0
	s_mov_b32 m0, s80
	ds_read_b128 v[160:163], v230 offset:16384
	ds_read_b128 v[164:167], v230 offset:17408
	ds_read_b128 v[168:171], v230 offset:18432
	ds_read_b128 v[172:175], v230 offset:19456
	ds_read_b128 v[176:179], v230 offset:20480
	ds_read_b128 v[180:183], v230 offset:21504
	ds_read_b128 v[184:187], v230 offset:22528
	ds_read_b128 v[188:191], v230 offset:23552
	global_load_lds_dwordx4 v194, s[46:47]
	s_add_i32 m0, s80, 0x2000
	s_add_u32 s80, s46, 0x400000
	s_addc_u32 s81, s47, 0
	s_add_i32 s84, s69, s97
	global_load_lds_dwordx4 v198, s[46:47]
	s_mov_b32 m0, s84
	s_add_u32 s100, s48, 0x80
	s_addc_u32 s101, s49, 0
	global_load_lds_dwordx4 v194, s[80:81]
	s_add_i32 m0, s84, 0x2000
	s_nop 0
	global_load_lds_dwordx4 v198, s[80:81]
	s_mov_b32 m0, s94
	s_nop 0
	global_load_lds_dwordx4 v192, s[48:49]
	s_mov_b32 m0, s51
	s_nop 0
	global_load_lds_dwordx4 v196, s[48:49]
	s_waitcnt vmcnt(8)
	s_waitcnt lgkmcnt(0)
	s_setprio 1
	s_barrier
	v_mfma_f32_16x16x32_bf16 v[60:63], v[128:131], v[160:163], v[60:63]
	v_mfma_f32_16x16x32_bf16 v[56:59], v[136:139], v[160:163], v[56:59]
	v_mfma_f32_16x16x32_bf16 v[36:39], v[128:131], v[168:171], v[36:39]
	v_mfma_f32_16x16x32_bf16 v[32:35], v[136:139], v[168:171], v[32:35]
	v_mfma_f32_16x16x32_bf16 v[20:23], v[128:131], v[176:179], v[20:23]
	v_mfma_f32_16x16x32_bf16 v[16:19], v[136:139], v[176:179], v[16:19]
	v_mfma_f32_16x16x32_bf16 v[4:7], v[128:131], v[184:187], v[4:7]
	v_mfma_f32_16x16x32_bf16 v[0:3], v[136:139], v[184:187], v[0:3]
	v_mfma_f32_16x16x32_bf16 v[60:63], v[132:135], v[164:167], v[60:63]
	v_mfma_f32_16x16x32_bf16 v[56:59], v[140:143], v[164:167], v[56:59]
	v_mfma_f32_16x16x32_bf16 v[36:39], v[132:135], v[172:175], v[36:39]
	v_mfma_f32_16x16x32_bf16 v[32:35], v[140:143], v[172:175], v[32:35]
	v_mfma_f32_16x16x32_bf16 v[20:23], v[132:135], v[180:183], v[20:23]
	v_mfma_f32_16x16x32_bf16 v[16:19], v[140:143], v[180:183], v[16:19]
	v_mfma_f32_16x16x32_bf16 v[4:7], v[132:135], v[188:191], v[4:7]
	v_mfma_f32_16x16x32_bf16 v[0:3], v[140:143], v[188:191], v[0:3]
	s_setprio 0
	s_setprio 1
	v_mfma_f32_16x16x32_bf16 v[76:79], v[144:147], v[160:163], v[76:79]
	v_mfma_f32_16x16x32_bf16 v[72:75], v[152:155], v[160:163], v[72:75]
	v_mfma_f32_16x16x32_bf16 v[44:47], v[144:147], v[168:171], v[44:47]
	v_mfma_f32_16x16x32_bf16 v[40:43], v[152:155], v[168:171], v[40:43]
	v_mfma_f32_16x16x32_bf16 v[28:31], v[144:147], v[176:179], v[28:31]
	v_mfma_f32_16x16x32_bf16 v[24:27], v[152:155], v[176:179], v[24:27]
	v_mfma_f32_16x16x32_bf16 v[12:15], v[144:147], v[184:187], v[12:15]
	v_mfma_f32_16x16x32_bf16 v[8:11], v[152:155], v[184:187], v[8:11]
	v_mfma_f32_16x16x32_bf16 v[76:79], v[148:151], v[164:167], v[76:79]
	v_mfma_f32_16x16x32_bf16 v[72:75], v[156:159], v[164:167], v[72:75]
	v_mfma_f32_16x16x32_bf16 v[44:47], v[148:151], v[172:175], v[44:47]
	v_mfma_f32_16x16x32_bf16 v[40:43], v[156:159], v[172:175], v[40:43]
	v_mfma_f32_16x16x32_bf16 v[28:31], v[148:151], v[180:183], v[28:31]
	v_mfma_f32_16x16x32_bf16 v[24:27], v[156:159], v[180:183], v[24:27]
	v_mfma_f32_16x16x32_bf16 v[12:15], v[148:151], v[188:191], v[12:15]
	v_mfma_f32_16x16x32_bf16 v[8:11], v[156:159], v[188:191], v[8:11]
	s_barrier
	s_setprio 0
	s_add_i32 s80, 0, 0x18000
	s_add_i32 s81, 0, 0x1c000
	v_add_u32_e32 v140, s80, v226
	v_add_u32_e32 v156, s81, v226
	ds_read_b128 v[128:131], v140
	ds_read_b128 v[132:135], v140 offset:1024
	ds_read_b128 v[136:139], v140 offset:2048
	ds_read_b128 v[140:143], v140 offset:3072
	ds_read_b128 v[144:147], v156
	ds_read_b128 v[148:151], v156 offset:1024
	ds_read_b128 v[152:155], v156 offset:2048
	ds_read_b128 v[156:159], v156 offset:3072
	s_add_u32 s48, s48, 0x400000
	s_addc_u32 s49, s49, 0
	s_mov_b32 m0, s52
	ds_read_b128 v[160:163], v230 offset:32768
	ds_read_b128 v[164:167], v230 offset:33792
	ds_read_b128 v[168:171], v230 offset:34816
	ds_read_b128 v[172:175], v230 offset:35840
	ds_read_b128 v[176:179], v230 offset:36864
	ds_read_b128 v[180:183], v230 offset:37888
	ds_read_b128 v[184:187], v230 offset:38912
	ds_read_b128 v[188:191], v230 offset:39936
	global_load_lds_dwordx4 v192, s[48:49]
	s_mov_b32 m0, s53
	s_nop 0
	global_load_lds_dwordx4 v196, s[48:49]
	s_waitcnt vmcnt(8)
	s_waitcnt lgkmcnt(0)
	s_setprio 1
	s_barrier
	v_mfma_f32_16x16x32_bf16 v[112:115], v[128:131], v[160:163], v[112:115]
	v_mfma_f32_16x16x32_bf16 v[116:119], v[136:139], v[160:163], v[116:119]
	v_mfma_f32_16x16x32_bf16 v[100:103], v[128:131], v[168:171], v[100:103]
	v_mfma_f32_16x16x32_bf16 v[96:99], v[136:139], v[168:171], v[96:99]
	v_mfma_f32_16x16x32_bf16 v[84:87], v[128:131], v[176:179], v[84:87]
	v_mfma_f32_16x16x32_bf16 v[80:83], v[136:139], v[176:179], v[80:83]
	v_mfma_f32_16x16x32_bf16 v[52:55], v[128:131], v[184:187], v[52:55]
	v_mfma_f32_16x16x32_bf16 v[48:51], v[136:139], v[184:187], v[48:51]
	v_mfma_f32_16x16x32_bf16 v[112:115], v[132:135], v[164:167], v[112:115]
	v_mfma_f32_16x16x32_bf16 v[116:119], v[140:143], v[164:167], v[116:119]
	v_mfma_f32_16x16x32_bf16 v[100:103], v[132:135], v[172:175], v[100:103]
	v_mfma_f32_16x16x32_bf16 v[96:99], v[140:143], v[172:175], v[96:99]
	v_mfma_f32_16x16x32_bf16 v[84:87], v[132:135], v[180:183], v[84:87]
	v_mfma_f32_16x16x32_bf16 v[80:83], v[140:143], v[180:183], v[80:83]
	v_mfma_f32_16x16x32_bf16 v[52:55], v[132:135], v[188:191], v[52:55]
	v_mfma_f32_16x16x32_bf16 v[48:51], v[140:143], v[188:191], v[48:51]
	s_setprio 0
	s_setprio 1
	v_mfma_f32_16x16x32_bf16 v[124:127], v[144:147], v[160:163], v[124:127]
	v_mfma_f32_16x16x32_bf16 v[120:123], v[152:155], v[160:163], v[120:123]
	v_mfma_f32_16x16x32_bf16 v[108:111], v[144:147], v[168:171], v[108:111]
	v_mfma_f32_16x16x32_bf16 v[104:107], v[152:155], v[168:171], v[104:107]
	v_mfma_f32_16x16x32_bf16 v[92:95], v[144:147], v[176:179], v[92:95]
	v_mfma_f32_16x16x32_bf16 v[88:91], v[152:155], v[176:179], v[88:91]
	v_mfma_f32_16x16x32_bf16 v[68:71], v[144:147], v[184:187], v[68:71]
	v_mfma_f32_16x16x32_bf16 v[64:67], v[152:155], v[184:187], v[64:67]
	v_mfma_f32_16x16x32_bf16 v[124:127], v[148:151], v[164:167], v[124:127]
	v_mfma_f32_16x16x32_bf16 v[120:123], v[156:159], v[164:167], v[120:123]
	v_mfma_f32_16x16x32_bf16 v[108:111], v[148:151], v[172:175], v[108:111]
	v_mfma_f32_16x16x32_bf16 v[104:107], v[156:159], v[172:175], v[104:107]
	v_mfma_f32_16x16x32_bf16 v[92:95], v[148:151], v[180:183], v[92:95]
	v_mfma_f32_16x16x32_bf16 v[88:91], v[156:159], v[180:183], v[88:91]
	v_mfma_f32_16x16x32_bf16 v[68:71], v[148:151], v[188:191], v[68:71]
	v_mfma_f32_16x16x32_bf16 v[64:67], v[156:159], v[188:191], v[64:67]
	s_barrier
	s_setprio 0
	s_add_i32 s48, s80, s97
	s_mov_b32 m0, s48
	ds_read_b128 v[160:163], v230 offset:49152
	ds_read_b128 v[164:167], v230 offset:50176
	ds_read_b128 v[168:171], v230 offset:51200
	ds_read_b128 v[172:175], v230 offset:52224
	ds_read_b128 v[176:179], v230 offset:53248
	ds_read_b128 v[180:183], v230 offset:54272
	ds_read_b128 v[184:187], v230 offset:55296
	ds_read_b128 v[188:191], v230 offset:56320
	global_load_lds_dwordx4 v194, s[98:99]
	s_add_i32 m0, s48, 0x2000
	s_add_u32 s46, s46, 0x400080
	s_addc_u32 s47, s47, 0
	s_add_i32 s48, s81, s97
	global_load_lds_dwordx4 v198, s[98:99]
	s_mov_b32 m0, s48
	s_nop 0
	global_load_lds_dwordx4 v194, s[46:47]
	s_add_i32 m0, s48, 0x2000
	s_nop 0
	global_load_lds_dwordx4 v198, s[46:47]
	s_mov_b32 m0, s54
	s_nop 0
	global_load_lds_dwordx4 v192, s[100:101]
	s_mov_b32 m0, s55
	s_nop 0
	global_load_lds_dwordx4 v196, s[100:101]
	s_waitcnt vmcnt(8)
	s_waitcnt lgkmcnt(0)
	s_setprio 1
	s_barrier
	v_mfma_f32_16x16x32_bf16 v[60:63], v[128:131], v[160:163], v[60:63]
	v_mfma_f32_16x16x32_bf16 v[56:59], v[136:139], v[160:163], v[56:59]
	v_mfma_f32_16x16x32_bf16 v[36:39], v[128:131], v[168:171], v[36:39]
	v_mfma_f32_16x16x32_bf16 v[32:35], v[136:139], v[168:171], v[32:35]
	v_mfma_f32_16x16x32_bf16 v[20:23], v[128:131], v[176:179], v[20:23]
	v_mfma_f32_16x16x32_bf16 v[16:19], v[136:139], v[176:179], v[16:19]
	v_mfma_f32_16x16x32_bf16 v[4:7], v[128:131], v[184:187], v[4:7]
	v_mfma_f32_16x16x32_bf16 v[0:3], v[136:139], v[184:187], v[0:3]
	v_mfma_f32_16x16x32_bf16 v[60:63], v[132:135], v[164:167], v[60:63]
	v_mfma_f32_16x16x32_bf16 v[56:59], v[140:143], v[164:167], v[56:59]
	v_mfma_f32_16x16x32_bf16 v[36:39], v[132:135], v[172:175], v[36:39]
	v_mfma_f32_16x16x32_bf16 v[32:35], v[140:143], v[172:175], v[32:35]
	v_mfma_f32_16x16x32_bf16 v[20:23], v[132:135], v[180:183], v[20:23]
	v_mfma_f32_16x16x32_bf16 v[16:19], v[140:143], v[180:183], v[16:19]
	v_mfma_f32_16x16x32_bf16 v[4:7], v[132:135], v[188:191], v[4:7]
	v_mfma_f32_16x16x32_bf16 v[0:3], v[140:143], v[188:191], v[0:3]
	s_setprio 0
	s_setprio 1
	v_mfma_f32_16x16x32_bf16 v[76:79], v[144:147], v[160:163], v[76:79]
	v_mfma_f32_16x16x32_bf16 v[72:75], v[152:155], v[160:163], v[72:75]
	v_mfma_f32_16x16x32_bf16 v[44:47], v[144:147], v[168:171], v[44:47]
	v_mfma_f32_16x16x32_bf16 v[40:43], v[152:155], v[168:171], v[40:43]
	v_mfma_f32_16x16x32_bf16 v[28:31], v[144:147], v[176:179], v[28:31]
	v_mfma_f32_16x16x32_bf16 v[24:27], v[152:155], v[176:179], v[24:27]
	v_mfma_f32_16x16x32_bf16 v[12:15], v[144:147], v[184:187], v[12:15]
	v_mfma_f32_16x16x32_bf16 v[8:11], v[152:155], v[184:187], v[8:11]
	v_mfma_f32_16x16x32_bf16 v[76:79], v[148:151], v[164:167], v[76:79]
	v_mfma_f32_16x16x32_bf16 v[72:75], v[156:159], v[164:167], v[72:75]
	v_mfma_f32_16x16x32_bf16 v[44:47], v[148:151], v[172:175], v[44:47]
	v_mfma_f32_16x16x32_bf16 v[40:43], v[156:159], v[172:175], v[40:43]
	v_mfma_f32_16x16x32_bf16 v[28:31], v[148:151], v[180:183], v[28:31]
	v_mfma_f32_16x16x32_bf16 v[24:27], v[156:159], v[180:183], v[24:27]
	v_mfma_f32_16x16x32_bf16 v[12:15], v[148:151], v[188:191], v[12:15]
	v_mfma_f32_16x16x32_bf16 v[8:11], v[156:159], v[188:191], v[8:11]
	s_barrier
	s_setprio 0
	s_add_u32 s77, s77, 0x100
	s_addc_u32 s78, s78, 0
	s_add_u32 s44, s44, 0x100
	s_addc_u32 s45, s45, 0
	s_cmp_ge_u32 s79, s76
	s_mov_b32 s46, s79
	s_cbranch_scc0 .LBB0_2453
